# K-loops: leading half (waves 0-3) skips the LDS-read drain in front of the pre-MFMA barrier (the drain behind the barrier covers it; restaging is two rendezvous later)
# speedup vs baseline: 1.0051x; 1.0051x over previous
; #define PG8_STAGE(bufoff, gbase, voff) do { _Pragma("unroll") for (int _i = 0; _i < 2; ++_i) \
;         __builtin_amdgcn_global_load_lds((const unsigned*)((const char*)(gbase) + (voff)[_i]), (PG8_LAS unsigned*)(lds + (bufoff) + ldsw + _i * 8192), 16, 0, 0); } while (0)
; #define PG8_LDA(dst, b, h) do { _Pragma("unroll") for (int m = 0; m < 4; ++m) _Pragma("unroll") for (int k = 0; k < 2; ++k) dst[m][k] = *(const PG8_LAS bf16x8*)(lds + PG8_SA(b, h) + aoff + m * 2048 + k * 1024); } while (0)
; #define PG8_LDB(dst, b, h) do { _Pragma("unroll") for (int n = 0; n < 2; ++n) _Pragma("unroll") for (int k = 0; k < 2; ++k) dst[n][k] = *(const PG8_LAS bf16x8*)(lds + PG8_SB(b, h) + boff + n * 2048 + k * 1024); } while (0)
; #define PG8_MMA(ai, bj, At, Bt) do { __builtin_amdgcn_s_setprio(1); _Pragma("unroll") for (int m = 0; m < 4; ++m) _Pragma("unroll") for (int n = 0; n < 2; ++n) _Pragma("unroll") for (int k = 0; k < 2; ++k) \
;         acc[ai][bj][m][n] = __builtin_amdgcn_mfma_f32_16x16x32_bf16(Bt[n][k], At[m][k], acc[ai][bj][m][n], 0, 0, 0); __builtin_amdgcn_s_setprio(0); } while (0)
; #define PG8_WAIT_V(n) asm volatile("s_waitcnt vmcnt(" #n ")" ::: "memory")
; #define PG8_WAIT_L(n) asm volatile("s_waitcnt lgkmcnt(" #n ")" ::: "memory")
; #define PG8_BAR __builtin_amdgcn_s_barrier()
; #define PG8_SCHED __builtin_amdgcn_sched_barrier(0)
;     ...
;             PG8_LDB(B0, 0, 0); PG8_LDB(B1, 0, 1); PG8_SCHED; PG8_LDA(At, 0, 0); PG8_STAGE(PG8_SA(1, 1), a1 + hstepA, voffA);
;             PG8_WAIT_V(8); PG8_WAIT_L(0); PG8_BAR; PG8_MMA(0, 0, At, B0); PG8_MMA(0, 1, At, B1); PG8_BAR; PG8_SCHED;
;             PG8_LDA(At, 0, 1); PG8_STAGE(PG8_SB(0, 0), b2, voffB); PG8_STAGE(PG8_SB(0, 1), b2 + hstepB, voffB); PG8_STAGE(PG8_SA(0, 0), a2, voffA);
;             PG8_WAIT_V(8); PG8_WAIT_L(0); PG8_BAR; PG8_MMA(1, 0, At, B0); PG8_MMA(1, 1, At, B1); PG8_BAR; PG8_SCHED;
.LBB0_228:
	ds_read_b128 v[128:131], v201
	ds_read_b128 v[132:135], v201 offset:1024
	ds_read_b128 v[136:139], v201 offset:2048
	ds_read_b128 v[140:143], v201 offset:3072
	ds_read_b128 v[144:147], v205
	ds_read_b128 v[148:151], v205 offset:1024
	ds_read_b128 v[152:155], v205 offset:2048
	ds_read_b128 v[156:159], v205 offset:3072
	s_add_u32 s34, s28, 0xfffc0080
	s_addc_u32 s35, s29, -1
	s_cmp_eq_u32 s63, 12
	s_cselect_b32 s41, s42, s35
	s_cselect_b32 s40, s43, s34
	s_cselect_b32 s35, s44, s53
	s_cselect_b32 s34, s45, s51
	v_lshl_add_u64 v[192:193], s[28:29], 0, v[184:185]
	s_add_i32 m0, s61, 0xc000
	ds_read_b128 v[160:163], v207
	ds_read_b128 v[164:167], v207 offset:1024
	ds_read_b128 v[210:213], v207 offset:2048
	ds_read_b128 v[214:217], v207 offset:3072
	ds_read_b128 v[218:221], v207 offset:4096
	ds_read_b128 v[222:225], v207 offset:5120
	ds_read_b128 v[226:229], v207 offset:6144
	ds_read_b128 v[234:237], v207 offset:7168
	global_load_lds_dwordx4 v[192:193], off
	v_lshl_add_u64 v[192:193], s[28:29], 0, v[186:187]
	s_add_i32 m0, s61, 0xe000
	s_nop 0
	global_load_lds_dwordx4 v[192:193], off
	s_waitcnt vmcnt(8)
	s_cmp_lg_u32 s98, 0
	s_cbranch_scc0 .Llk_1
	s_waitcnt lgkmcnt(0)
.Llk_1:
	s_barrier
	s_setprio 1
	s_waitcnt lgkmcnt(0)
	v_mfma_f32_16x16x32_bf16 v[124:127], v[128:131], v[160:163], v[124:127]
	v_mfma_f32_16x16x32_bf16 v[120:123], v[136:139], v[160:163], v[120:123]
	v_mfma_f32_16x16x32_bf16 v[108:111], v[128:131], v[210:213], v[108:111]
	v_mfma_f32_16x16x32_bf16 v[104:107], v[136:139], v[210:213], v[104:107]
	v_mfma_f32_16x16x32_bf16 v[92:95], v[128:131], v[218:221], v[92:95]
	v_mfma_f32_16x16x32_bf16 v[88:91], v[136:139], v[218:221], v[88:91]
	v_mfma_f32_16x16x32_bf16 v[76:79], v[128:131], v[226:229], v[76:79]
	v_mfma_f32_16x16x32_bf16 v[72:75], v[136:139], v[226:229], v[72:75]
	v_mfma_f32_16x16x32_bf16 v[124:127], v[132:135], v[164:167], v[124:127]
	v_mfma_f32_16x16x32_bf16 v[120:123], v[140:143], v[164:167], v[120:123]
	v_mfma_f32_16x16x32_bf16 v[108:111], v[132:135], v[214:217], v[108:111]
	v_mfma_f32_16x16x32_bf16 v[104:107], v[140:143], v[214:217], v[104:107]
	v_mfma_f32_16x16x32_bf16 v[92:95], v[132:135], v[222:225], v[92:95]
	v_mfma_f32_16x16x32_bf16 v[88:91], v[140:143], v[222:225], v[88:91]
	v_mfma_f32_16x16x32_bf16 v[76:79], v[132:135], v[234:237], v[76:79]
	v_mfma_f32_16x16x32_bf16 v[72:75], v[140:143], v[234:237], v[72:75]
	s_setprio 0
	s_setprio 1
	v_mfma_f32_16x16x32_bf16 v[116:119], v[144:147], v[160:163], v[116:119]
	v_mfma_f32_16x16x32_bf16 v[112:115], v[152:155], v[160:163], v[112:115]
	v_mfma_f32_16x16x32_bf16 v[100:103], v[144:147], v[210:213], v[100:103]
	v_mfma_f32_16x16x32_bf16 v[96:99], v[152:155], v[210:213], v[96:99]
	v_mfma_f32_16x16x32_bf16 v[84:87], v[144:147], v[218:221], v[84:87]
	v_mfma_f32_16x16x32_bf16 v[80:83], v[152:155], v[218:221], v[80:83]
	v_mfma_f32_16x16x32_bf16 v[68:71], v[144:147], v[226:229], v[68:71]
	v_mfma_f32_16x16x32_bf16 v[64:67], v[152:155], v[226:229], v[64:67]
	v_mfma_f32_16x16x32_bf16 v[116:119], v[148:151], v[164:167], v[116:119]
	v_mfma_f32_16x16x32_bf16 v[112:115], v[156:159], v[164:167], v[112:115]
	v_mfma_f32_16x16x32_bf16 v[100:103], v[148:151], v[214:217], v[100:103]
	v_mfma_f32_16x16x32_bf16 v[96:99], v[156:159], v[214:217], v[96:99]
	v_mfma_f32_16x16x32_bf16 v[84:87], v[148:151], v[222:225], v[84:87]
	v_mfma_f32_16x16x32_bf16 v[80:83], v[156:159], v[222:225], v[80:83]
	v_mfma_f32_16x16x32_bf16 v[68:71], v[148:151], v[234:237], v[68:71]
	v_mfma_f32_16x16x32_bf16 v[64:67], v[156:159], v[234:237], v[64:67]
	s_setprio 0
	s_barrier
	s_add_i32 s85, s79, s65
	v_lshl_add_u64 v[192:193], s[34:35], 0, v[176:177]
	s_mov_b32 m0, s85
	ds_read_b128 v[160:163], v207 offset:16384
	ds_read_b128 v[164:167], v207 offset:17408
	ds_read_b128 v[210:213], v207 offset:18432
	ds_read_b128 v[214:217], v207 offset:19456
	ds_read_b128 v[218:221], v207 offset:20480
	ds_read_b128 v[222:225], v207 offset:21504
	ds_read_b128 v[226:229], v207 offset:22528
	ds_read_b128 v[234:237], v207 offset:23552
	global_load_lds_dwordx4 v[192:193], off
	s_add_i32 m0, s85, 0x2000
	s_add_u32 s86, s34, 0x40000
	v_lshl_add_u64 v[202:203], s[34:35], 0, v[180:181]
	s_addc_u32 s87, s35, 0
	s_add_i32 s85, s80, s65
	global_load_lds_dwordx4 v[202:203], off
	v_lshl_add_u64 v[230:231], s[86:87], 0, v[176:177]
	s_mov_b32 m0, s85
	v_lshl_add_u64 v[238:239], s[40:41], 0, v[178:179]
	global_load_lds_dwordx4 v[230:231], off
	v_lshl_add_u64 v[230:231], s[86:87], 0, v[180:181]
	s_add_i32 m0, s85, 0x2000
	s_nop 0
	global_load_lds_dwordx4 v[230:231], off
	v_lshl_add_u64 v[230:231], s[40:41], 0, v[174:175]
	s_mov_b32 m0, s61
	s_nop 0
	global_load_lds_dwordx4 v[230:231], off
	s_mov_b32 m0, s66
	s_nop 0
	global_load_lds_dwordx4 v[238:239], off
	s_waitcnt vmcnt(8)
	s_cmp_lg_u32 s98, 0
	s_cbranch_scc0 .Llk_2
	s_waitcnt lgkmcnt(0)
; #define PG8_STAGE(bufoff, gbase, voff) do { _Pragma("unroll") for (int _i = 0; _i < 2; ++_i) \
;         __builtin_amdgcn_global_load_lds((const unsigned*)((const char*)(gbase) + (voff)[_i]), (PG8_LAS unsigned*)(lds + (bufoff) + ldsw + _i * 8192), 16, 0, 0); } while (0)
; #define PG8_LDA(dst, b, h) do { _Pragma("unroll") for (int m = 0; m < 4; ++m) _Pragma("unroll") for (int k = 0; k < 2; ++k) dst[m][k] = *(const PG8_LAS bf16x8*)(lds + PG8_SA(b, h) + aoff + m * 2048 + k * 1024); } while (0)
; #define PG8_LDB(dst, b, h) do { _Pragma("unroll") for (int n = 0; n < 2; ++n) _Pragma("unroll") for (int k = 0; k < 2; ++k) dst[n][k] = *(const PG8_LAS bf16x8*)(lds + PG8_SB(b, h) + boff + n * 2048 + k * 1024); } while (0)
; #define PG8_MMA(ai, bj, At, Bt) do { __builtin_amdgcn_s_setprio(1); _Pragma("unroll") for (int m = 0; m < 4; ++m) _Pragma("unroll") for (int n = 0; n < 2; ++n) _Pragma("unroll") for (int k = 0; k < 2; ++k) \
;         acc[ai][bj][m][n] = __builtin_amdgcn_mfma_f32_16x16x32_bf16(Bt[n][k], At[m][k], acc[ai][bj][m][n], 0, 0, 0); __builtin_amdgcn_s_setprio(0); } while (0)
; #define PG8_WAIT_V(n) asm volatile("s_waitcnt vmcnt(" #n ")" ::: "memory")
; #define PG8_WAIT_L(n) asm volatile("s_waitcnt lgkmcnt(" #n ")" ::: "memory")
; #define PG8_BAR __builtin_amdgcn_s_barrier()
; #define PG8_SCHED __builtin_amdgcn_sched_barrier(0)
;     ...
;             PG8_WAIT_V(8); PG8_WAIT_L(0); PG8_BAR; PG8_MMA(1, 0, At, B0); PG8_MMA(1, 1, At, B1); PG8_BAR; PG8_SCHED;
;             PG8_LDB(B0, 1, 0); PG8_LDB(B1, 1, 1); PG8_SCHED; PG8_LDA(At, 1, 0); PG8_STAGE(PG8_SA(0, 1), a2 + hstepA, voffA);
;             PG8_WAIT_V(8); PG8_WAIT_L(0); PG8_BAR; PG8_MMA(0, 0, At, B0); PG8_MMA(0, 1, At, B1); PG8_BAR; PG8_SCHED;
.Llk_2:
	s_barrier
	s_setprio 1
	s_waitcnt lgkmcnt(0)
	v_mfma_f32_16x16x32_bf16 v[60:63], v[128:131], v[160:163], v[60:63]
	v_mfma_f32_16x16x32_bf16 v[56:59], v[136:139], v[160:163], v[56:59]
	v_mfma_f32_16x16x32_bf16 v[44:47], v[128:131], v[210:213], v[44:47]
	v_mfma_f32_16x16x32_bf16 v[40:43], v[136:139], v[210:213], v[40:43]
	v_mfma_f32_16x16x32_bf16 v[28:31], v[128:131], v[218:221], v[28:31]
	v_mfma_f32_16x16x32_bf16 v[24:27], v[136:139], v[218:221], v[24:27]
	v_mfma_f32_16x16x32_bf16 v[12:15], v[128:131], v[226:229], v[12:15]
	v_mfma_f32_16x16x32_bf16 v[8:11], v[136:139], v[226:229], v[8:11]
	v_mfma_f32_16x16x32_bf16 v[60:63], v[132:135], v[164:167], v[60:63]
	v_mfma_f32_16x16x32_bf16 v[56:59], v[140:143], v[164:167], v[56:59]
	v_mfma_f32_16x16x32_bf16 v[44:47], v[132:135], v[214:217], v[44:47]
	v_mfma_f32_16x16x32_bf16 v[40:43], v[140:143], v[214:217], v[40:43]
	v_mfma_f32_16x16x32_bf16 v[28:31], v[132:135], v[222:225], v[28:31]
	v_mfma_f32_16x16x32_bf16 v[24:27], v[140:143], v[222:225], v[24:27]
	v_mfma_f32_16x16x32_bf16 v[12:15], v[132:135], v[234:237], v[12:15]
	v_mfma_f32_16x16x32_bf16 v[8:11], v[140:143], v[234:237], v[8:11]
	s_setprio 0
	s_setprio 1
	v_mfma_f32_16x16x32_bf16 v[52:55], v[144:147], v[160:163], v[52:55]
	v_mfma_f32_16x16x32_bf16 v[48:51], v[152:155], v[160:163], v[48:51]
	v_mfma_f32_16x16x32_bf16 v[36:39], v[144:147], v[210:213], v[36:39]
	v_mfma_f32_16x16x32_bf16 v[32:35], v[152:155], v[210:213], v[32:35]
	v_mfma_f32_16x16x32_bf16 v[20:23], v[144:147], v[218:221], v[20:23]
	v_mfma_f32_16x16x32_bf16 v[16:19], v[152:155], v[218:221], v[16:19]
	v_mfma_f32_16x16x32_bf16 v[4:7], v[144:147], v[226:229], v[4:7]
	v_mfma_f32_16x16x32_bf16 v[0:3], v[152:155], v[226:229], v[0:3]
	v_mfma_f32_16x16x32_bf16 v[52:55], v[148:151], v[164:167], v[52:55]
	v_mfma_f32_16x16x32_bf16 v[48:51], v[156:159], v[164:167], v[48:51]
	v_mfma_f32_16x16x32_bf16 v[36:39], v[148:151], v[214:217], v[36:39]
	v_mfma_f32_16x16x32_bf16 v[32:35], v[156:159], v[214:217], v[32:35]
	v_mfma_f32_16x16x32_bf16 v[20:23], v[148:151], v[222:225], v[20:23]
	v_mfma_f32_16x16x32_bf16 v[16:19], v[156:159], v[222:225], v[16:19]
	v_mfma_f32_16x16x32_bf16 v[4:7], v[148:151], v[234:237], v[4:7]
	v_mfma_f32_16x16x32_bf16 v[0:3], v[156:159], v[234:237], v[0:3]
	s_setprio 0
	s_barrier
	s_add_i32 s85, 0, 0x18000
	s_add_i32 s86, 0, 0x1c000
	v_add_u32_e32 v140, s85, v199
	v_add_u32_e32 v156, s86, v199
	ds_read_b128 v[128:131], v140
	ds_read_b128 v[132:135], v140 offset:1024
	ds_read_b128 v[136:139], v140 offset:2048
	ds_read_b128 v[140:143], v140 offset:3072
	ds_read_b128 v[144:147], v156
	ds_read_b128 v[148:151], v156 offset:1024
	ds_read_b128 v[152:155], v156 offset:2048
	ds_read_b128 v[156:159], v156 offset:3072
	s_add_u32 s40, s40, 0x40000
	s_addc_u32 s41, s41, 0
	s_mov_b32 m0, s67
	v_lshl_add_u64 v[240:241], s[40:41], 0, v[174:175]
	ds_read_b128 v[160:163], v207 offset:32768
	ds_read_b128 v[164:167], v207 offset:33792
	ds_read_b128 v[210:213], v207 offset:34816
	ds_read_b128 v[214:217], v207 offset:35840
	ds_read_b128 v[218:221], v207 offset:36864
	ds_read_b128 v[222:225], v207 offset:37888
	ds_read_b128 v[226:229], v207 offset:38912
	ds_read_b128 v[234:237], v207 offset:39936
	global_load_lds_dwordx4 v[240:241], off
	v_lshl_add_u64 v[240:241], s[40:41], 0, v[178:179]
	s_mov_b32 m0, s68
	s_nop 0
	global_load_lds_dwordx4 v[240:241], off
	s_waitcnt vmcnt(8)
	s_cmp_lg_u32 s98, 0
	s_cbranch_scc0 .Llk_3
	s_waitcnt lgkmcnt(0)
; #define PG8_STAGE(bufoff, gbase, voff) do { _Pragma("unroll") for (int _i = 0; _i < 2; ++_i) \
;         __builtin_amdgcn_global_load_lds((const unsigned*)((const char*)(gbase) + (voff)[_i]), (PG8_LAS unsigned*)(lds + (bufoff) + ldsw + _i * 8192), 16, 0, 0); } while (0)
; #define PG8_LDA(dst, b, h) do { _Pragma("unroll") for (int m = 0; m < 4; ++m) _Pragma("unroll") for (int k = 0; k < 2; ++k) dst[m][k] = *(const PG8_LAS bf16x8*)(lds + PG8_SA(b, h) + aoff + m * 2048 + k * 1024); } while (0)
; #define PG8_MMA(ai, bj, At, Bt) do { __builtin_amdgcn_s_setprio(1); _Pragma("unroll") for (int m = 0; m < 4; ++m) _Pragma("unroll") for (int n = 0; n < 2; ++n) _Pragma("unroll") for (int k = 0; k < 2; ++k) \
;         acc[ai][bj][m][n] = __builtin_amdgcn_mfma_f32_16x16x32_bf16(Bt[n][k], At[m][k], acc[ai][bj][m][n], 0, 0, 0); __builtin_amdgcn_s_setprio(0); } while (0)
; #define PG8_WAIT_V(n) asm volatile("s_waitcnt vmcnt(" #n ")" ::: "memory")
; #define PG8_WAIT_L(n) asm volatile("s_waitcnt lgkmcnt(" #n ")" ::: "memory")
; #define PG8_BAR __builtin_amdgcn_s_barrier()
; #define PG8_SCHED __builtin_amdgcn_sched_barrier(0)
;     ...
;             PG8_WAIT_V(8); PG8_WAIT_L(0); PG8_BAR; PG8_MMA(0, 0, At, B0); PG8_MMA(0, 1, At, B1); PG8_BAR; PG8_SCHED;
;             PG8_LDA(At, 1, 1); PG8_STAGE(PG8_SB(1, 0), b3, voffB); PG8_STAGE(PG8_SB(1, 1), b3 + hstepB, voffB); PG8_STAGE(PG8_SA(1, 0), a3, voffA);
;             PG8_WAIT_V(8); PG8_WAIT_L(0); PG8_BAR; PG8_MMA(1, 0, At, B0); PG8_MMA(1, 1, At, B1); PG8_BAR; PG8_SCHED;
.Llk_3:
	s_barrier
	s_setprio 1
	s_waitcnt lgkmcnt(0)
	v_mfma_f32_16x16x32_bf16 v[124:127], v[128:131], v[160:163], v[124:127]
	v_mfma_f32_16x16x32_bf16 v[120:123], v[136:139], v[160:163], v[120:123]
	v_mfma_f32_16x16x32_bf16 v[108:111], v[128:131], v[210:213], v[108:111]
	v_mfma_f32_16x16x32_bf16 v[104:107], v[136:139], v[210:213], v[104:107]
	v_mfma_f32_16x16x32_bf16 v[92:95], v[128:131], v[218:221], v[92:95]
	v_mfma_f32_16x16x32_bf16 v[88:91], v[136:139], v[218:221], v[88:91]
	v_mfma_f32_16x16x32_bf16 v[76:79], v[128:131], v[226:229], v[76:79]
	v_mfma_f32_16x16x32_bf16 v[72:75], v[136:139], v[226:229], v[72:75]
	v_mfma_f32_16x16x32_bf16 v[124:127], v[132:135], v[164:167], v[124:127]
	v_mfma_f32_16x16x32_bf16 v[120:123], v[140:143], v[164:167], v[120:123]
	v_mfma_f32_16x16x32_bf16 v[108:111], v[132:135], v[214:217], v[108:111]
	v_mfma_f32_16x16x32_bf16 v[104:107], v[140:143], v[214:217], v[104:107]
	v_mfma_f32_16x16x32_bf16 v[92:95], v[132:135], v[222:225], v[92:95]
	v_mfma_f32_16x16x32_bf16 v[88:91], v[140:143], v[222:225], v[88:91]
	v_mfma_f32_16x16x32_bf16 v[76:79], v[132:135], v[234:237], v[76:79]
	v_mfma_f32_16x16x32_bf16 v[72:75], v[140:143], v[234:237], v[72:75]
	s_setprio 0
	s_setprio 1
	v_mfma_f32_16x16x32_bf16 v[116:119], v[144:147], v[160:163], v[116:119]
	v_mfma_f32_16x16x32_bf16 v[112:115], v[152:155], v[160:163], v[112:115]
	v_mfma_f32_16x16x32_bf16 v[100:103], v[144:147], v[210:213], v[100:103]
	v_mfma_f32_16x16x32_bf16 v[96:99], v[152:155], v[210:213], v[96:99]
	v_mfma_f32_16x16x32_bf16 v[84:87], v[144:147], v[218:221], v[84:87]
	v_mfma_f32_16x16x32_bf16 v[80:83], v[152:155], v[218:221], v[80:83]
	v_mfma_f32_16x16x32_bf16 v[68:71], v[144:147], v[226:229], v[68:71]
	v_mfma_f32_16x16x32_bf16 v[64:67], v[152:155], v[226:229], v[64:67]
	v_mfma_f32_16x16x32_bf16 v[116:119], v[148:151], v[164:167], v[116:119]
	v_mfma_f32_16x16x32_bf16 v[112:115], v[156:159], v[164:167], v[112:115]
	v_mfma_f32_16x16x32_bf16 v[100:103], v[148:151], v[214:217], v[100:103]
	v_mfma_f32_16x16x32_bf16 v[96:99], v[156:159], v[214:217], v[96:99]
	v_mfma_f32_16x16x32_bf16 v[84:87], v[148:151], v[222:225], v[84:87]
	v_mfma_f32_16x16x32_bf16 v[80:83], v[156:159], v[222:225], v[80:83]
	v_mfma_f32_16x16x32_bf16 v[68:71], v[148:151], v[234:237], v[68:71]
	v_mfma_f32_16x16x32_bf16 v[64:67], v[156:159], v[234:237], v[64:67]
	s_setprio 0
	s_barrier
	s_add_i32 s40, s85, s65
	v_lshl_add_u64 v[192:193], v[192:193], 0, s[26:27]
	s_mov_b32 m0, s40
	ds_read_b128 v[160:163], v207 offset:49152
	ds_read_b128 v[164:167], v207 offset:50176
	ds_read_b128 v[210:213], v207 offset:51200
	ds_read_b128 v[214:217], v207 offset:52224
	ds_read_b128 v[218:221], v207 offset:53248
	ds_read_b128 v[222:225], v207 offset:54272
	ds_read_b128 v[226:229], v207 offset:55296
	ds_read_b128 v[234:237], v207 offset:56320
	global_load_lds_dwordx4 v[192:193], off
	s_add_i32 m0, s40, 0x2000
	s_add_u32 s34, s34, 0x40080
	v_lshl_add_u64 v[192:193], v[202:203], 0, s[26:27]
	s_addc_u32 s35, s35, 0
	s_add_i32 s40, s86, s65
	global_load_lds_dwordx4 v[192:193], off
	v_lshl_add_u64 v[192:193], s[34:35], 0, v[176:177]
	s_mov_b32 m0, s40
	s_nop 0
	global_load_lds_dwordx4 v[192:193], off
	v_lshl_add_u64 v[192:193], s[34:35], 0, v[180:181]
	s_add_i32 m0, s40, 0x2000
	s_nop 0
	global_load_lds_dwordx4 v[192:193], off
	v_lshl_add_u64 v[192:193], v[230:231], 0, s[26:27]
	s_mov_b32 m0, s76
	s_nop 0
	global_load_lds_dwordx4 v[192:193], off
	v_lshl_add_u64 v[192:193], v[238:239], 0, s[26:27]
	s_mov_b32 m0, s77
	s_nop 0
	global_load_lds_dwordx4 v[192:193], off
	s_waitcnt vmcnt(8)
	s_cmp_lg_u32 s98, 0
	s_cbranch_scc0 .Llk_4
	s_waitcnt lgkmcnt(0)
.Llk_4:
	s_barrier
	s_setprio 1
	s_waitcnt lgkmcnt(0)
	v_mfma_f32_16x16x32_bf16 v[60:63], v[128:131], v[160:163], v[60:63]
	v_mfma_f32_16x16x32_bf16 v[56:59], v[136:139], v[160:163], v[56:59]
	v_mfma_f32_16x16x32_bf16 v[44:47], v[128:131], v[210:213], v[44:47]
	v_mfma_f32_16x16x32_bf16 v[40:43], v[136:139], v[210:213], v[40:43]
	v_mfma_f32_16x16x32_bf16 v[28:31], v[128:131], v[218:221], v[28:31]
	v_mfma_f32_16x16x32_bf16 v[24:27], v[136:139], v[218:221], v[24:27]
	v_mfma_f32_16x16x32_bf16 v[12:15], v[128:131], v[226:229], v[12:15]
	v_mfma_f32_16x16x32_bf16 v[8:11], v[136:139], v[226:229], v[8:11]
	v_mfma_f32_16x16x32_bf16 v[60:63], v[132:135], v[164:167], v[60:63]
	v_mfma_f32_16x16x32_bf16 v[56:59], v[140:143], v[164:167], v[56:59]
	v_mfma_f32_16x16x32_bf16 v[44:47], v[132:135], v[214:217], v[44:47]
	v_mfma_f32_16x16x32_bf16 v[40:43], v[140:143], v[214:217], v[40:43]
	v_mfma_f32_16x16x32_bf16 v[28:31], v[132:135], v[222:225], v[28:31]
	v_mfma_f32_16x16x32_bf16 v[24:27], v[140:143], v[222:225], v[24:27]
	v_mfma_f32_16x16x32_bf16 v[12:15], v[132:135], v[234:237], v[12:15]
	v_mfma_f32_16x16x32_bf16 v[8:11], v[140:143], v[234:237], v[8:11]
	s_setprio 0
	s_setprio 1
	v_mfma_f32_16x16x32_bf16 v[52:55], v[144:147], v[160:163], v[52:55]
	v_mfma_f32_16x16x32_bf16 v[48:51], v[152:155], v[160:163], v[48:51]
	v_mfma_f32_16x16x32_bf16 v[36:39], v[144:147], v[210:213], v[36:39]
	v_mfma_f32_16x16x32_bf16 v[32:35], v[152:155], v[210:213], v[32:35]
	v_mfma_f32_16x16x32_bf16 v[20:23], v[144:147], v[218:221], v[20:23]
	v_mfma_f32_16x16x32_bf16 v[16:19], v[152:155], v[218:221], v[16:19]
	v_mfma_f32_16x16x32_bf16 v[4:7], v[144:147], v[226:229], v[4:7]
	v_mfma_f32_16x16x32_bf16 v[0:3], v[152:155], v[226:229], v[0:3]
	v_mfma_f32_16x16x32_bf16 v[52:55], v[148:151], v[164:167], v[52:55]
	v_mfma_f32_16x16x32_bf16 v[48:51], v[156:159], v[164:167], v[48:51]
	v_mfma_f32_16x16x32_bf16 v[36:39], v[148:151], v[214:217], v[36:39]
	v_mfma_f32_16x16x32_bf16 v[32:35], v[156:159], v[214:217], v[32:35]
	v_mfma_f32_16x16x32_bf16 v[20:23], v[148:151], v[222:225], v[20:23]
	v_mfma_f32_16x16x32_bf16 v[16:19], v[156:159], v[222:225], v[16:19]
	v_mfma_f32_16x16x32_bf16 v[4:7], v[148:151], v[234:237], v[4:7]
	v_mfma_f32_16x16x32_bf16 v[0:3], v[156:159], v[234:237], v[0:3]
	s_setprio 0
	s_barrier
	s_add_i32 s63, s63, 2
	s_add_u32 s28, s28, 0x100
	s_addc_u32 s29, s29, 0
	s_add_u32 s51, s51, 0x100
	s_addc_u32 s53, s53, 0
	s_cmp_gt_u32 s63, 13
	s_cbranch_scc0 .LBB0_228
	s_and_b64 vcc, exec, s[36:37]
	s_cbranch_vccz .LBB0_231
	s_barrier

; #define PG8_STAGE(bufoff, gbase, voff) do { _Pragma("unroll") for (int _i = 0; _i < 2; ++_i) \
;         __builtin_amdgcn_global_load_lds((const unsigned*)((const char*)(gbase) + (voff)[_i]), (PG8_LAS unsigned*)(lds + (bufoff) + ldsw + _i * 8192), 16, 0, 0); } while (0)
; #define PG8_LDA(dst, b, h) do { _Pragma("unroll") for (int m = 0; m < 4; ++m) _Pragma("unroll") for (int k = 0; k < 2; ++k) dst[m][k] = *(const PG8_LAS bf16x8*)(lds + PG8_SA(b, h) + aoff + m * 2048 + k * 1024); } while (0)
; #define PG8_LDB(dst, b, h) do { _Pragma("unroll") for (int n = 0; n < 2; ++n) _Pragma("unroll") for (int k = 0; k < 2; ++k) dst[n][k] = *(const PG8_LAS bf16x8*)(lds + PG8_SB(b, h) + boff + n * 2048 + k * 1024); } while (0)
; #define PG8_MMA(ai, bj, At, Bt) do { __builtin_amdgcn_s_setprio(1); _Pragma("unroll") for (int m = 0; m < 4; ++m) _Pragma("unroll") for (int n = 0; n < 2; ++n) _Pragma("unroll") for (int k = 0; k < 2; ++k) \
;         acc[ai][bj][m][n] = __builtin_amdgcn_mfma_f32_16x16x32_bf16(Bt[n][k], At[m][k], acc[ai][bj][m][n], 0, 0, 0); __builtin_amdgcn_s_setprio(0); } while (0)
; #define PG8_WAIT_V(n) asm volatile("s_waitcnt vmcnt(" #n ")" ::: "memory")
; #define PG8_WAIT_L(n) asm volatile("s_waitcnt lgkmcnt(" #n ")" ::: "memory")
; #define PG8_BAR __builtin_amdgcn_s_barrier()
; #define PG8_SCHED __builtin_amdgcn_sched_barrier(0)
;     ...
;             PG8_LDB(B0, 0, 0); PG8_LDB(B1, 0, 1); PG8_SCHED; PG8_LDA(At, 0, 0); PG8_STAGE(PG8_SA(1, 1), a1 + hstepA, voffA);
;             PG8_WAIT_V(8); PG8_WAIT_L(0); PG8_BAR; PG8_MMA(0, 0, At, B0); PG8_MMA(0, 1, At, B1); PG8_BAR; PG8_SCHED;
;             PG8_LDA(At, 0, 1); PG8_STAGE(PG8_SB(0, 0), b2, voffB); PG8_STAGE(PG8_SB(0, 1), b2 + hstepB, voffB); PG8_STAGE(PG8_SA(0, 0), a2, voffA);
;             PG8_WAIT_V(8); PG8_WAIT_L(0); PG8_BAR; PG8_MMA(1, 0, At, B0); PG8_MMA(1, 1, At, B1); PG8_BAR; PG8_SCHED;
.LBB0_396:
	ds_read_b128 v[128:131], v163
	ds_read_b128 v[132:135], v163 offset:1024
	ds_read_b128 v[152:155], v163 offset:2048
	ds_read_b128 v[156:159], v163 offset:3072
	ds_read_b128 v[168:171], v164
	ds_read_b128 v[172:175], v164 offset:1024
	ds_read_b128 v[176:179], v164 offset:2048
	ds_read_b128 v[180:183], v164 offset:3072
	s_add_u32 s34, s28, 0xfffc0080
	s_addc_u32 s35, s29, -1
	s_cmp_eq_u32 s72, 12
	s_cselect_b32 s41, s37, s35
	s_cselect_b32 s40, s68, s34
	s_cselect_b32 s35, s27, s71
	s_cselect_b32 s34, s69, s70
	v_lshl_add_u64 v[160:161], s[28:29], 0, v[144:145]
	s_add_i32 m0, s49, 0xc000
	ds_read_b128 v[184:187], v165
	ds_read_b128 v[188:191], v165 offset:1024
	ds_read_b128 v[192:195], v165 offset:2048
	ds_read_b128 v[196:199], v165 offset:3072
	ds_read_b128 v[200:203], v165 offset:4096
	ds_read_b128 v[204:207], v165 offset:5120
	ds_read_b128 v[208:211], v165 offset:6144
	ds_read_b128 v[212:215], v165 offset:7168
	global_load_lds_dwordx4 v[160:161], off
	v_lshl_add_u64 v[160:161], s[28:29], 0, v[146:147]
	s_add_i32 m0, s49, 0xe000
	s_nop 0
	global_load_lds_dwordx4 v[160:161], off
	s_waitcnt vmcnt(8)
	s_cmp_lg_u32 s98, 0
	s_cbranch_scc0 .Llk_5
	s_waitcnt lgkmcnt(0)
.Llk_5:
	s_barrier
	s_setprio 1
	s_waitcnt lgkmcnt(0)
	v_mfma_f32_16x16x32_bf16 v[124:127], v[128:131], v[184:187], v[124:127]
	v_mfma_f32_16x16x32_bf16 v[120:123], v[152:155], v[184:187], v[120:123]
	v_mfma_f32_16x16x32_bf16 v[108:111], v[128:131], v[192:195], v[108:111]
	v_mfma_f32_16x16x32_bf16 v[104:107], v[152:155], v[192:195], v[104:107]
	v_mfma_f32_16x16x32_bf16 v[92:95], v[128:131], v[200:203], v[92:95]
	v_mfma_f32_16x16x32_bf16 v[88:91], v[152:155], v[200:203], v[88:91]
	v_mfma_f32_16x16x32_bf16 v[76:79], v[128:131], v[208:211], v[76:79]
	v_mfma_f32_16x16x32_bf16 v[72:75], v[152:155], v[208:211], v[72:75]
	v_mfma_f32_16x16x32_bf16 v[124:127], v[132:135], v[188:191], v[124:127]
	v_mfma_f32_16x16x32_bf16 v[120:123], v[156:159], v[188:191], v[120:123]
	v_mfma_f32_16x16x32_bf16 v[108:111], v[132:135], v[196:199], v[108:111]
	v_mfma_f32_16x16x32_bf16 v[104:107], v[156:159], v[196:199], v[104:107]
	v_mfma_f32_16x16x32_bf16 v[92:95], v[132:135], v[204:207], v[92:95]
	v_mfma_f32_16x16x32_bf16 v[88:91], v[156:159], v[204:207], v[88:91]
	v_mfma_f32_16x16x32_bf16 v[76:79], v[132:135], v[212:215], v[76:79]
	v_mfma_f32_16x16x32_bf16 v[72:75], v[156:159], v[212:215], v[72:75]
	s_setprio 0
	s_setprio 1
	v_mfma_f32_16x16x32_bf16 v[116:119], v[168:171], v[184:187], v[116:119]
	v_mfma_f32_16x16x32_bf16 v[112:115], v[176:179], v[184:187], v[112:115]
	v_mfma_f32_16x16x32_bf16 v[100:103], v[168:171], v[192:195], v[100:103]
	v_mfma_f32_16x16x32_bf16 v[96:99], v[176:179], v[192:195], v[96:99]
	v_mfma_f32_16x16x32_bf16 v[84:87], v[168:171], v[200:203], v[84:87]
	v_mfma_f32_16x16x32_bf16 v[80:83], v[176:179], v[200:203], v[80:83]
	v_mfma_f32_16x16x32_bf16 v[68:71], v[168:171], v[208:211], v[68:71]
	v_mfma_f32_16x16x32_bf16 v[64:67], v[176:179], v[208:211], v[64:67]
	v_mfma_f32_16x16x32_bf16 v[116:119], v[172:175], v[188:191], v[116:119]
	v_mfma_f32_16x16x32_bf16 v[112:115], v[180:183], v[188:191], v[112:115]
	v_mfma_f32_16x16x32_bf16 v[100:103], v[172:175], v[196:199], v[100:103]
	v_mfma_f32_16x16x32_bf16 v[96:99], v[180:183], v[196:199], v[96:99]
	v_mfma_f32_16x16x32_bf16 v[84:87], v[172:175], v[204:207], v[84:87]
	v_mfma_f32_16x16x32_bf16 v[80:83], v[180:183], v[204:207], v[80:83]
	v_mfma_f32_16x16x32_bf16 v[68:71], v[172:175], v[212:215], v[68:71]
	v_mfma_f32_16x16x32_bf16 v[64:67], v[180:183], v[212:215], v[64:67]
	s_setprio 0
	s_barrier
	s_add_i32 s73, s62, s52
	v_lshl_add_u64 v[160:161], s[34:35], 0, v[138:139]
	s_mov_b32 m0, s73
	ds_read_b128 v[184:187], v165 offset:16384
	ds_read_b128 v[188:191], v165 offset:17408
	ds_read_b128 v[192:195], v165 offset:18432
	ds_read_b128 v[196:199], v165 offset:19456
	ds_read_b128 v[200:203], v165 offset:20480
	ds_read_b128 v[204:207], v165 offset:21504
	ds_read_b128 v[208:211], v165 offset:22528
	ds_read_b128 v[212:215], v165 offset:23552
	global_load_lds_dwordx4 v[160:161], off
	s_add_i32 m0, s73, 0x2000
	s_add_u32 s74, s34, 0x40000
	v_lshl_add_u64 v[216:217], s[34:35], 0, v[142:143]
	s_addc_u32 s75, s35, 0
	s_add_i32 s73, s63, s52
	global_load_lds_dwordx4 v[216:217], off
	v_lshl_add_u64 v[218:219], s[74:75], 0, v[138:139]
	s_mov_b32 m0, s73
	v_lshl_add_u64 v[220:221], s[40:41], 0, v[140:141]
	global_load_lds_dwordx4 v[218:219], off
	v_lshl_add_u64 v[218:219], s[74:75], 0, v[142:143]
	s_add_i32 m0, s73, 0x2000
	s_nop 0
	global_load_lds_dwordx4 v[218:219], off
	v_lshl_add_u64 v[218:219], s[40:41], 0, v[136:137]
	s_mov_b32 m0, s49
	s_nop 0
	global_load_lds_dwordx4 v[218:219], off
	s_mov_b32 m0, s51
	s_nop 0
	global_load_lds_dwordx4 v[220:221], off
	s_waitcnt vmcnt(8)
	s_cmp_lg_u32 s98, 0
	s_cbranch_scc0 .Llk_6
	s_waitcnt lgkmcnt(0)
; #define PG8_STAGE(bufoff, gbase, voff) do { _Pragma("unroll") for (int _i = 0; _i < 2; ++_i) \
;         __builtin_amdgcn_global_load_lds((const unsigned*)((const char*)(gbase) + (voff)[_i]), (PG8_LAS unsigned*)(lds + (bufoff) + ldsw + _i * 8192), 16, 0, 0); } while (0)
; #define PG8_LDA(dst, b, h) do { _Pragma("unroll") for (int m = 0; m < 4; ++m) _Pragma("unroll") for (int k = 0; k < 2; ++k) dst[m][k] = *(const PG8_LAS bf16x8*)(lds + PG8_SA(b, h) + aoff + m * 2048 + k * 1024); } while (0)
; #define PG8_LDB(dst, b, h) do { _Pragma("unroll") for (int n = 0; n < 2; ++n) _Pragma("unroll") for (int k = 0; k < 2; ++k) dst[n][k] = *(const PG8_LAS bf16x8*)(lds + PG8_SB(b, h) + boff + n * 2048 + k * 1024); } while (0)
; #define PG8_MMA(ai, bj, At, Bt) do { __builtin_amdgcn_s_setprio(1); _Pragma("unroll") for (int m = 0; m < 4; ++m) _Pragma("unroll") for (int n = 0; n < 2; ++n) _Pragma("unroll") for (int k = 0; k < 2; ++k) \
;         acc[ai][bj][m][n] = __builtin_amdgcn_mfma_f32_16x16x32_bf16(Bt[n][k], At[m][k], acc[ai][bj][m][n], 0, 0, 0); __builtin_amdgcn_s_setprio(0); } while (0)
; #define PG8_WAIT_V(n) asm volatile("s_waitcnt vmcnt(" #n ")" ::: "memory")
; #define PG8_WAIT_L(n) asm volatile("s_waitcnt lgkmcnt(" #n ")" ::: "memory")
; #define PG8_BAR __builtin_amdgcn_s_barrier()
; #define PG8_SCHED __builtin_amdgcn_sched_barrier(0)
;     ...
;             PG8_WAIT_V(8); PG8_WAIT_L(0); PG8_BAR; PG8_MMA(1, 0, At, B0); PG8_MMA(1, 1, At, B1); PG8_BAR; PG8_SCHED;
;             PG8_LDB(B0, 1, 0); PG8_LDB(B1, 1, 1); PG8_SCHED; PG8_LDA(At, 1, 0); PG8_STAGE(PG8_SA(0, 1), a2 + hstepA, voffA);
;             PG8_WAIT_V(8); PG8_WAIT_L(0); PG8_BAR; PG8_MMA(0, 0, At, B0); PG8_MMA(0, 1, At, B1); PG8_BAR; PG8_SCHED;
.Llk_6:
	s_barrier
	s_setprio 1
	s_waitcnt lgkmcnt(0)
	v_mfma_f32_16x16x32_bf16 v[60:63], v[128:131], v[184:187], v[60:63]
	v_mfma_f32_16x16x32_bf16 v[56:59], v[152:155], v[184:187], v[56:59]
	v_mfma_f32_16x16x32_bf16 v[44:47], v[128:131], v[192:195], v[44:47]
	v_mfma_f32_16x16x32_bf16 v[40:43], v[152:155], v[192:195], v[40:43]
	v_mfma_f32_16x16x32_bf16 v[28:31], v[128:131], v[200:203], v[28:31]
	v_mfma_f32_16x16x32_bf16 v[24:27], v[152:155], v[200:203], v[24:27]
	v_mfma_f32_16x16x32_bf16 v[12:15], v[128:131], v[208:211], v[12:15]
	v_mfma_f32_16x16x32_bf16 v[8:11], v[152:155], v[208:211], v[8:11]
	v_mfma_f32_16x16x32_bf16 v[60:63], v[132:135], v[188:191], v[60:63]
	v_mfma_f32_16x16x32_bf16 v[56:59], v[156:159], v[188:191], v[56:59]
	v_mfma_f32_16x16x32_bf16 v[44:47], v[132:135], v[196:199], v[44:47]
	v_mfma_f32_16x16x32_bf16 v[40:43], v[156:159], v[196:199], v[40:43]
	v_mfma_f32_16x16x32_bf16 v[28:31], v[132:135], v[204:207], v[28:31]
	v_mfma_f32_16x16x32_bf16 v[24:27], v[156:159], v[204:207], v[24:27]
	v_mfma_f32_16x16x32_bf16 v[12:15], v[132:135], v[212:215], v[12:15]
	v_mfma_f32_16x16x32_bf16 v[8:11], v[156:159], v[212:215], v[8:11]
	s_setprio 0
	s_setprio 1
	v_mfma_f32_16x16x32_bf16 v[52:55], v[168:171], v[184:187], v[52:55]
	v_mfma_f32_16x16x32_bf16 v[48:51], v[176:179], v[184:187], v[48:51]
	v_mfma_f32_16x16x32_bf16 v[36:39], v[168:171], v[192:195], v[36:39]
	v_mfma_f32_16x16x32_bf16 v[32:35], v[176:179], v[192:195], v[32:35]
	v_mfma_f32_16x16x32_bf16 v[20:23], v[168:171], v[200:203], v[20:23]
	v_mfma_f32_16x16x32_bf16 v[16:19], v[176:179], v[200:203], v[16:19]
	v_mfma_f32_16x16x32_bf16 v[4:7], v[168:171], v[208:211], v[4:7]
	v_mfma_f32_16x16x32_bf16 v[0:3], v[176:179], v[208:211], v[0:3]
	v_mfma_f32_16x16x32_bf16 v[52:55], v[172:175], v[188:191], v[52:55]
	v_mfma_f32_16x16x32_bf16 v[48:51], v[180:183], v[188:191], v[48:51]
	v_mfma_f32_16x16x32_bf16 v[36:39], v[172:175], v[196:199], v[36:39]
	v_mfma_f32_16x16x32_bf16 v[32:35], v[180:183], v[196:199], v[32:35]
	v_mfma_f32_16x16x32_bf16 v[20:23], v[172:175], v[204:207], v[20:23]
	v_mfma_f32_16x16x32_bf16 v[16:19], v[180:183], v[204:207], v[16:19]
	v_mfma_f32_16x16x32_bf16 v[4:7], v[172:175], v[212:215], v[4:7]
	v_mfma_f32_16x16x32_bf16 v[0:3], v[180:183], v[212:215], v[0:3]
	s_setprio 0
	s_barrier
	s_add_i32 s73, 0, 0x18000
	s_add_i32 s74, 0, 0x1c000
	v_add_u32_e32 v156, s73, v162
	v_add_u32_e32 v167, s74, v162
	ds_read_b128 v[128:131], v156
	ds_read_b128 v[132:135], v156 offset:1024
	ds_read_b128 v[152:155], v156 offset:2048
	ds_read_b128 v[156:159], v156 offset:3072
	ds_read_b128 v[168:171], v167
	ds_read_b128 v[172:175], v167 offset:1024
	ds_read_b128 v[176:179], v167 offset:2048
	ds_read_b128 v[180:183], v167 offset:3072
	s_add_u32 s40, s40, 0x40000
	s_addc_u32 s41, s41, 0
	s_mov_b32 m0, s53
	v_lshl_add_u64 v[222:223], s[40:41], 0, v[136:137]
	ds_read_b128 v[184:187], v165 offset:32768
	ds_read_b128 v[188:191], v165 offset:33792
	ds_read_b128 v[192:195], v165 offset:34816
	ds_read_b128 v[196:199], v165 offset:35840
	ds_read_b128 v[200:203], v165 offset:36864
	ds_read_b128 v[204:207], v165 offset:37888
	ds_read_b128 v[208:211], v165 offset:38912
	ds_read_b128 v[212:215], v165 offset:39936
	global_load_lds_dwordx4 v[222:223], off
	v_lshl_add_u64 v[222:223], s[40:41], 0, v[140:141]
	s_mov_b32 m0, s54
	s_nop 0
	global_load_lds_dwordx4 v[222:223], off
	s_waitcnt vmcnt(8)
	s_cmp_lg_u32 s98, 0
	s_cbranch_scc0 .Llk_7
	s_waitcnt lgkmcnt(0)
; #define PG8_STAGE(bufoff, gbase, voff) do { _Pragma("unroll") for (int _i = 0; _i < 2; ++_i) \
;         __builtin_amdgcn_global_load_lds((const unsigned*)((const char*)(gbase) + (voff)[_i]), (PG8_LAS unsigned*)(lds + (bufoff) + ldsw + _i * 8192), 16, 0, 0); } while (0)
; #define PG8_LDA(dst, b, h) do { _Pragma("unroll") for (int m = 0; m < 4; ++m) _Pragma("unroll") for (int k = 0; k < 2; ++k) dst[m][k] = *(const PG8_LAS bf16x8*)(lds + PG8_SA(b, h) + aoff + m * 2048 + k * 1024); } while (0)
; #define PG8_MMA(ai, bj, At, Bt) do { __builtin_amdgcn_s_setprio(1); _Pragma("unroll") for (int m = 0; m < 4; ++m) _Pragma("unroll") for (int n = 0; n < 2; ++n) _Pragma("unroll") for (int k = 0; k < 2; ++k) \
;         acc[ai][bj][m][n] = __builtin_amdgcn_mfma_f32_16x16x32_bf16(Bt[n][k], At[m][k], acc[ai][bj][m][n], 0, 0, 0); __builtin_amdgcn_s_setprio(0); } while (0)
; #define PG8_WAIT_V(n) asm volatile("s_waitcnt vmcnt(" #n ")" ::: "memory")
; #define PG8_WAIT_L(n) asm volatile("s_waitcnt lgkmcnt(" #n ")" ::: "memory")
; #define PG8_BAR __builtin_amdgcn_s_barrier()
; #define PG8_SCHED __builtin_amdgcn_sched_barrier(0)
;     ...
;             PG8_WAIT_V(8); PG8_WAIT_L(0); PG8_BAR; PG8_MMA(0, 0, At, B0); PG8_MMA(0, 1, At, B1); PG8_BAR; PG8_SCHED;
;             PG8_LDA(At, 1, 1); PG8_STAGE(PG8_SB(1, 0), b3, voffB); PG8_STAGE(PG8_SB(1, 1), b3 + hstepB, voffB); PG8_STAGE(PG8_SA(1, 0), a3, voffA);
;             PG8_WAIT_V(8); PG8_WAIT_L(0); PG8_BAR; PG8_MMA(1, 0, At, B0); PG8_MMA(1, 1, At, B1); PG8_BAR; PG8_SCHED;
.Llk_7:
	s_barrier
	s_setprio 1
	s_waitcnt lgkmcnt(0)
	v_mfma_f32_16x16x32_bf16 v[124:127], v[128:131], v[184:187], v[124:127]
	v_mfma_f32_16x16x32_bf16 v[120:123], v[152:155], v[184:187], v[120:123]
	v_mfma_f32_16x16x32_bf16 v[108:111], v[128:131], v[192:195], v[108:111]
	v_mfma_f32_16x16x32_bf16 v[104:107], v[152:155], v[192:195], v[104:107]
	v_mfma_f32_16x16x32_bf16 v[92:95], v[128:131], v[200:203], v[92:95]
	v_mfma_f32_16x16x32_bf16 v[88:91], v[152:155], v[200:203], v[88:91]
	v_mfma_f32_16x16x32_bf16 v[76:79], v[128:131], v[208:211], v[76:79]
	v_mfma_f32_16x16x32_bf16 v[72:75], v[152:155], v[208:211], v[72:75]
	v_mfma_f32_16x16x32_bf16 v[124:127], v[132:135], v[188:191], v[124:127]
	v_mfma_f32_16x16x32_bf16 v[120:123], v[156:159], v[188:191], v[120:123]
	v_mfma_f32_16x16x32_bf16 v[108:111], v[132:135], v[196:199], v[108:111]
	v_mfma_f32_16x16x32_bf16 v[104:107], v[156:159], v[196:199], v[104:107]
	v_mfma_f32_16x16x32_bf16 v[92:95], v[132:135], v[204:207], v[92:95]
	v_mfma_f32_16x16x32_bf16 v[88:91], v[156:159], v[204:207], v[88:91]
	v_mfma_f32_16x16x32_bf16 v[76:79], v[132:135], v[212:215], v[76:79]
	v_mfma_f32_16x16x32_bf16 v[72:75], v[156:159], v[212:215], v[72:75]
	s_setprio 0
	s_setprio 1
	v_mfma_f32_16x16x32_bf16 v[116:119], v[168:171], v[184:187], v[116:119]
	v_mfma_f32_16x16x32_bf16 v[112:115], v[176:179], v[184:187], v[112:115]
	v_mfma_f32_16x16x32_bf16 v[100:103], v[168:171], v[192:195], v[100:103]
	v_mfma_f32_16x16x32_bf16 v[96:99], v[176:179], v[192:195], v[96:99]
	v_mfma_f32_16x16x32_bf16 v[84:87], v[168:171], v[200:203], v[84:87]
	v_mfma_f32_16x16x32_bf16 v[80:83], v[176:179], v[200:203], v[80:83]
	v_mfma_f32_16x16x32_bf16 v[68:71], v[168:171], v[208:211], v[68:71]
	v_mfma_f32_16x16x32_bf16 v[64:67], v[176:179], v[208:211], v[64:67]
	v_mfma_f32_16x16x32_bf16 v[116:119], v[172:175], v[188:191], v[116:119]
	v_mfma_f32_16x16x32_bf16 v[112:115], v[180:183], v[188:191], v[112:115]
	v_mfma_f32_16x16x32_bf16 v[100:103], v[172:175], v[196:199], v[100:103]
	v_mfma_f32_16x16x32_bf16 v[96:99], v[180:183], v[196:199], v[96:99]
	v_mfma_f32_16x16x32_bf16 v[84:87], v[172:175], v[204:207], v[84:87]
	v_mfma_f32_16x16x32_bf16 v[80:83], v[180:183], v[204:207], v[80:83]
	v_mfma_f32_16x16x32_bf16 v[68:71], v[172:175], v[212:215], v[68:71]
	v_mfma_f32_16x16x32_bf16 v[64:67], v[180:183], v[212:215], v[64:67]
	s_setprio 0
	s_barrier
	s_add_i32 s40, s73, s52
	v_lshl_add_u64 v[160:161], v[160:161], 0, s[16:17]
	s_mov_b32 m0, s40
	ds_read_b128 v[184:187], v165 offset:49152
	ds_read_b128 v[188:191], v165 offset:50176
	ds_read_b128 v[192:195], v165 offset:51200
	ds_read_b128 v[196:199], v165 offset:52224
	ds_read_b128 v[200:203], v165 offset:53248
	ds_read_b128 v[204:207], v165 offset:54272
	ds_read_b128 v[208:211], v165 offset:55296
	ds_read_b128 v[212:215], v165 offset:56320
	global_load_lds_dwordx4 v[160:161], off
	s_add_i32 m0, s40, 0x2000
	s_add_u32 s34, s34, 0x40080
	v_lshl_add_u64 v[160:161], v[216:217], 0, s[16:17]
	s_addc_u32 s35, s35, 0
	s_add_i32 s40, s74, s52
	global_load_lds_dwordx4 v[160:161], off
	v_lshl_add_u64 v[160:161], s[34:35], 0, v[138:139]
	s_mov_b32 m0, s40
	s_nop 0
	global_load_lds_dwordx4 v[160:161], off
	v_lshl_add_u64 v[160:161], s[34:35], 0, v[142:143]
	s_add_i32 m0, s40, 0x2000
	s_nop 0
	global_load_lds_dwordx4 v[160:161], off
	v_lshl_add_u64 v[160:161], v[218:219], 0, s[16:17]
	s_mov_b32 m0, s58
	s_nop 0
	global_load_lds_dwordx4 v[160:161], off
	v_lshl_add_u64 v[160:161], v[220:221], 0, s[16:17]
	s_mov_b32 m0, s59
	s_nop 0
	global_load_lds_dwordx4 v[160:161], off
	s_waitcnt vmcnt(8)
	s_cmp_lg_u32 s98, 0
	s_cbranch_scc0 .Llk_8
	s_waitcnt lgkmcnt(0)
.Llk_8:
	s_barrier
	s_setprio 1
	s_waitcnt lgkmcnt(0)
	v_mfma_f32_16x16x32_bf16 v[60:63], v[128:131], v[184:187], v[60:63]
	v_mfma_f32_16x16x32_bf16 v[56:59], v[152:155], v[184:187], v[56:59]
	v_mfma_f32_16x16x32_bf16 v[44:47], v[128:131], v[192:195], v[44:47]
	v_mfma_f32_16x16x32_bf16 v[40:43], v[152:155], v[192:195], v[40:43]
	v_mfma_f32_16x16x32_bf16 v[28:31], v[128:131], v[200:203], v[28:31]
	v_mfma_f32_16x16x32_bf16 v[24:27], v[152:155], v[200:203], v[24:27]
	v_mfma_f32_16x16x32_bf16 v[12:15], v[128:131], v[208:211], v[12:15]
	v_mfma_f32_16x16x32_bf16 v[8:11], v[152:155], v[208:211], v[8:11]
	v_mfma_f32_16x16x32_bf16 v[60:63], v[132:135], v[188:191], v[60:63]
	v_mfma_f32_16x16x32_bf16 v[56:59], v[156:159], v[188:191], v[56:59]
	v_mfma_f32_16x16x32_bf16 v[44:47], v[132:135], v[196:199], v[44:47]
	v_mfma_f32_16x16x32_bf16 v[40:43], v[156:159], v[196:199], v[40:43]
	v_mfma_f32_16x16x32_bf16 v[28:31], v[132:135], v[204:207], v[28:31]
	v_mfma_f32_16x16x32_bf16 v[24:27], v[156:159], v[204:207], v[24:27]
	v_mfma_f32_16x16x32_bf16 v[12:15], v[132:135], v[212:215], v[12:15]
	v_mfma_f32_16x16x32_bf16 v[8:11], v[156:159], v[212:215], v[8:11]
	s_setprio 0
	s_setprio 1
	v_mfma_f32_16x16x32_bf16 v[52:55], v[168:171], v[184:187], v[52:55]
	v_mfma_f32_16x16x32_bf16 v[48:51], v[176:179], v[184:187], v[48:51]
	v_mfma_f32_16x16x32_bf16 v[36:39], v[168:171], v[192:195], v[36:39]
	v_mfma_f32_16x16x32_bf16 v[32:35], v[176:179], v[192:195], v[32:35]
	v_mfma_f32_16x16x32_bf16 v[20:23], v[168:171], v[200:203], v[20:23]
	v_mfma_f32_16x16x32_bf16 v[16:19], v[176:179], v[200:203], v[16:19]
	v_mfma_f32_16x16x32_bf16 v[4:7], v[168:171], v[208:211], v[4:7]
	v_mfma_f32_16x16x32_bf16 v[0:3], v[176:179], v[208:211], v[0:3]
	v_mfma_f32_16x16x32_bf16 v[52:55], v[172:175], v[188:191], v[52:55]
	v_mfma_f32_16x16x32_bf16 v[48:51], v[180:183], v[188:191], v[48:51]
	v_mfma_f32_16x16x32_bf16 v[36:39], v[172:175], v[196:199], v[36:39]
	v_mfma_f32_16x16x32_bf16 v[32:35], v[180:183], v[196:199], v[32:35]
	v_mfma_f32_16x16x32_bf16 v[20:23], v[172:175], v[204:207], v[20:23]
	v_mfma_f32_16x16x32_bf16 v[16:19], v[180:183], v[204:207], v[16:19]
	v_mfma_f32_16x16x32_bf16 v[4:7], v[172:175], v[212:215], v[4:7]
	v_mfma_f32_16x16x32_bf16 v[0:3], v[180:183], v[212:215], v[0:3]
	s_setprio 0
	s_barrier
	s_add_i32 s72, s72, 2
	s_add_u32 s28, s28, 0x100
	s_addc_u32 s29, s29, 0
	s_add_u32 s70, s70, 0x100
	s_addc_u32 s71, s71, 0
	s_cmp_gt_u32 s72, 13
	s_cbranch_scc0 .LBB0_396
	s_and_b64 vcc, exec, s[18:19]
	s_cbranch_vccz .LBB0_399
	s_barrier

; #define PG8_STAGE(bufoff, gbase, voff) do { _Pragma("unroll") for (int _i = 0; _i < 2; ++_i) \
;         __builtin_amdgcn_global_load_lds((const unsigned*)((const char*)(gbase) + (voff)[_i]), (PG8_LAS unsigned*)(lds + (bufoff) + ldsw + _i * 8192), 16, 0, 0); } while (0)
; #define PG8_LDA(dst, b, h) do { _Pragma("unroll") for (int m = 0; m < 4; ++m) _Pragma("unroll") for (int k = 0; k < 2; ++k) dst[m][k] = *(const PG8_LAS bf16x8*)(lds + PG8_SA(b, h) + aoff + m * 2048 + k * 1024); } while (0)
; #define PG8_LDB(dst, b, h) do { _Pragma("unroll") for (int n = 0; n < 2; ++n) _Pragma("unroll") for (int k = 0; k < 2; ++k) dst[n][k] = *(const PG8_LAS bf16x8*)(lds + PG8_SB(b, h) + boff + n * 2048 + k * 1024); } while (0)
; #define PG8_MMA(ai, bj, At, Bt) do { __builtin_amdgcn_s_setprio(1); _Pragma("unroll") for (int m = 0; m < 4; ++m) _Pragma("unroll") for (int n = 0; n < 2; ++n) _Pragma("unroll") for (int k = 0; k < 2; ++k) \
;         acc[ai][bj][m][n] = __builtin_amdgcn_mfma_f32_16x16x32_bf16(Bt[n][k], At[m][k], acc[ai][bj][m][n], 0, 0, 0); __builtin_amdgcn_s_setprio(0); } while (0)
; #define PG8_WAIT_V(n) asm volatile("s_waitcnt vmcnt(" #n ")" ::: "memory")
; #define PG8_WAIT_L(n) asm volatile("s_waitcnt lgkmcnt(" #n ")" ::: "memory")
; #define PG8_BAR __builtin_amdgcn_s_barrier()
; #define PG8_SCHED __builtin_amdgcn_sched_barrier(0)
;     ...
;             PG8_LDB(B0, 0, 0); PG8_LDB(B1, 0, 1); PG8_SCHED; PG8_LDA(At, 0, 0); PG8_STAGE(PG8_SA(1, 1), a1 + hstepA, voffA);
;             PG8_WAIT_V(8); PG8_WAIT_L(0); PG8_BAR; PG8_MMA(0, 0, At, B0); PG8_MMA(0, 1, At, B1); PG8_BAR; PG8_SCHED;
;             PG8_LDA(At, 0, 1); PG8_STAGE(PG8_SB(0, 0), b2, voffB); PG8_STAGE(PG8_SB(0, 1), b2 + hstepB, voffB); PG8_STAGE(PG8_SA(0, 0), a2, voffA);
;             PG8_WAIT_V(8); PG8_WAIT_L(0); PG8_BAR; PG8_MMA(1, 0, At, B0); PG8_MMA(1, 1, At, B1); PG8_BAR; PG8_SCHED;
.LBB0_632:
	s_add_u32 s28, s8, 0xfffe0080
	s_addc_u32 s29, s9, -1
	s_add_i32 s48, 0, 0x10000
	s_cmp_eq_u32 s86, 2
	s_cselect_b32 s35, s23, s29
	s_cselect_b32 s34, s37, s28
	s_cselect_b32 s29, s25, s85
	s_cselect_b32 s28, s24, s69
	s_add_i32 s61, 0, 0x14000
	v_add_u32_e32 v142, s48, v1
	v_add_u32_e32 v158, s61, v1
	ds_read_b128 v[130:133], v142
	ds_read_b128 v[134:137], v142 offset:1024
	ds_read_b128 v[138:141], v142 offset:2048
	ds_read_b128 v[142:145], v142 offset:3072
	ds_read_b128 v[146:149], v158
	ds_read_b128 v[150:153], v158 offset:1024
	ds_read_b128 v[154:157], v158 offset:2048
	ds_read_b128 v[158:161], v158 offset:3072
	v_lshl_add_u64 v[188:189], s[8:9], 0, v[170:171]
	s_add_i32 m0, s43, 0xc000
	ds_read_b128 v[174:177], v190
	ds_read_b128 v[180:183], v190 offset:1024
	ds_read_b128 v[184:187], v190 offset:2048
	ds_read_b128 v[192:195], v190 offset:3072
	ds_read_b128 v[196:199], v190 offset:4096
	ds_read_b128 v[200:203], v190 offset:5120
	ds_read_b128 v[204:207], v190 offset:6144
	ds_read_b128 v[210:213], v190 offset:7168
	global_load_lds_dwordx4 v[188:189], off
	v_lshl_add_u64 v[188:189], s[8:9], 0, v[172:173]
	s_add_i32 m0, s43, 0xe000
	s_nop 0
	global_load_lds_dwordx4 v[188:189], off
	s_waitcnt vmcnt(8)
	s_cmp_lg_u32 s98, 0
	s_cbranch_scc0 .Llk_9
	s_waitcnt lgkmcnt(0)
.Llk_9:
	s_barrier
	s_setprio 1
	s_waitcnt lgkmcnt(0)
	v_mfma_f32_16x16x32_bf16 v[126:129], v[130:133], v[174:177], v[126:129]
	v_mfma_f32_16x16x32_bf16 v[122:125], v[138:141], v[174:177], v[122:125]
	v_mfma_f32_16x16x32_bf16 v[110:113], v[130:133], v[184:187], v[110:113]
	v_mfma_f32_16x16x32_bf16 v[106:109], v[138:141], v[184:187], v[106:109]
	v_mfma_f32_16x16x32_bf16 v[94:97], v[130:133], v[196:199], v[94:97]
	v_mfma_f32_16x16x32_bf16 v[90:93], v[138:141], v[196:199], v[90:93]
	v_mfma_f32_16x16x32_bf16 v[78:81], v[130:133], v[204:207], v[78:81]
	v_mfma_f32_16x16x32_bf16 v[74:77], v[138:141], v[204:207], v[74:77]
	v_mfma_f32_16x16x32_bf16 v[126:129], v[134:137], v[180:183], v[126:129]
	v_mfma_f32_16x16x32_bf16 v[122:125], v[142:145], v[180:183], v[122:125]
	v_mfma_f32_16x16x32_bf16 v[110:113], v[134:137], v[192:195], v[110:113]
	v_mfma_f32_16x16x32_bf16 v[106:109], v[142:145], v[192:195], v[106:109]
	v_mfma_f32_16x16x32_bf16 v[94:97], v[134:137], v[200:203], v[94:97]
	v_mfma_f32_16x16x32_bf16 v[90:93], v[142:145], v[200:203], v[90:93]
	v_mfma_f32_16x16x32_bf16 v[78:81], v[134:137], v[210:213], v[78:81]
	v_mfma_f32_16x16x32_bf16 v[74:77], v[142:145], v[210:213], v[74:77]
	s_setprio 0
	s_setprio 1
	v_mfma_f32_16x16x32_bf16 v[118:121], v[146:149], v[174:177], v[118:121]
	v_mfma_f32_16x16x32_bf16 v[114:117], v[154:157], v[174:177], v[114:117]
	v_mfma_f32_16x16x32_bf16 v[102:105], v[146:149], v[184:187], v[102:105]
	v_mfma_f32_16x16x32_bf16 v[98:101], v[154:157], v[184:187], v[98:101]
	v_mfma_f32_16x16x32_bf16 v[86:89], v[146:149], v[196:199], v[86:89]
	v_mfma_f32_16x16x32_bf16 v[82:85], v[154:157], v[196:199], v[82:85]
	v_mfma_f32_16x16x32_bf16 v[70:73], v[146:149], v[204:207], v[70:73]
	v_mfma_f32_16x16x32_bf16 v[66:69], v[154:157], v[204:207], v[66:69]
	v_mfma_f32_16x16x32_bf16 v[118:121], v[150:153], v[180:183], v[118:121]
	v_mfma_f32_16x16x32_bf16 v[114:117], v[158:161], v[180:183], v[114:117]
	v_mfma_f32_16x16x32_bf16 v[102:105], v[150:153], v[192:195], v[102:105]
	v_mfma_f32_16x16x32_bf16 v[98:101], v[158:161], v[192:195], v[98:101]
	v_mfma_f32_16x16x32_bf16 v[86:89], v[150:153], v[200:203], v[86:89]
	v_mfma_f32_16x16x32_bf16 v[82:85], v[158:161], v[200:203], v[82:85]
	v_mfma_f32_16x16x32_bf16 v[70:73], v[150:153], v[210:213], v[70:73]
	v_mfma_f32_16x16x32_bf16 v[66:69], v[158:161], v[210:213], v[66:69]
	s_setprio 0
	s_barrier
	s_add_i32 s48, s48, s42
	v_lshl_add_u64 v[188:189], s[28:29], 0, v[166:167]
	s_mov_b32 m0, s48
	ds_read_b128 v[174:177], v190 offset:16384
	ds_read_b128 v[180:183], v190 offset:17408
	ds_read_b128 v[184:187], v190 offset:18432
	ds_read_b128 v[192:195], v190 offset:19456
	ds_read_b128 v[196:199], v190 offset:20480
	ds_read_b128 v[200:203], v190 offset:21504
	ds_read_b128 v[204:207], v190 offset:22528
	ds_read_b128 v[210:213], v190 offset:23552
	global_load_lds_dwordx4 v[188:189], off
	s_add_i32 m0, s48, 0x2000
	s_add_u32 s48, s28, 0x18000
	v_lshl_add_u64 v[214:215], s[28:29], 0, v[162:163]
	s_addc_u32 s49, s29, 0
	s_add_i32 s61, s61, s42
	global_load_lds_dwordx4 v[214:215], off
	v_lshl_add_u64 v[216:217], s[48:49], 0, v[166:167]
	s_mov_b32 m0, s61
	v_lshl_add_u64 v[218:219], s[34:35], 0, v[164:165]
	global_load_lds_dwordx4 v[216:217], off
	v_lshl_add_u64 v[216:217], s[48:49], 0, v[162:163]
	s_add_i32 m0, s61, 0x2000
	s_nop 0
	global_load_lds_dwordx4 v[216:217], off
	v_lshl_add_u64 v[216:217], s[34:35], 0, v[168:169]
	s_mov_b32 m0, s43
	s_nop 0
	global_load_lds_dwordx4 v[216:217], off
	s_mov_b32 m0, s44
	s_nop 0
	global_load_lds_dwordx4 v[218:219], off
	s_waitcnt vmcnt(8)
	s_cmp_lg_u32 s98, 0
	s_cbranch_scc0 .Llk_10
	s_waitcnt lgkmcnt(0)
; #define PG8_STAGE(bufoff, gbase, voff) do { _Pragma("unroll") for (int _i = 0; _i < 2; ++_i) \
;         __builtin_amdgcn_global_load_lds((const unsigned*)((const char*)(gbase) + (voff)[_i]), (PG8_LAS unsigned*)(lds + (bufoff) + ldsw + _i * 8192), 16, 0, 0); } while (0)
; #define PG8_LDA(dst, b, h) do { _Pragma("unroll") for (int m = 0; m < 4; ++m) _Pragma("unroll") for (int k = 0; k < 2; ++k) dst[m][k] = *(const PG8_LAS bf16x8*)(lds + PG8_SA(b, h) + aoff + m * 2048 + k * 1024); } while (0)
; #define PG8_LDB(dst, b, h) do { _Pragma("unroll") for (int n = 0; n < 2; ++n) _Pragma("unroll") for (int k = 0; k < 2; ++k) dst[n][k] = *(const PG8_LAS bf16x8*)(lds + PG8_SB(b, h) + boff + n * 2048 + k * 1024); } while (0)
; #define PG8_MMA(ai, bj, At, Bt) do { __builtin_amdgcn_s_setprio(1); _Pragma("unroll") for (int m = 0; m < 4; ++m) _Pragma("unroll") for (int n = 0; n < 2; ++n) _Pragma("unroll") for (int k = 0; k < 2; ++k) \
;         acc[ai][bj][m][n] = __builtin_amdgcn_mfma_f32_16x16x32_bf16(Bt[n][k], At[m][k], acc[ai][bj][m][n], 0, 0, 0); __builtin_amdgcn_s_setprio(0); } while (0)
; #define PG8_WAIT_V(n) asm volatile("s_waitcnt vmcnt(" #n ")" ::: "memory")
; #define PG8_WAIT_L(n) asm volatile("s_waitcnt lgkmcnt(" #n ")" ::: "memory")
; #define PG8_BAR __builtin_amdgcn_s_barrier()
; #define PG8_SCHED __builtin_amdgcn_sched_barrier(0)
;     ...
;             PG8_WAIT_V(8); PG8_WAIT_L(0); PG8_BAR; PG8_MMA(1, 0, At, B0); PG8_MMA(1, 1, At, B1); PG8_BAR; PG8_SCHED;
;             PG8_LDB(B0, 1, 0); PG8_LDB(B1, 1, 1); PG8_SCHED; PG8_LDA(At, 1, 0); PG8_STAGE(PG8_SA(0, 1), a2 + hstepA, voffA);
;             PG8_WAIT_V(8); PG8_WAIT_L(0); PG8_BAR; PG8_MMA(0, 0, At, B0); PG8_MMA(0, 1, At, B1); PG8_BAR; PG8_SCHED;
.Llk_10:
	s_barrier
	s_setprio 1
	s_waitcnt lgkmcnt(0)
	v_mfma_f32_16x16x32_bf16 v[62:65], v[130:133], v[174:177], v[62:65]
	v_mfma_f32_16x16x32_bf16 v[58:61], v[138:141], v[174:177], v[58:61]
	v_mfma_f32_16x16x32_bf16 v[46:49], v[130:133], v[184:187], v[46:49]
	v_mfma_f32_16x16x32_bf16 v[42:45], v[138:141], v[184:187], v[42:45]
	v_mfma_f32_16x16x32_bf16 v[30:33], v[130:133], v[196:199], v[30:33]
	v_mfma_f32_16x16x32_bf16 v[26:29], v[138:141], v[196:199], v[26:29]
	v_mfma_f32_16x16x32_bf16 v[14:17], v[130:133], v[204:207], v[14:17]
	v_mfma_f32_16x16x32_bf16 v[10:13], v[138:141], v[204:207], v[10:13]
	v_mfma_f32_16x16x32_bf16 v[62:65], v[134:137], v[180:183], v[62:65]
	v_mfma_f32_16x16x32_bf16 v[58:61], v[142:145], v[180:183], v[58:61]
	v_mfma_f32_16x16x32_bf16 v[46:49], v[134:137], v[192:195], v[46:49]
	v_mfma_f32_16x16x32_bf16 v[42:45], v[142:145], v[192:195], v[42:45]
	v_mfma_f32_16x16x32_bf16 v[30:33], v[134:137], v[200:203], v[30:33]
	v_mfma_f32_16x16x32_bf16 v[26:29], v[142:145], v[200:203], v[26:29]
	v_mfma_f32_16x16x32_bf16 v[14:17], v[134:137], v[210:213], v[14:17]
	v_mfma_f32_16x16x32_bf16 v[10:13], v[142:145], v[210:213], v[10:13]
	s_setprio 0
	s_setprio 1
	v_mfma_f32_16x16x32_bf16 v[54:57], v[146:149], v[174:177], v[54:57]
	v_mfma_f32_16x16x32_bf16 v[50:53], v[154:157], v[174:177], v[50:53]
	v_mfma_f32_16x16x32_bf16 v[38:41], v[146:149], v[184:187], v[38:41]
	v_mfma_f32_16x16x32_bf16 v[34:37], v[154:157], v[184:187], v[34:37]
	v_mfma_f32_16x16x32_bf16 v[22:25], v[146:149], v[196:199], v[22:25]
	v_mfma_f32_16x16x32_bf16 v[18:21], v[154:157], v[196:199], v[18:21]
	v_mfma_f32_16x16x32_bf16 v[6:9], v[146:149], v[204:207], v[6:9]
	v_mfma_f32_16x16x32_bf16 v[2:5], v[154:157], v[204:207], v[2:5]
	v_mfma_f32_16x16x32_bf16 v[54:57], v[150:153], v[180:183], v[54:57]
	v_mfma_f32_16x16x32_bf16 v[50:53], v[158:161], v[180:183], v[50:53]
	v_mfma_f32_16x16x32_bf16 v[38:41], v[150:153], v[192:195], v[38:41]
	v_mfma_f32_16x16x32_bf16 v[34:37], v[158:161], v[192:195], v[34:37]
	v_mfma_f32_16x16x32_bf16 v[22:25], v[150:153], v[200:203], v[22:25]
	v_mfma_f32_16x16x32_bf16 v[18:21], v[158:161], v[200:203], v[18:21]
	v_mfma_f32_16x16x32_bf16 v[6:9], v[150:153], v[210:213], v[6:9]
	v_mfma_f32_16x16x32_bf16 v[2:5], v[158:161], v[210:213], v[2:5]
	s_setprio 0
	s_barrier
	s_add_i32 s48, 0, 0x18000
	s_add_i32 s49, 0, 0x1c000
	v_add_u32_e32 v142, s48, v1
	v_add_u32_e32 v158, s49, v1
	ds_read_b128 v[130:133], v142
	ds_read_b128 v[134:137], v142 offset:1024
	ds_read_b128 v[138:141], v142 offset:2048
	ds_read_b128 v[142:145], v142 offset:3072
	ds_read_b128 v[146:149], v158
	ds_read_b128 v[150:153], v158 offset:1024
	ds_read_b128 v[154:157], v158 offset:2048
	ds_read_b128 v[158:161], v158 offset:3072
	s_add_u32 s34, s34, 0x20000
	s_addc_u32 s35, s35, 0
	s_mov_b32 m0, s45
	v_lshl_add_u64 v[222:223], s[34:35], 0, v[168:169]
	ds_read_b128 v[174:177], v190 offset:32768
	ds_read_b128 v[180:183], v190 offset:33792
	ds_read_b128 v[184:187], v190 offset:34816
	ds_read_b128 v[192:195], v190 offset:35840
	ds_read_b128 v[196:199], v190 offset:36864
	ds_read_b128 v[200:203], v190 offset:37888
	ds_read_b128 v[204:207], v190 offset:38912
	ds_read_b128 v[210:213], v190 offset:39936
	global_load_lds_dwordx4 v[222:223], off
	v_lshl_add_u64 v[222:223], s[34:35], 0, v[164:165]
	s_mov_b32 m0, s46
	s_nop 0
	global_load_lds_dwordx4 v[222:223], off
	s_waitcnt vmcnt(8)
	s_cmp_lg_u32 s98, 0
	s_cbranch_scc0 .Llk_11
	s_waitcnt lgkmcnt(0)
; #define PG8_STAGE(bufoff, gbase, voff) do { _Pragma("unroll") for (int _i = 0; _i < 2; ++_i) \
;         __builtin_amdgcn_global_load_lds((const unsigned*)((const char*)(gbase) + (voff)[_i]), (PG8_LAS unsigned*)(lds + (bufoff) + ldsw + _i * 8192), 16, 0, 0); } while (0)
; #define PG8_LDA(dst, b, h) do { _Pragma("unroll") for (int m = 0; m < 4; ++m) _Pragma("unroll") for (int k = 0; k < 2; ++k) dst[m][k] = *(const PG8_LAS bf16x8*)(lds + PG8_SA(b, h) + aoff + m * 2048 + k * 1024); } while (0)
; #define PG8_LDB(dst, b, h) do { _Pragma("unroll") for (int n = 0; n < 2; ++n) _Pragma("unroll") for (int k = 0; k < 2; ++k) dst[n][k] = *(const PG8_LAS bf16x8*)(lds + PG8_SB(b, h) + boff + n * 2048 + k * 1024); } while (0)
; #define PG8_MMA(ai, bj, At, Bt) do { __builtin_amdgcn_s_setprio(1); _Pragma("unroll") for (int m = 0; m < 4; ++m) _Pragma("unroll") for (int n = 0; n < 2; ++n) _Pragma("unroll") for (int k = 0; k < 2; ++k) \
;         acc[ai][bj][m][n] = __builtin_amdgcn_mfma_f32_16x16x32_bf16(Bt[n][k], At[m][k], acc[ai][bj][m][n], 0, 0, 0); __builtin_amdgcn_s_setprio(0); } while (0)
; #define PG8_WAIT_V(n) asm volatile("s_waitcnt vmcnt(" #n ")" ::: "memory")
; #define PG8_WAIT_L(n) asm volatile("s_waitcnt lgkmcnt(" #n ")" ::: "memory")
; #define PG8_BAR __builtin_amdgcn_s_barrier()
; #define PG8_SCHED __builtin_amdgcn_sched_barrier(0)
;     ...
;             PG8_LDB(B0, 0, 0); PG8_LDB(B1, 0, 1); PG8_SCHED; PG8_LDA(At, 0, 0); PG8_STAGE(PG8_SA(1, 1), a1 + hstepA, voffA);
;             PG8_WAIT_V(8); PG8_WAIT_L(0); PG8_BAR; PG8_MMA(0, 0, At, B0); PG8_MMA(0, 1, At, B1); PG8_BAR; PG8_SCHED;
;             PG8_LDA(At, 0, 1); PG8_STAGE(PG8_SB(0, 0), b2, voffB); PG8_STAGE(PG8_SB(0, 1), b2 + hstepB, voffB); PG8_STAGE(PG8_SA(0, 0), a2, voffA);
;             PG8_WAIT_V(8); PG8_WAIT_L(0); PG8_BAR; PG8_MMA(1, 0, At, B0); PG8_MMA(1, 1, At, B1); PG8_BAR; PG8_SCHED;
;             PG8_LDB(B0, 1, 0); PG8_LDB(B1, 1, 1); PG8_SCHED; PG8_LDA(At, 1, 0); PG8_STAGE(PG8_SA(0, 1), a2 + hstepA, voffA);
;             PG8_WAIT_V(8); PG8_WAIT_L(0); PG8_BAR; PG8_MMA(0, 0, At, B0); PG8_MMA(0, 1, At, B1); PG8_BAR; PG8_SCHED;
;             PG8_LDA(At, 1, 1); PG8_STAGE(PG8_SB(1, 0), b3, voffB); PG8_STAGE(PG8_SB(1, 1), b3 + hstepB, voffB); PG8_STAGE(PG8_SA(1, 0), a3, voffA);
;             PG8_WAIT_V(8); PG8_WAIT_L(0); PG8_BAR; PG8_MMA(1, 0, At, B0); PG8_MMA(1, 1, At, B1); PG8_BAR; PG8_SCHED;
.Llk_11:
	s_barrier
	s_setprio 1
	s_waitcnt lgkmcnt(0)
	v_mfma_f32_16x16x32_bf16 v[126:129], v[130:133], v[174:177], v[126:129]
	v_mfma_f32_16x16x32_bf16 v[122:125], v[138:141], v[174:177], v[122:125]
	v_mfma_f32_16x16x32_bf16 v[110:113], v[130:133], v[184:187], v[110:113]
	v_mfma_f32_16x16x32_bf16 v[106:109], v[138:141], v[184:187], v[106:109]
	v_mfma_f32_16x16x32_bf16 v[94:97], v[130:133], v[196:199], v[94:97]
	v_mfma_f32_16x16x32_bf16 v[90:93], v[138:141], v[196:199], v[90:93]
	v_mfma_f32_16x16x32_bf16 v[78:81], v[130:133], v[204:207], v[78:81]
	v_mfma_f32_16x16x32_bf16 v[74:77], v[138:141], v[204:207], v[74:77]
	v_mfma_f32_16x16x32_bf16 v[126:129], v[134:137], v[180:183], v[126:129]
	v_mfma_f32_16x16x32_bf16 v[122:125], v[142:145], v[180:183], v[122:125]
	v_mfma_f32_16x16x32_bf16 v[110:113], v[134:137], v[192:195], v[110:113]
	v_mfma_f32_16x16x32_bf16 v[106:109], v[142:145], v[192:195], v[106:109]
	v_mfma_f32_16x16x32_bf16 v[94:97], v[134:137], v[200:203], v[94:97]
	v_mfma_f32_16x16x32_bf16 v[90:93], v[142:145], v[200:203], v[90:93]
	v_mfma_f32_16x16x32_bf16 v[78:81], v[134:137], v[210:213], v[78:81]
	v_mfma_f32_16x16x32_bf16 v[74:77], v[142:145], v[210:213], v[74:77]
	s_setprio 0
	s_setprio 1
	v_mfma_f32_16x16x32_bf16 v[118:121], v[146:149], v[174:177], v[118:121]
	v_mfma_f32_16x16x32_bf16 v[114:117], v[154:157], v[174:177], v[114:117]
	v_mfma_f32_16x16x32_bf16 v[102:105], v[146:149], v[184:187], v[102:105]
	v_mfma_f32_16x16x32_bf16 v[98:101], v[154:157], v[184:187], v[98:101]
	v_mfma_f32_16x16x32_bf16 v[86:89], v[146:149], v[196:199], v[86:89]
	v_mfma_f32_16x16x32_bf16 v[82:85], v[154:157], v[196:199], v[82:85]
	v_mfma_f32_16x16x32_bf16 v[70:73], v[146:149], v[204:207], v[70:73]
	v_mfma_f32_16x16x32_bf16 v[66:69], v[154:157], v[204:207], v[66:69]
	v_mfma_f32_16x16x32_bf16 v[118:121], v[150:153], v[180:183], v[118:121]
	v_mfma_f32_16x16x32_bf16 v[114:117], v[158:161], v[180:183], v[114:117]
	v_mfma_f32_16x16x32_bf16 v[102:105], v[150:153], v[192:195], v[102:105]
	v_mfma_f32_16x16x32_bf16 v[98:101], v[158:161], v[192:195], v[98:101]
	v_mfma_f32_16x16x32_bf16 v[86:89], v[150:153], v[200:203], v[86:89]
	v_mfma_f32_16x16x32_bf16 v[82:85], v[158:161], v[200:203], v[82:85]
	v_mfma_f32_16x16x32_bf16 v[70:73], v[150:153], v[210:213], v[70:73]
	v_mfma_f32_16x16x32_bf16 v[66:69], v[158:161], v[210:213], v[66:69]
	s_setprio 0
	s_barrier
	s_add_i32 s34, s48, s42
	v_lshl_add_u64 v[188:189], v[188:189], 0, s[66:67]
	s_mov_b32 m0, s34
	ds_read_b128 v[174:177], v190 offset:49152
	ds_read_b128 v[180:183], v190 offset:50176
	ds_read_b128 v[184:187], v190 offset:51200
	ds_read_b128 v[192:195], v190 offset:52224
	ds_read_b128 v[196:199], v190 offset:53248
	ds_read_b128 v[200:203], v190 offset:54272
	ds_read_b128 v[204:207], v190 offset:55296
	ds_read_b128 v[210:213], v190 offset:56320
	global_load_lds_dwordx4 v[188:189], off
	s_add_i32 m0, s34, 0x2000
	s_add_u32 s28, s28, 0x18080
	v_lshl_add_u64 v[188:189], v[214:215], 0, s[66:67]
	s_addc_u32 s29, s29, 0
	s_add_i32 s34, s49, s42
	global_load_lds_dwordx4 v[188:189], off
	v_lshl_add_u64 v[188:189], s[28:29], 0, v[166:167]
	s_mov_b32 m0, s34
	s_nop 0
	global_load_lds_dwordx4 v[188:189], off
	v_lshl_add_u64 v[188:189], s[28:29], 0, v[162:163]
	s_add_i32 m0, s34, 0x2000
	s_nop 0
	global_load_lds_dwordx4 v[188:189], off
	v_lshl_add_u64 v[188:189], v[216:217], 0, s[66:67]
	s_mov_b32 m0, s55
	s_nop 0
	global_load_lds_dwordx4 v[188:189], off
	v_lshl_add_u64 v[188:189], v[218:219], 0, s[66:67]
	s_mov_b32 m0, s56
	s_nop 0
	global_load_lds_dwordx4 v[188:189], off
	s_waitcnt vmcnt(8)
	s_cmp_lg_u32 s98, 0
	s_cbranch_scc0 .Llk_12
	s_waitcnt lgkmcnt(0)
.Llk_12:
	s_barrier
	s_setprio 1
	s_waitcnt lgkmcnt(0)
	v_mfma_f32_16x16x32_bf16 v[62:65], v[130:133], v[174:177], v[62:65]
	v_mfma_f32_16x16x32_bf16 v[58:61], v[138:141], v[174:177], v[58:61]
	v_mfma_f32_16x16x32_bf16 v[46:49], v[130:133], v[184:187], v[46:49]
	v_mfma_f32_16x16x32_bf16 v[42:45], v[138:141], v[184:187], v[42:45]
	v_mfma_f32_16x16x32_bf16 v[30:33], v[130:133], v[196:199], v[30:33]
	v_mfma_f32_16x16x32_bf16 v[26:29], v[138:141], v[196:199], v[26:29]
	v_mfma_f32_16x16x32_bf16 v[14:17], v[130:133], v[204:207], v[14:17]
	v_mfma_f32_16x16x32_bf16 v[10:13], v[138:141], v[204:207], v[10:13]
	v_mfma_f32_16x16x32_bf16 v[62:65], v[134:137], v[180:183], v[62:65]
	v_mfma_f32_16x16x32_bf16 v[58:61], v[142:145], v[180:183], v[58:61]
	v_mfma_f32_16x16x32_bf16 v[46:49], v[134:137], v[192:195], v[46:49]
	v_mfma_f32_16x16x32_bf16 v[42:45], v[142:145], v[192:195], v[42:45]
	v_mfma_f32_16x16x32_bf16 v[30:33], v[134:137], v[200:203], v[30:33]
	v_mfma_f32_16x16x32_bf16 v[26:29], v[142:145], v[200:203], v[26:29]
	v_mfma_f32_16x16x32_bf16 v[14:17], v[134:137], v[210:213], v[14:17]
	v_mfma_f32_16x16x32_bf16 v[10:13], v[142:145], v[210:213], v[10:13]
	s_setprio 0
	s_setprio 1
	v_mfma_f32_16x16x32_bf16 v[54:57], v[146:149], v[174:177], v[54:57]
	v_mfma_f32_16x16x32_bf16 v[50:53], v[154:157], v[174:177], v[50:53]
	v_mfma_f32_16x16x32_bf16 v[38:41], v[146:149], v[184:187], v[38:41]
	v_mfma_f32_16x16x32_bf16 v[34:37], v[154:157], v[184:187], v[34:37]
	v_mfma_f32_16x16x32_bf16 v[22:25], v[146:149], v[196:199], v[22:25]
	v_mfma_f32_16x16x32_bf16 v[18:21], v[154:157], v[196:199], v[18:21]
	v_mfma_f32_16x16x32_bf16 v[6:9], v[146:149], v[204:207], v[6:9]
	v_mfma_f32_16x16x32_bf16 v[2:5], v[154:157], v[204:207], v[2:5]
	v_mfma_f32_16x16x32_bf16 v[54:57], v[150:153], v[180:183], v[54:57]
	v_mfma_f32_16x16x32_bf16 v[50:53], v[158:161], v[180:183], v[50:53]
	v_mfma_f32_16x16x32_bf16 v[38:41], v[150:153], v[192:195], v[38:41]
	v_mfma_f32_16x16x32_bf16 v[34:37], v[158:161], v[192:195], v[34:37]
	v_mfma_f32_16x16x32_bf16 v[22:25], v[150:153], v[200:203], v[22:25]
	v_mfma_f32_16x16x32_bf16 v[18:21], v[158:161], v[200:203], v[18:21]
	v_mfma_f32_16x16x32_bf16 v[6:9], v[150:153], v[210:213], v[6:9]
	v_mfma_f32_16x16x32_bf16 v[2:5], v[158:161], v[210:213], v[2:5]
	s_setprio 0
	s_barrier
	s_add_i32 s86, s86, 2
	s_add_u32 s8, s8, 0x100
	s_addc_u32 s9, s9, 0
	s_add_u32 s69, s69, 0x100
	s_addc_u32 s85, s85, 0
	s_cmp_gt_u32 s86, 3
	s_cbranch_scc0 .LBB0_632
	s_and_b64 vcc, exec, s[20:21]
	s_cbranch_vccz .LBB0_635
	s_barrier

;     __host__ __device__ bool next(int i, Unit& u) const { if (rev) { if (i >= 21) return false; return StaticOrder::next(20 - i, u); } return StaticOrder::next(i, u); }
; #define PG8_STAGE(bufoff, gbase, voff) do { _Pragma("unroll") for (int _i = 0; _i < 2; ++_i) \
;         __builtin_amdgcn_global_load_lds((const unsigned*)((const char*)(gbase) + (voff)[_i]), (PG8_LAS unsigned*)(lds + (bufoff) + ldsw + _i * 8192), 16, 0, 0); } while (0)
; #define PG8_LDA(dst, b, h) do { _Pragma("unroll") for (int m = 0; m < 4; ++m) _Pragma("unroll") for (int k = 0; k < 2; ++k) dst[m][k] = *(const PG8_LAS bf16x8*)(lds + PG8_SA(b, h) + aoff + m * 2048 + k * 1024); } while (0)
;     ...
;         const bool has_next = S.next(ui + 1, nxt);
;         const char* nA = has_next ? (const char*)g.A + (size_t)nxt.pm * tstepA : cA; const char* nB = has_next ? (const char*)g.Bt + (size_t)nxt.pn * tstepB : cB;
; #pragma unroll 1
;         for (int t = 0; t < nt; t += 2) {
;             const bool last = (t == nt - 2);
;             const char* a1 = cA + (size_t)(t + 1) * kstep;
;             const char* a2 = last ? nA : cA + (size_t)(t + 2) * kstep; const char* b2 = last ? nB : cB + (size_t)(t + 2) * kstep;
;             const char* a3 = a2 + kstep; const char* b3 = b2 + kstep;
;             if (last && has_next) S.a_ready(nxt);
;             if constexpr (SP2) {
;             PG8_LDB(B0, 0, 0); PG8_LDB(B1, 0, 1); PG8_SCHED; PG8_LDA(At, 0, 0); PG8_STAGE(PG8_SA(1, 1), a1 + hstepA, voffA);
;             PG8_WAIT_V(8); PG8_WAIT_L(0); PG8_BAR; PG8_MMA(0, 0, At, B0); PG8_MMA(0, 1, At, B1); PG8_BAR; PG8_SCHED;
;             PG8_LDA(At, 0, 1); PG8_STAGE(PG8_SB(0, 0), b2, voffB); PG8_STAGE(PG8_SB(0, 1), b2 + hstepB, voffB); PG8_STAGE(PG8_SA(0, 0), a2, voffA);
;             PG8_WAIT_V(8); PG8_WAIT_L(0); PG8_BAR; PG8_MMA(1, 0, At, B0); PG8_MMA(1, 1, At, B1); PG8_BAR; PG8_SCHED;
;             PG8_LDB(B0, 1, 0); PG8_LDB(B1, 1, 1); PG8_SCHED; PG8_LDA(At, 1, 0); PG8_STAGE(PG8_SA(0, 1), a2 + hstepA, voffA);
;             PG8_WAIT_V(8); PG8_WAIT_L(0); PG8_BAR; PG8_MMA(0, 0, At, B0); PG8_MMA(0, 1, At, B1); PG8_BAR; PG8_SCHED;
;             PG8_LDA(At, 1, 1); PG8_STAGE(PG8_SB(1, 0), b3, voffB); PG8_STAGE(PG8_SB(1, 1), b3 + hstepB, voffB); PG8_STAGE(PG8_SA(1, 0), a3, voffA);
;             PG8_WAIT_V(8); PG8_WAIT_L(0); PG8_BAR; PG8_MMA(1, 0, At, B0); PG8_MMA(1, 1, At, B1); PG8_BAR; PG8_SCHED;
.LBB0_720:
	s_add_u32 s42, s26, s36
	s_addc_u32 s43, s27, s37
	s_add_u32 s40, s42, 0x100
	s_addc_u32 s41, s43, 0
	s_and_b64 s[38:39], s[34:35], exec
	s_cselect_b32 s39, s19, s41
	s_cselect_b32 s38, s85, s40
	s_add_u32 s36, s24, s36
	s_addc_u32 s37, s25, s37
	s_add_u32 s36, s36, 0x100
	s_addc_u32 s37, s37, 0
	s_add_i32 s48, 0, 0x10000
	s_and_b64 s[34:35], s[34:35], exec
	s_cselect_b32 s41, s17, s37
	s_cselect_b32 s40, s91, s36
	s_add_i32 s35, 0, 0x14000
	s_add_u32 s44, s42, 0x10080
	s_addc_u32 s45, s43, 0
	s_add_i32 vcc_hi, s48, s54
	s_add_i32 m0, s55, 0xc000
	s_add_i32 s49, s55, 0xe000
	s_add_i32 s96, vcc_hi, 0x2000
	s_add_u32 s42, s40, 0x10000
	v_add_u32_e32 v150, s48, v1
	v_add_u32_e32 v158, s35, v1
	s_addc_u32 s43, s41, 0
	s_add_i32 vcc_lo, s35, s54
	ds_read_b128 v[130:133], v150
	ds_read_b128 v[134:137], v150 offset:1024
	ds_read_b128 v[146:149], v150 offset:2048
	ds_read_b128 v[150:153], v150 offset:3072
	ds_read_b128 v[154:157], v158
	ds_read_b128 v[160:163], v158 offset:1024
	ds_read_b128 v[164:167], v158 offset:2048
	ds_read_b128 v[168:171], v158 offset:3072
	s_add_i32 s97, vcc_lo, 0x2000
	s_add_i32 s95, 0, 0x18000
	s_add_i32 s94, 0, 0x1c000
	s_add_u32 s36, s38, 0x10000
	s_addc_u32 s37, s39, 0
	s_add_i32 s93, s95, s54
	s_add_i32 s92, s93, 0x2000
	s_add_u32 s34, s40, 0x10080
	s_addc_u32 s35, s41, 0
	s_add_i32 s61, s94, s54
	s_add_i32 s48, s61, 0x2000
	v_lshl_add_u64 v[176:177], s[44:45], 0, v[144:145]
	ds_read_b128 v[172:175], v159
	ds_read_b128 v[180:183], v159 offset:1024
	ds_read_b128 v[184:187], v159 offset:2048
	ds_read_b128 v[188:191], v159 offset:3072
	ds_read_b128 v[192:195], v159 offset:4096
	ds_read_b128 v[196:199], v159 offset:5120
	ds_read_b128 v[200:203], v159 offset:6144
	ds_read_b128 v[204:207], v159 offset:7168
	global_load_lds_dwordx4 v[176:177], off
	v_lshl_add_u64 v[176:177], s[44:45], 0, v[140:141]
	s_mov_b32 m0, s49
	s_nop 0
	global_load_lds_dwordx4 v[176:177], off
	s_waitcnt vmcnt(8)
	s_cmp_lg_u32 s98, 0
	s_cbranch_scc0 .Llk_13
	s_waitcnt lgkmcnt(0)
.Llk_13:
	s_barrier
	s_setprio 1
	s_waitcnt lgkmcnt(0)
	v_mfma_f32_16x16x32_bf16 v[126:129], v[130:133], v[172:175], v[126:129]
	v_mfma_f32_16x16x32_bf16 v[122:125], v[146:149], v[172:175], v[122:125]
	v_mfma_f32_16x16x32_bf16 v[110:113], v[130:133], v[184:187], v[110:113]
	v_mfma_f32_16x16x32_bf16 v[106:109], v[146:149], v[184:187], v[106:109]
	v_mfma_f32_16x16x32_bf16 v[94:97], v[130:133], v[192:195], v[94:97]
	v_mfma_f32_16x16x32_bf16 v[90:93], v[146:149], v[192:195], v[90:93]
	v_mfma_f32_16x16x32_bf16 v[78:81], v[130:133], v[200:203], v[78:81]
	v_mfma_f32_16x16x32_bf16 v[74:77], v[146:149], v[200:203], v[74:77]
	v_mfma_f32_16x16x32_bf16 v[126:129], v[134:137], v[180:183], v[126:129]
	v_mfma_f32_16x16x32_bf16 v[122:125], v[150:153], v[180:183], v[122:125]
	v_mfma_f32_16x16x32_bf16 v[110:113], v[134:137], v[188:191], v[110:113]
	v_mfma_f32_16x16x32_bf16 v[106:109], v[150:153], v[188:191], v[106:109]
	v_mfma_f32_16x16x32_bf16 v[94:97], v[134:137], v[196:199], v[94:97]
	v_mfma_f32_16x16x32_bf16 v[90:93], v[150:153], v[196:199], v[90:93]
	v_mfma_f32_16x16x32_bf16 v[78:81], v[134:137], v[204:207], v[78:81]
	v_mfma_f32_16x16x32_bf16 v[74:77], v[150:153], v[204:207], v[74:77]
	s_setprio 0
	s_setprio 1
	v_mfma_f32_16x16x32_bf16 v[118:121], v[154:157], v[172:175], v[118:121]
	v_mfma_f32_16x16x32_bf16 v[114:117], v[164:167], v[172:175], v[114:117]
	v_mfma_f32_16x16x32_bf16 v[102:105], v[154:157], v[184:187], v[102:105]
	v_mfma_f32_16x16x32_bf16 v[98:101], v[164:167], v[184:187], v[98:101]
	v_mfma_f32_16x16x32_bf16 v[86:89], v[154:157], v[192:195], v[86:89]
	v_mfma_f32_16x16x32_bf16 v[82:85], v[164:167], v[192:195], v[82:85]
	v_mfma_f32_16x16x32_bf16 v[70:73], v[154:157], v[200:203], v[70:73]
	v_mfma_f32_16x16x32_bf16 v[66:69], v[164:167], v[200:203], v[66:69]
	v_mfma_f32_16x16x32_bf16 v[118:121], v[160:163], v[180:183], v[118:121]
	v_mfma_f32_16x16x32_bf16 v[114:117], v[168:171], v[180:183], v[114:117]
	v_mfma_f32_16x16x32_bf16 v[102:105], v[160:163], v[188:191], v[102:105]
	v_mfma_f32_16x16x32_bf16 v[98:101], v[168:171], v[188:191], v[98:101]
	v_mfma_f32_16x16x32_bf16 v[86:89], v[160:163], v[196:199], v[86:89]
	v_mfma_f32_16x16x32_bf16 v[82:85], v[168:171], v[196:199], v[82:85]
	v_mfma_f32_16x16x32_bf16 v[70:73], v[160:163], v[204:207], v[70:73]
	v_mfma_f32_16x16x32_bf16 v[66:69], v[168:171], v[204:207], v[66:69]
	s_setprio 0
	s_barrier
	s_mov_b32 m0, vcc_hi
	v_lshl_add_u64 v[176:177], s[40:41], 0, v[142:143]
	ds_read_b128 v[172:175], v159 offset:16384
	ds_read_b128 v[180:183], v159 offset:17408
	ds_read_b128 v[184:187], v159 offset:18432
	ds_read_b128 v[188:191], v159 offset:19456
	ds_read_b128 v[192:195], v159 offset:20480
	ds_read_b128 v[196:199], v159 offset:21504
	ds_read_b128 v[200:203], v159 offset:22528
	ds_read_b128 v[204:207], v159 offset:23552
	global_load_lds_dwordx4 v[176:177], off
	v_lshl_add_u64 v[210:211], s[40:41], 0, v[138:139]
	s_mov_b32 m0, s96
	v_lshl_add_u64 v[212:213], s[42:43], 0, v[142:143]
	global_load_lds_dwordx4 v[210:211], off
	s_mov_b32 m0, vcc_lo
	v_lshl_add_u64 v[214:215], s[38:39], 0, v[140:141]
	global_load_lds_dwordx4 v[212:213], off
	v_lshl_add_u64 v[212:213], s[42:43], 0, v[138:139]
	s_mov_b32 m0, s97
	s_nop 0
	global_load_lds_dwordx4 v[212:213], off
	v_lshl_add_u64 v[212:213], s[38:39], 0, v[144:145]
	s_mov_b32 m0, s55
	s_nop 0
	global_load_lds_dwordx4 v[212:213], off
	s_mov_b32 m0, s56
	s_nop 0
	global_load_lds_dwordx4 v[214:215], off
	s_waitcnt vmcnt(8)
	s_cmp_lg_u32 s98, 0
	s_cbranch_scc0 .Llk_14
	s_waitcnt lgkmcnt(0)
; #define PG8_STAGE(bufoff, gbase, voff) do { _Pragma("unroll") for (int _i = 0; _i < 2; ++_i) \
;         __builtin_amdgcn_global_load_lds((const unsigned*)((const char*)(gbase) + (voff)[_i]), (PG8_LAS unsigned*)(lds + (bufoff) + ldsw + _i * 8192), 16, 0, 0); } while (0)
; #define PG8_LDA(dst, b, h) do { _Pragma("unroll") for (int m = 0; m < 4; ++m) _Pragma("unroll") for (int k = 0; k < 2; ++k) dst[m][k] = *(const PG8_LAS bf16x8*)(lds + PG8_SA(b, h) + aoff + m * 2048 + k * 1024); } while (0)
; #define PG8_LDB(dst, b, h) do { _Pragma("unroll") for (int n = 0; n < 2; ++n) _Pragma("unroll") for (int k = 0; k < 2; ++k) dst[n][k] = *(const PG8_LAS bf16x8*)(lds + PG8_SB(b, h) + boff + n * 2048 + k * 1024); } while (0)
; #define PG8_MMA(ai, bj, At, Bt) do { __builtin_amdgcn_s_setprio(1); _Pragma("unroll") for (int m = 0; m < 4; ++m) _Pragma("unroll") for (int n = 0; n < 2; ++n) _Pragma("unroll") for (int k = 0; k < 2; ++k) \
;         acc[ai][bj][m][n] = __builtin_amdgcn_mfma_f32_16x16x32_bf16(Bt[n][k], At[m][k], acc[ai][bj][m][n], 0, 0, 0); __builtin_amdgcn_s_setprio(0); } while (0)
; #define PG8_WAIT_V(n) asm volatile("s_waitcnt vmcnt(" #n ")" ::: "memory")
; #define PG8_WAIT_L(n) asm volatile("s_waitcnt lgkmcnt(" #n ")" ::: "memory")
; #define PG8_BAR __builtin_amdgcn_s_barrier()
; #define PG8_SCHED __builtin_amdgcn_sched_barrier(0)
;     ...
;             PG8_LDB(B0, 0, 0); PG8_LDB(B1, 0, 1); PG8_SCHED; PG8_LDA(At, 0, 0); PG8_STAGE(PG8_SA(1, 1), a1 + hstepA, voffA);
;             PG8_WAIT_V(8); PG8_WAIT_L(0); PG8_BAR; PG8_MMA(0, 0, At, B0); PG8_MMA(0, 1, At, B1); PG8_BAR; PG8_SCHED;
;             PG8_LDA(At, 0, 1); PG8_STAGE(PG8_SB(0, 0), b2, voffB); PG8_STAGE(PG8_SB(0, 1), b2 + hstepB, voffB); PG8_STAGE(PG8_SA(0, 0), a2, voffA);
;             PG8_WAIT_V(8); PG8_WAIT_L(0); PG8_BAR; PG8_MMA(1, 0, At, B0); PG8_MMA(1, 1, At, B1); PG8_BAR; PG8_SCHED;
;             PG8_LDB(B0, 1, 0); PG8_LDB(B1, 1, 1); PG8_SCHED; PG8_LDA(At, 1, 0); PG8_STAGE(PG8_SA(0, 1), a2 + hstepA, voffA);
;             PG8_WAIT_V(8); PG8_WAIT_L(0); PG8_BAR; PG8_MMA(0, 0, At, B0); PG8_MMA(0, 1, At, B1); PG8_BAR; PG8_SCHED;
;             PG8_LDA(At, 1, 1); PG8_STAGE(PG8_SB(1, 0), b3, voffB); PG8_STAGE(PG8_SB(1, 1), b3 + hstepB, voffB); PG8_STAGE(PG8_SA(1, 0), a3, voffA);
;             PG8_WAIT_V(8); PG8_WAIT_L(0); PG8_BAR; PG8_MMA(1, 0, At, B0); PG8_MMA(1, 1, At, B1); PG8_BAR; PG8_SCHED;
.Llk_14:
	s_barrier
	s_setprio 1
	s_waitcnt lgkmcnt(0)
	v_mfma_f32_16x16x32_bf16 v[62:65], v[130:133], v[172:175], v[62:65]
	v_mfma_f32_16x16x32_bf16 v[58:61], v[146:149], v[172:175], v[58:61]
	v_mfma_f32_16x16x32_bf16 v[46:49], v[130:133], v[184:187], v[46:49]
	v_mfma_f32_16x16x32_bf16 v[42:45], v[146:149], v[184:187], v[42:45]
	v_mfma_f32_16x16x32_bf16 v[30:33], v[130:133], v[192:195], v[30:33]
	v_mfma_f32_16x16x32_bf16 v[26:29], v[146:149], v[192:195], v[26:29]
	v_mfma_f32_16x16x32_bf16 v[14:17], v[130:133], v[200:203], v[14:17]
	v_mfma_f32_16x16x32_bf16 v[10:13], v[146:149], v[200:203], v[10:13]
	v_mfma_f32_16x16x32_bf16 v[62:65], v[134:137], v[180:183], v[62:65]
	v_mfma_f32_16x16x32_bf16 v[58:61], v[150:153], v[180:183], v[58:61]
	v_mfma_f32_16x16x32_bf16 v[46:49], v[134:137], v[188:191], v[46:49]
	v_mfma_f32_16x16x32_bf16 v[42:45], v[150:153], v[188:191], v[42:45]
	v_mfma_f32_16x16x32_bf16 v[30:33], v[134:137], v[196:199], v[30:33]
	v_mfma_f32_16x16x32_bf16 v[26:29], v[150:153], v[196:199], v[26:29]
	v_mfma_f32_16x16x32_bf16 v[14:17], v[134:137], v[204:207], v[14:17]
	v_mfma_f32_16x16x32_bf16 v[10:13], v[150:153], v[204:207], v[10:13]
	s_setprio 0
	s_setprio 1
	v_mfma_f32_16x16x32_bf16 v[54:57], v[154:157], v[172:175], v[54:57]
	v_mfma_f32_16x16x32_bf16 v[50:53], v[164:167], v[172:175], v[50:53]
	v_mfma_f32_16x16x32_bf16 v[38:41], v[154:157], v[184:187], v[38:41]
	v_mfma_f32_16x16x32_bf16 v[34:37], v[164:167], v[184:187], v[34:37]
	v_mfma_f32_16x16x32_bf16 v[22:25], v[154:157], v[192:195], v[22:25]
	v_mfma_f32_16x16x32_bf16 v[18:21], v[164:167], v[192:195], v[18:21]
	v_mfma_f32_16x16x32_bf16 v[6:9], v[154:157], v[200:203], v[6:9]
	v_mfma_f32_16x16x32_bf16 v[2:5], v[164:167], v[200:203], v[2:5]
	v_mfma_f32_16x16x32_bf16 v[54:57], v[160:163], v[180:183], v[54:57]
	v_mfma_f32_16x16x32_bf16 v[50:53], v[168:171], v[180:183], v[50:53]
	v_mfma_f32_16x16x32_bf16 v[38:41], v[160:163], v[188:191], v[38:41]
	v_mfma_f32_16x16x32_bf16 v[34:37], v[168:171], v[188:191], v[34:37]
	v_mfma_f32_16x16x32_bf16 v[22:25], v[160:163], v[196:199], v[22:25]
	v_mfma_f32_16x16x32_bf16 v[18:21], v[168:171], v[196:199], v[18:21]
	v_mfma_f32_16x16x32_bf16 v[6:9], v[160:163], v[204:207], v[6:9]
	v_mfma_f32_16x16x32_bf16 v[2:5], v[168:171], v[204:207], v[2:5]
	s_setprio 0
	s_barrier
	v_add_u32_e32 v150, s95, v1
	v_add_u32_e32 v158, s94, v1
	ds_read_b128 v[130:133], v150
	ds_read_b128 v[134:137], v150 offset:1024
	ds_read_b128 v[146:149], v150 offset:2048
	ds_read_b128 v[150:153], v150 offset:3072
	ds_read_b128 v[154:157], v158
	ds_read_b128 v[160:163], v158 offset:1024
	ds_read_b128 v[164:167], v158 offset:2048
	ds_read_b128 v[168:171], v158 offset:3072
	s_mov_b32 m0, s57
	v_lshl_add_u64 v[216:217], s[36:37], 0, v[144:145]
	ds_read_b128 v[172:175], v159 offset:32768
	ds_read_b128 v[180:183], v159 offset:33792
	ds_read_b128 v[184:187], v159 offset:34816
	ds_read_b128 v[188:191], v159 offset:35840
	ds_read_b128 v[192:195], v159 offset:36864
	ds_read_b128 v[196:199], v159 offset:37888
	ds_read_b128 v[200:203], v159 offset:38912
	ds_read_b128 v[204:207], v159 offset:39936
	global_load_lds_dwordx4 v[216:217], off
	v_lshl_add_u64 v[216:217], s[36:37], 0, v[140:141]
	s_mov_b32 m0, s58
	s_nop 0
	global_load_lds_dwordx4 v[216:217], off
	s_waitcnt vmcnt(8)
	s_cmp_lg_u32 s98, 0
	s_cbranch_scc0 .Llk_15
	s_waitcnt lgkmcnt(0)
; #define PG8_STAGE(bufoff, gbase, voff) do { _Pragma("unroll") for (int _i = 0; _i < 2; ++_i) \
;         __builtin_amdgcn_global_load_lds((const unsigned*)((const char*)(gbase) + (voff)[_i]), (PG8_LAS unsigned*)(lds + (bufoff) + ldsw + _i * 8192), 16, 0, 0); } while (0)
; #define PG8_LDA(dst, b, h) do { _Pragma("unroll") for (int m = 0; m < 4; ++m) _Pragma("unroll") for (int k = 0; k < 2; ++k) dst[m][k] = *(const PG8_LAS bf16x8*)(lds + PG8_SA(b, h) + aoff + m * 2048 + k * 1024); } while (0)
; #define PG8_LDB(dst, b, h) do { _Pragma("unroll") for (int n = 0; n < 2; ++n) _Pragma("unroll") for (int k = 0; k < 2; ++k) dst[n][k] = *(const PG8_LAS bf16x8*)(lds + PG8_SB(b, h) + boff + n * 2048 + k * 1024); } while (0)
; #define PG8_WAIT_V(n) asm volatile("s_waitcnt vmcnt(" #n ")" ::: "memory")
; #define PG8_WAIT_L(n) asm volatile("s_waitcnt lgkmcnt(" #n ")" ::: "memory")
; #define PG8_BAR __builtin_amdgcn_s_barrier()
;     ...
;         for (int t = 0; t < nt; t += 2) {
;             const bool last = (t == nt - 2);
;             const char* a1 = cA + (size_t)(t + 1) * kstep;
;             const char* a2 = last ? nA : cA + (size_t)(t + 2) * kstep; const char* b2 = last ? nB : cB + (size_t)(t + 2) * kstep;
;             const char* a3 = a2 + kstep; const char* b3 = b2 + kstep;
;             if (last && has_next) S.a_ready(nxt);
;     ...
;             PG8_LDB(B0, 0, 0); PG8_LDB(B1, 0, 1); PG8_SCHED; PG8_LDA(At, 0, 0); PG8_STAGE(PG8_SA(1, 1), a1 + hstepA, voffA);
;             PG8_WAIT_V(8); PG8_WAIT_L(0); PG8_BAR; PG8_MMA(0, 0, At, B0); PG8_MMA(0, 1, At, B1); PG8_BAR; PG8_SCHED;
;             PG8_LDA(At, 0, 1); PG8_STAGE(PG8_SB(0, 0), b2, voffB); PG8_STAGE(PG8_SB(0, 1), b2 + hstepB, voffB); PG8_STAGE(PG8_SA(0, 0), a2, voffA);
;             PG8_WAIT_V(8); PG8_WAIT_L(0); PG8_BAR; PG8_MMA(1, 0, At, B0); PG8_MMA(1, 1, At, B1); PG8_BAR; PG8_SCHED;
;             PG8_LDB(B0, 1, 0); PG8_LDB(B1, 1, 1); PG8_SCHED; PG8_LDA(At, 1, 0); PG8_STAGE(PG8_SA(0, 1), a2 + hstepA, voffA);
;             PG8_WAIT_V(8); PG8_WAIT_L(0); PG8_BAR; PG8_MMA(0, 0, At, B0); PG8_MMA(0, 1, At, B1); PG8_BAR; PG8_SCHED;
;             PG8_LDA(At, 1, 1); PG8_STAGE(PG8_SB(1, 0), b3, voffB); PG8_STAGE(PG8_SB(1, 1), b3 + hstepB, voffB); PG8_STAGE(PG8_SA(1, 0), a3, voffA);
;             PG8_WAIT_V(8); PG8_WAIT_L(0); PG8_BAR; PG8_MMA(1, 0, At, B0); PG8_MMA(1, 1, At, B1); PG8_BAR; PG8_SCHED;
.Llk_15:
	s_barrier
	s_setprio 1
	s_waitcnt lgkmcnt(0)
	v_mfma_f32_16x16x32_bf16 v[126:129], v[130:133], v[172:175], v[126:129]
	v_mfma_f32_16x16x32_bf16 v[122:125], v[146:149], v[172:175], v[122:125]
	v_mfma_f32_16x16x32_bf16 v[110:113], v[130:133], v[184:187], v[110:113]
	v_mfma_f32_16x16x32_bf16 v[106:109], v[146:149], v[184:187], v[106:109]
	v_mfma_f32_16x16x32_bf16 v[94:97], v[130:133], v[192:195], v[94:97]
	v_mfma_f32_16x16x32_bf16 v[90:93], v[146:149], v[192:195], v[90:93]
	v_mfma_f32_16x16x32_bf16 v[78:81], v[130:133], v[200:203], v[78:81]
	v_mfma_f32_16x16x32_bf16 v[74:77], v[146:149], v[200:203], v[74:77]
	v_mfma_f32_16x16x32_bf16 v[126:129], v[134:137], v[180:183], v[126:129]
	v_mfma_f32_16x16x32_bf16 v[122:125], v[150:153], v[180:183], v[122:125]
	v_mfma_f32_16x16x32_bf16 v[110:113], v[134:137], v[188:191], v[110:113]
	v_mfma_f32_16x16x32_bf16 v[106:109], v[150:153], v[188:191], v[106:109]
	v_mfma_f32_16x16x32_bf16 v[94:97], v[134:137], v[196:199], v[94:97]
	v_mfma_f32_16x16x32_bf16 v[90:93], v[150:153], v[196:199], v[90:93]
	v_mfma_f32_16x16x32_bf16 v[78:81], v[134:137], v[204:207], v[78:81]
	v_mfma_f32_16x16x32_bf16 v[74:77], v[150:153], v[204:207], v[74:77]
	s_setprio 0
	s_setprio 1
	v_mfma_f32_16x16x32_bf16 v[118:121], v[154:157], v[172:175], v[118:121]
	v_mfma_f32_16x16x32_bf16 v[114:117], v[164:167], v[172:175], v[114:117]
	v_mfma_f32_16x16x32_bf16 v[102:105], v[154:157], v[184:187], v[102:105]
	v_mfma_f32_16x16x32_bf16 v[98:101], v[164:167], v[184:187], v[98:101]
	v_mfma_f32_16x16x32_bf16 v[86:89], v[154:157], v[192:195], v[86:89]
	v_mfma_f32_16x16x32_bf16 v[82:85], v[164:167], v[192:195], v[82:85]
	v_mfma_f32_16x16x32_bf16 v[70:73], v[154:157], v[200:203], v[70:73]
	v_mfma_f32_16x16x32_bf16 v[66:69], v[164:167], v[200:203], v[66:69]
	v_mfma_f32_16x16x32_bf16 v[118:121], v[160:163], v[180:183], v[118:121]
	v_mfma_f32_16x16x32_bf16 v[114:117], v[168:171], v[180:183], v[114:117]
	v_mfma_f32_16x16x32_bf16 v[102:105], v[160:163], v[188:191], v[102:105]
	v_mfma_f32_16x16x32_bf16 v[98:101], v[168:171], v[188:191], v[98:101]
	v_mfma_f32_16x16x32_bf16 v[86:89], v[160:163], v[196:199], v[86:89]
	v_mfma_f32_16x16x32_bf16 v[82:85], v[168:171], v[196:199], v[82:85]
	v_mfma_f32_16x16x32_bf16 v[70:73], v[160:163], v[204:207], v[70:73]
	v_mfma_f32_16x16x32_bf16 v[66:69], v[168:171], v[204:207], v[66:69]
	s_setprio 0
	s_barrier
	s_mov_b32 m0, s93
	v_lshl_add_u64 v[176:177], v[176:177], 0, s[66:67]
	ds_read_b128 v[172:175], v159 offset:49152
	ds_read_b128 v[180:183], v159 offset:50176
	ds_read_b128 v[184:187], v159 offset:51200
	ds_read_b128 v[188:191], v159 offset:52224
	ds_read_b128 v[192:195], v159 offset:53248
	ds_read_b128 v[196:199], v159 offset:54272
	ds_read_b128 v[200:203], v159 offset:55296
	ds_read_b128 v[204:207], v159 offset:56320
	global_load_lds_dwordx4 v[176:177], off
	v_lshl_add_u64 v[176:177], v[210:211], 0, s[66:67]
	s_mov_b32 m0, s92
	s_nop 0
	global_load_lds_dwordx4 v[176:177], off
	v_lshl_add_u64 v[176:177], s[34:35], 0, v[142:143]
	s_mov_b32 m0, s61
	s_nop 0
	global_load_lds_dwordx4 v[176:177], off
	v_lshl_add_u64 v[176:177], s[34:35], 0, v[138:139]
	s_mov_b32 m0, s48
	s_nop 0
	global_load_lds_dwordx4 v[176:177], off
	v_lshl_add_u64 v[176:177], v[212:213], 0, s[66:67]
	s_mov_b32 m0, s87
	s_nop 0
	global_load_lds_dwordx4 v[176:177], off
	v_lshl_add_u64 v[176:177], v[214:215], 0, s[66:67]
	s_mov_b32 m0, s88
	s_nop 0
	global_load_lds_dwordx4 v[176:177], off
	s_waitcnt vmcnt(8)
	s_cmp_lg_u32 s98, 0
	s_cbranch_scc0 .Llk_16
	s_waitcnt lgkmcnt(0)
.Llk_16:
	s_barrier
	s_setprio 1
	s_waitcnt lgkmcnt(0)
	v_mfma_f32_16x16x32_bf16 v[62:65], v[130:133], v[172:175], v[62:65]
	v_mfma_f32_16x16x32_bf16 v[58:61], v[146:149], v[172:175], v[58:61]
	v_mfma_f32_16x16x32_bf16 v[46:49], v[130:133], v[184:187], v[46:49]
	v_mfma_f32_16x16x32_bf16 v[42:45], v[146:149], v[184:187], v[42:45]
	v_mfma_f32_16x16x32_bf16 v[30:33], v[130:133], v[192:195], v[30:33]
	v_mfma_f32_16x16x32_bf16 v[26:29], v[146:149], v[192:195], v[26:29]
	v_mfma_f32_16x16x32_bf16 v[14:17], v[130:133], v[200:203], v[14:17]
	v_mfma_f32_16x16x32_bf16 v[10:13], v[146:149], v[200:203], v[10:13]
	v_mfma_f32_16x16x32_bf16 v[62:65], v[134:137], v[180:183], v[62:65]
	v_mfma_f32_16x16x32_bf16 v[58:61], v[150:153], v[180:183], v[58:61]
	v_mfma_f32_16x16x32_bf16 v[46:49], v[134:137], v[188:191], v[46:49]
	v_mfma_f32_16x16x32_bf16 v[42:45], v[150:153], v[188:191], v[42:45]
	v_mfma_f32_16x16x32_bf16 v[30:33], v[134:137], v[196:199], v[30:33]
	v_mfma_f32_16x16x32_bf16 v[26:29], v[150:153], v[196:199], v[26:29]
	v_mfma_f32_16x16x32_bf16 v[14:17], v[134:137], v[204:207], v[14:17]
	v_mfma_f32_16x16x32_bf16 v[10:13], v[150:153], v[204:207], v[10:13]
	s_setprio 0
	s_setprio 1
	v_mfma_f32_16x16x32_bf16 v[54:57], v[154:157], v[172:175], v[54:57]
	v_mfma_f32_16x16x32_bf16 v[50:53], v[164:167], v[172:175], v[50:53]
	v_mfma_f32_16x16x32_bf16 v[38:41], v[154:157], v[184:187], v[38:41]
	v_mfma_f32_16x16x32_bf16 v[34:37], v[164:167], v[184:187], v[34:37]
	v_mfma_f32_16x16x32_bf16 v[22:25], v[154:157], v[192:195], v[22:25]
	v_mfma_f32_16x16x32_bf16 v[18:21], v[164:167], v[192:195], v[18:21]
	v_mfma_f32_16x16x32_bf16 v[6:9], v[154:157], v[200:203], v[6:9]
	v_mfma_f32_16x16x32_bf16 v[2:5], v[164:167], v[200:203], v[2:5]
	v_mfma_f32_16x16x32_bf16 v[54:57], v[160:163], v[180:183], v[54:57]
	v_mfma_f32_16x16x32_bf16 v[50:53], v[168:171], v[180:183], v[50:53]
	v_mfma_f32_16x16x32_bf16 v[38:41], v[160:163], v[188:191], v[38:41]
	v_mfma_f32_16x16x32_bf16 v[34:37], v[168:171], v[188:191], v[34:37]
	v_mfma_f32_16x16x32_bf16 v[22:25], v[160:163], v[196:199], v[22:25]
	v_mfma_f32_16x16x32_bf16 v[18:21], v[168:171], v[196:199], v[18:21]
	v_mfma_f32_16x16x32_bf16 v[6:9], v[160:163], v[204:207], v[6:9]
	v_mfma_f32_16x16x32_bf16 v[2:5], v[168:171], v[204:207], v[2:5]
	s_setprio 0
	s_barrier
	s_andn2_b64 vcc, exec, s[28:29]
	s_mov_b64 s[34:35], -1
	s_mov_b64 s[28:29], 0
	s_mov_b64 s[36:37], 0x100
	s_cbranch_vccz .LBB0_720
	s_and_b64 vcc, exec, s[14:15]
	s_cbranch_vccz .LBB0_723
	s_barrier

; #define PG8_STAGE(bufoff, gbase, voff) do { _Pragma("unroll") for (int _i = 0; _i < 2; ++_i) \
;         __builtin_amdgcn_global_load_lds((const unsigned*)((const char*)(gbase) + (voff)[_i]), (PG8_LAS unsigned*)(lds + (bufoff) + ldsw + _i * 8192), 16, 0, 0); } while (0)
; #define PG8_LDA(dst, b, h) do { _Pragma("unroll") for (int m = 0; m < 4; ++m) _Pragma("unroll") for (int k = 0; k < 2; ++k) dst[m][k] = *(const PG8_LAS bf16x8*)(lds + PG8_SA(b, h) + aoff + m * 2048 + k * 1024); } while (0)
; #define PG8_LDB(dst, b, h) do { _Pragma("unroll") for (int n = 0; n < 2; ++n) _Pragma("unroll") for (int k = 0; k < 2; ++k) dst[n][k] = *(const PG8_LAS bf16x8*)(lds + PG8_SB(b, h) + boff + n * 2048 + k * 1024); } while (0)
; #define PG8_WAIT_V(n) asm volatile("s_waitcnt vmcnt(" #n ")" ::: "memory")
; #define PG8_WAIT_L(n) asm volatile("s_waitcnt lgkmcnt(" #n ")" ::: "memory")
; #define PG8_BAR __builtin_amdgcn_s_barrier()
;     ...
;         for (int t = 0; t < nt; t += 2) {
;             const bool last = (t == nt - 2);
;             const char* a1 = cA + (size_t)(t + 1) * kstep;
;             const char* a2 = last ? nA : cA + (size_t)(t + 2) * kstep; const char* b2 = last ? nB : cB + (size_t)(t + 2) * kstep;
;             const char* a3 = a2 + kstep; const char* b3 = b2 + kstep;
;             if (last && has_next) S.a_ready(nxt);
;             if constexpr (SP2) {
;             PG8_LDB(B0, 0, 0); PG8_LDB(B1, 0, 1); PG8_SCHED; PG8_LDA(At, 0, 0); PG8_STAGE(PG8_SA(1, 1), a1 + hstepA, voffA);
;             PG8_WAIT_V(8); PG8_WAIT_L(0); PG8_BAR; PG8_MMA(0, 0, At, B0); PG8_MMA(0, 1, At, B1); PG8_BAR; PG8_SCHED;
;             PG8_LDA(At, 0, 1); PG8_STAGE(PG8_SB(0, 0), b2, voffB); PG8_STAGE(PG8_SB(0, 1), b2 + hstepB, voffB); PG8_STAGE(PG8_SA(0, 0), a2, voffA);
;             PG8_WAIT_V(8); PG8_WAIT_L(0); PG8_BAR; PG8_MMA(1, 0, At, B0); PG8_MMA(1, 1, At, B1); PG8_BAR; PG8_SCHED;
;             PG8_LDB(B0, 1, 0); PG8_LDB(B1, 1, 1); PG8_SCHED; PG8_LDA(At, 1, 0); PG8_STAGE(PG8_SA(0, 1), a2 + hstepA, voffA);
;             PG8_WAIT_V(8); PG8_WAIT_L(0); PG8_BAR; PG8_MMA(0, 0, At, B0); PG8_MMA(0, 1, At, B1); PG8_BAR; PG8_SCHED;
;             PG8_LDA(At, 1, 1); PG8_STAGE(PG8_SB(1, 0), b3, voffB); PG8_STAGE(PG8_SB(1, 1), b3 + hstepB, voffB); PG8_STAGE(PG8_SA(1, 0), a3, voffA);
;             PG8_WAIT_V(8); PG8_WAIT_L(0); PG8_BAR; PG8_MMA(1, 0, At, B0); PG8_MMA(1, 1, At, B1); PG8_BAR; PG8_SCHED;
.LBB0_963:
	s_add_u32 s28, s6, 0xfffe0080
	s_addc_u32 s29, s7, -1
	s_add_i32 s48, 0, 0x10000
	s_cmp_eq_u32 s81, 4
	s_cselect_b32 s35, s57, s29
	s_cselect_b32 s34, s77, s28
	s_cselect_b32 s29, s55, s80
	s_cselect_b32 s28, s78, s79
	s_add_i32 s82, 0, 0x14000
	v_add_u32_e32 v92, s48, v234
	v_add_u32_e32 v132, s82, v234
	ds_read_b128 v[64:67], v92
	ds_read_b128 v[68:71], v92 offset:1024
	ds_read_b128 v[80:83], v92 offset:2048
	ds_read_b128 v[92:95], v92 offset:3072
	ds_read_b128 v[104:107], v132
	ds_read_b128 v[108:111], v132 offset:1024
	ds_read_b128 v[120:123], v132 offset:2048
	ds_read_b128 v[132:135], v132 offset:3072
	v_lshl_add_u64 v[208:209], s[6:7], 0, v[204:205]
	s_add_i32 m0, s66, 0xc000
	ds_read_b128 v[152:155], v235
	ds_read_b128 v[164:167], v235 offset:1024
	ds_read_b128 v[168:171], v235 offset:2048
	ds_read_b128 v[172:175], v235 offset:3072
	ds_read_b128 v[176:179], v235 offset:4096
	ds_read_b128 v[180:183], v235 offset:5120
	ds_read_b128 v[184:187], v235 offset:6144
	ds_read_b128 v[188:191], v235 offset:7168
	global_load_lds_dwordx4 v[208:209], off
	v_lshl_add_u64 v[208:209], s[6:7], 0, v[206:207]
	s_add_i32 m0, s66, 0xe000
	s_nop 0
	global_load_lds_dwordx4 v[208:209], off
	s_waitcnt vmcnt(8)
	s_cmp_lg_u32 s98, 0
	s_cbranch_scc0 .Llk_17
	s_waitcnt lgkmcnt(0)
.Llk_17:
	s_barrier
	s_setprio 1
	s_waitcnt lgkmcnt(0)
	v_mfma_f32_16x16x32_bf16 v[160:163], v[64:67], v[152:155], v[160:163]
	v_mfma_f32_16x16x32_bf16 v[156:159], v[80:83], v[152:155], v[156:159]
	v_mfma_f32_16x16x32_bf16 v[140:143], v[64:67], v[168:171], v[140:143]
	v_mfma_f32_16x16x32_bf16 v[136:139], v[80:83], v[168:171], v[136:139]
	v_mfma_f32_16x16x32_bf16 v[116:119], v[64:67], v[176:179], v[116:119]
	v_mfma_f32_16x16x32_bf16 v[112:115], v[80:83], v[176:179], v[112:115]
	v_mfma_f32_16x16x32_bf16 v[88:91], v[64:67], v[184:187], v[88:91]
	v_mfma_f32_16x16x32_bf16 v[84:87], v[80:83], v[184:187], v[84:87]
	v_mfma_f32_16x16x32_bf16 v[160:163], v[68:71], v[164:167], v[160:163]
	v_mfma_f32_16x16x32_bf16 v[156:159], v[92:95], v[164:167], v[156:159]
	v_mfma_f32_16x16x32_bf16 v[140:143], v[68:71], v[172:175], v[140:143]
	v_mfma_f32_16x16x32_bf16 v[136:139], v[92:95], v[172:175], v[136:139]
	v_mfma_f32_16x16x32_bf16 v[116:119], v[68:71], v[180:183], v[116:119]
	v_mfma_f32_16x16x32_bf16 v[112:115], v[92:95], v[180:183], v[112:115]
	v_mfma_f32_16x16x32_bf16 v[88:91], v[68:71], v[188:191], v[88:91]
	v_mfma_f32_16x16x32_bf16 v[84:87], v[92:95], v[188:191], v[84:87]
	s_setprio 0
	s_setprio 1
	v_mfma_f32_16x16x32_bf16 v[148:151], v[104:107], v[152:155], v[148:151]
	v_mfma_f32_16x16x32_bf16 v[144:147], v[120:123], v[152:155], v[144:147]
	v_mfma_f32_16x16x32_bf16 v[128:131], v[104:107], v[168:171], v[128:131]
	v_mfma_f32_16x16x32_bf16 v[124:127], v[120:123], v[168:171], v[124:127]
	v_mfma_f32_16x16x32_bf16 v[100:103], v[104:107], v[176:179], v[100:103]
	v_mfma_f32_16x16x32_bf16 v[96:99], v[120:123], v[176:179], v[96:99]
	v_mfma_f32_16x16x32_bf16 v[76:79], v[104:107], v[184:187], v[76:79]
	v_mfma_f32_16x16x32_bf16 v[72:75], v[120:123], v[184:187], v[72:75]
	v_mfma_f32_16x16x32_bf16 v[148:151], v[108:111], v[164:167], v[148:151]
	v_mfma_f32_16x16x32_bf16 v[144:147], v[132:135], v[164:167], v[144:147]
	v_mfma_f32_16x16x32_bf16 v[128:131], v[108:111], v[172:175], v[128:131]
	v_mfma_f32_16x16x32_bf16 v[124:127], v[132:135], v[172:175], v[124:127]
	v_mfma_f32_16x16x32_bf16 v[100:103], v[108:111], v[180:183], v[100:103]
	v_mfma_f32_16x16x32_bf16 v[96:99], v[132:135], v[180:183], v[96:99]
	v_mfma_f32_16x16x32_bf16 v[76:79], v[108:111], v[188:191], v[76:79]
	v_mfma_f32_16x16x32_bf16 v[72:75], v[132:135], v[188:191], v[72:75]
	s_setprio 0
	s_barrier
	s_add_i32 s48, s48, s65
	v_lshl_add_u64 v[208:209], s[28:29], 0, v[192:193]
	s_mov_b32 m0, s48
	ds_read_b128 v[152:155], v235 offset:16384
	ds_read_b128 v[164:167], v235 offset:17408
	ds_read_b128 v[168:171], v235 offset:18432
	ds_read_b128 v[172:175], v235 offset:19456
	ds_read_b128 v[176:179], v235 offset:20480
	ds_read_b128 v[180:183], v235 offset:21504
	ds_read_b128 v[184:187], v235 offset:22528
	ds_read_b128 v[188:191], v235 offset:23552
	global_load_lds_dwordx4 v[208:209], off
	s_add_i32 m0, s48, 0x2000
	s_add_u32 s48, s28, 0x20000
	v_lshl_add_u64 v[210:211], s[28:29], 0, v[198:199]
	s_addc_u32 s49, s29, 0
	s_add_i32 s82, s82, s65
	global_load_lds_dwordx4 v[210:211], off
	v_lshl_add_u64 v[212:213], s[48:49], 0, v[192:193]
	s_mov_b32 m0, s82
	v_lshl_add_u64 v[214:215], s[34:35], 0, v[200:201]
	global_load_lds_dwordx4 v[212:213], off
	v_lshl_add_u64 v[212:213], s[48:49], 0, v[198:199]
	s_add_i32 m0, s82, 0x2000
	s_nop 0
	global_load_lds_dwordx4 v[212:213], off
	v_lshl_add_u64 v[212:213], s[34:35], 0, v[202:203]
	s_mov_b32 m0, s66
	s_nop 0
	global_load_lds_dwordx4 v[212:213], off
	s_mov_b32 m0, s67
	s_nop 0
	global_load_lds_dwordx4 v[214:215], off
	s_waitcnt vmcnt(8)
	s_cmp_lg_u32 s98, 0
	s_cbranch_scc0 .Llk_18
	s_waitcnt lgkmcnt(0)
; #define PG8_STAGE(bufoff, gbase, voff) do { _Pragma("unroll") for (int _i = 0; _i < 2; ++_i) \
;         __builtin_amdgcn_global_load_lds((const unsigned*)((const char*)(gbase) + (voff)[_i]), (PG8_LAS unsigned*)(lds + (bufoff) + ldsw + _i * 8192), 16, 0, 0); } while (0)
; #define PG8_LDA(dst, b, h) do { _Pragma("unroll") for (int m = 0; m < 4; ++m) _Pragma("unroll") for (int k = 0; k < 2; ++k) dst[m][k] = *(const PG8_LAS bf16x8*)(lds + PG8_SA(b, h) + aoff + m * 2048 + k * 1024); } while (0)
; #define PG8_LDB(dst, b, h) do { _Pragma("unroll") for (int n = 0; n < 2; ++n) _Pragma("unroll") for (int k = 0; k < 2; ++k) dst[n][k] = *(const PG8_LAS bf16x8*)(lds + PG8_SB(b, h) + boff + n * 2048 + k * 1024); } while (0)
; #define PG8_MMA(ai, bj, At, Bt) do { __builtin_amdgcn_s_setprio(1); _Pragma("unroll") for (int m = 0; m < 4; ++m) _Pragma("unroll") for (int n = 0; n < 2; ++n) _Pragma("unroll") for (int k = 0; k < 2; ++k) \
;         acc[ai][bj][m][n] = __builtin_amdgcn_mfma_f32_16x16x32_bf16(Bt[n][k], At[m][k], acc[ai][bj][m][n], 0, 0, 0); __builtin_amdgcn_s_setprio(0); } while (0)
; #define PG8_WAIT_V(n) asm volatile("s_waitcnt vmcnt(" #n ")" ::: "memory")
; #define PG8_WAIT_L(n) asm volatile("s_waitcnt lgkmcnt(" #n ")" ::: "memory")
; #define PG8_BAR __builtin_amdgcn_s_barrier()
; #define PG8_SCHED __builtin_amdgcn_sched_barrier(0)
;     ...
;             PG8_LDB(B0, 0, 0); PG8_LDB(B1, 0, 1); PG8_SCHED; PG8_LDA(At, 0, 0); PG8_STAGE(PG8_SA(1, 1), a1 + hstepA, voffA);
;             PG8_WAIT_V(8); PG8_WAIT_L(0); PG8_BAR; PG8_MMA(0, 0, At, B0); PG8_MMA(0, 1, At, B1); PG8_BAR; PG8_SCHED;
;             PG8_LDA(At, 0, 1); PG8_STAGE(PG8_SB(0, 0), b2, voffB); PG8_STAGE(PG8_SB(0, 1), b2 + hstepB, voffB); PG8_STAGE(PG8_SA(0, 0), a2, voffA);
;             PG8_WAIT_V(8); PG8_WAIT_L(0); PG8_BAR; PG8_MMA(1, 0, At, B0); PG8_MMA(1, 1, At, B1); PG8_BAR; PG8_SCHED;
;             PG8_LDB(B0, 1, 0); PG8_LDB(B1, 1, 1); PG8_SCHED; PG8_LDA(At, 1, 0); PG8_STAGE(PG8_SA(0, 1), a2 + hstepA, voffA);
;             PG8_WAIT_V(8); PG8_WAIT_L(0); PG8_BAR; PG8_MMA(0, 0, At, B0); PG8_MMA(0, 1, At, B1); PG8_BAR; PG8_SCHED;
;             PG8_LDA(At, 1, 1); PG8_STAGE(PG8_SB(1, 0), b3, voffB); PG8_STAGE(PG8_SB(1, 1), b3 + hstepB, voffB); PG8_STAGE(PG8_SA(1, 0), a3, voffA);
;             PG8_WAIT_V(8); PG8_WAIT_L(0); PG8_BAR; PG8_MMA(1, 0, At, B0); PG8_MMA(1, 1, At, B1); PG8_BAR; PG8_SCHED;
.Llk_18:
	s_barrier
	s_setprio 1
	s_waitcnt lgkmcnt(0)
	v_mfma_f32_16x16x32_bf16 v[60:63], v[64:67], v[152:155], v[60:63]
	v_mfma_f32_16x16x32_bf16 v[56:59], v[80:83], v[152:155], v[56:59]
	v_mfma_f32_16x16x32_bf16 v[44:47], v[64:67], v[168:171], v[44:47]
	v_mfma_f32_16x16x32_bf16 v[40:43], v[80:83], v[168:171], v[40:43]
	v_mfma_f32_16x16x32_bf16 v[28:31], v[64:67], v[176:179], v[28:31]
	v_mfma_f32_16x16x32_bf16 v[24:27], v[80:83], v[176:179], v[24:27]
	v_mfma_f32_16x16x32_bf16 v[12:15], v[64:67], v[184:187], v[12:15]
	v_mfma_f32_16x16x32_bf16 v[8:11], v[80:83], v[184:187], v[8:11]
	v_mfma_f32_16x16x32_bf16 v[60:63], v[68:71], v[164:167], v[60:63]
	v_mfma_f32_16x16x32_bf16 v[56:59], v[92:95], v[164:167], v[56:59]
	v_mfma_f32_16x16x32_bf16 v[44:47], v[68:71], v[172:175], v[44:47]
	v_mfma_f32_16x16x32_bf16 v[40:43], v[92:95], v[172:175], v[40:43]
	v_mfma_f32_16x16x32_bf16 v[28:31], v[68:71], v[180:183], v[28:31]
	v_mfma_f32_16x16x32_bf16 v[24:27], v[92:95], v[180:183], v[24:27]
	v_mfma_f32_16x16x32_bf16 v[12:15], v[68:71], v[188:191], v[12:15]
	v_mfma_f32_16x16x32_bf16 v[8:11], v[92:95], v[188:191], v[8:11]
	s_setprio 0
	s_setprio 1
	v_mfma_f32_16x16x32_bf16 v[52:55], v[104:107], v[152:155], v[52:55]
	v_mfma_f32_16x16x32_bf16 v[48:51], v[120:123], v[152:155], v[48:51]
	v_mfma_f32_16x16x32_bf16 v[36:39], v[104:107], v[168:171], v[36:39]
	v_mfma_f32_16x16x32_bf16 v[32:35], v[120:123], v[168:171], v[32:35]
	v_mfma_f32_16x16x32_bf16 v[20:23], v[104:107], v[176:179], v[20:23]
	v_mfma_f32_16x16x32_bf16 v[16:19], v[120:123], v[176:179], v[16:19]
	v_mfma_f32_16x16x32_bf16 v[4:7], v[104:107], v[184:187], v[4:7]
	v_mfma_f32_16x16x32_bf16 v[0:3], v[120:123], v[184:187], v[0:3]
	v_mfma_f32_16x16x32_bf16 v[52:55], v[108:111], v[164:167], v[52:55]
	v_mfma_f32_16x16x32_bf16 v[48:51], v[132:135], v[164:167], v[48:51]
	v_mfma_f32_16x16x32_bf16 v[36:39], v[108:111], v[172:175], v[36:39]
	v_mfma_f32_16x16x32_bf16 v[32:35], v[132:135], v[172:175], v[32:35]
	v_mfma_f32_16x16x32_bf16 v[20:23], v[108:111], v[180:183], v[20:23]
	v_mfma_f32_16x16x32_bf16 v[16:19], v[132:135], v[180:183], v[16:19]
	v_mfma_f32_16x16x32_bf16 v[4:7], v[108:111], v[188:191], v[4:7]
	v_mfma_f32_16x16x32_bf16 v[0:3], v[132:135], v[188:191], v[0:3]
	s_setprio 0
	s_barrier
	s_add_i32 s48, 0, 0x18000
	s_add_i32 s49, 0, 0x1c000
	v_add_u32_e32 v92, s48, v234
	v_add_u32_e32 v132, s49, v234
	ds_read_b128 v[64:67], v92
	ds_read_b128 v[68:71], v92 offset:1024
	ds_read_b128 v[80:83], v92 offset:2048
	ds_read_b128 v[92:95], v92 offset:3072
	ds_read_b128 v[104:107], v132
	ds_read_b128 v[108:111], v132 offset:1024
	ds_read_b128 v[120:123], v132 offset:2048
	ds_read_b128 v[132:135], v132 offset:3072
	s_add_u32 s34, s34, 0x20000
	s_addc_u32 s35, s35, 0
	s_mov_b32 m0, s68
	v_lshl_add_u64 v[216:217], s[34:35], 0, v[202:203]
	ds_read_b128 v[152:155], v235 offset:32768
	ds_read_b128 v[164:167], v235 offset:33792
	ds_read_b128 v[168:171], v235 offset:34816
	ds_read_b128 v[172:175], v235 offset:35840
	ds_read_b128 v[176:179], v235 offset:36864
	ds_read_b128 v[180:183], v235 offset:37888
	ds_read_b128 v[184:187], v235 offset:38912
	ds_read_b128 v[188:191], v235 offset:39936
	global_load_lds_dwordx4 v[216:217], off
	v_lshl_add_u64 v[216:217], s[34:35], 0, v[200:201]
	s_mov_b32 m0, s69
	s_nop 0
	global_load_lds_dwordx4 v[216:217], off
	s_waitcnt vmcnt(8)
	s_cmp_lg_u32 s98, 0
	s_cbranch_scc0 .Llk_19
	s_waitcnt lgkmcnt(0)
; #define PG8_STAGE(bufoff, gbase, voff) do { _Pragma("unroll") for (int _i = 0; _i < 2; ++_i) \
;         __builtin_amdgcn_global_load_lds((const unsigned*)((const char*)(gbase) + (voff)[_i]), (PG8_LAS unsigned*)(lds + (bufoff) + ldsw + _i * 8192), 16, 0, 0); } while (0)
; #define PG8_LDA(dst, b, h) do { _Pragma("unroll") for (int m = 0; m < 4; ++m) _Pragma("unroll") for (int k = 0; k < 2; ++k) dst[m][k] = *(const PG8_LAS bf16x8*)(lds + PG8_SA(b, h) + aoff + m * 2048 + k * 1024); } while (0)
; #define PG8_LDB(dst, b, h) do { _Pragma("unroll") for (int n = 0; n < 2; ++n) _Pragma("unroll") for (int k = 0; k < 2; ++k) dst[n][k] = *(const PG8_LAS bf16x8*)(lds + PG8_SB(b, h) + boff + n * 2048 + k * 1024); } while (0)
; #define PG8_WAIT_V(n) asm volatile("s_waitcnt vmcnt(" #n ")" ::: "memory")
; #define PG8_WAIT_L(n) asm volatile("s_waitcnt lgkmcnt(" #n ")" ::: "memory")
; #define PG8_BAR __builtin_amdgcn_s_barrier()
;     ...
;         for (int t = 0; t < nt; t += 2) {
;             const bool last = (t == nt - 2);
;             const char* a1 = cA + (size_t)(t + 1) * kstep;
;             const char* a2 = last ? nA : cA + (size_t)(t + 2) * kstep; const char* b2 = last ? nB : cB + (size_t)(t + 2) * kstep;
;             const char* a3 = a2 + kstep; const char* b3 = b2 + kstep;
;             if (last && has_next) S.a_ready(nxt);
;     ...
;             PG8_LDB(B0, 0, 0); PG8_LDB(B1, 0, 1); PG8_SCHED; PG8_LDA(At, 0, 0); PG8_STAGE(PG8_SA(1, 1), a1 + hstepA, voffA);
;             PG8_WAIT_V(8); PG8_WAIT_L(0); PG8_BAR; PG8_MMA(0, 0, At, B0); PG8_MMA(0, 1, At, B1); PG8_BAR; PG8_SCHED;
;             PG8_LDA(At, 0, 1); PG8_STAGE(PG8_SB(0, 0), b2, voffB); PG8_STAGE(PG8_SB(0, 1), b2 + hstepB, voffB); PG8_STAGE(PG8_SA(0, 0), a2, voffA);
;             PG8_WAIT_V(8); PG8_WAIT_L(0); PG8_BAR; PG8_MMA(1, 0, At, B0); PG8_MMA(1, 1, At, B1); PG8_BAR; PG8_SCHED;
;             PG8_LDB(B0, 1, 0); PG8_LDB(B1, 1, 1); PG8_SCHED; PG8_LDA(At, 1, 0); PG8_STAGE(PG8_SA(0, 1), a2 + hstepA, voffA);
;             PG8_WAIT_V(8); PG8_WAIT_L(0); PG8_BAR; PG8_MMA(0, 0, At, B0); PG8_MMA(0, 1, At, B1); PG8_BAR; PG8_SCHED;
;             PG8_LDA(At, 1, 1); PG8_STAGE(PG8_SB(1, 0), b3, voffB); PG8_STAGE(PG8_SB(1, 1), b3 + hstepB, voffB); PG8_STAGE(PG8_SA(1, 0), a3, voffA);
;             PG8_WAIT_V(8); PG8_WAIT_L(0); PG8_BAR; PG8_MMA(1, 0, At, B0); PG8_MMA(1, 1, At, B1); PG8_BAR; PG8_SCHED;
.Llk_19:
	s_barrier
	s_setprio 1
	s_waitcnt lgkmcnt(0)
	v_mfma_f32_16x16x32_bf16 v[160:163], v[64:67], v[152:155], v[160:163]
	v_mfma_f32_16x16x32_bf16 v[156:159], v[80:83], v[152:155], v[156:159]
	v_mfma_f32_16x16x32_bf16 v[140:143], v[64:67], v[168:171], v[140:143]
	v_mfma_f32_16x16x32_bf16 v[136:139], v[80:83], v[168:171], v[136:139]
	v_mfma_f32_16x16x32_bf16 v[116:119], v[64:67], v[176:179], v[116:119]
	v_mfma_f32_16x16x32_bf16 v[112:115], v[80:83], v[176:179], v[112:115]
	v_mfma_f32_16x16x32_bf16 v[88:91], v[64:67], v[184:187], v[88:91]
	v_mfma_f32_16x16x32_bf16 v[84:87], v[80:83], v[184:187], v[84:87]
	v_mfma_f32_16x16x32_bf16 v[160:163], v[68:71], v[164:167], v[160:163]
	v_mfma_f32_16x16x32_bf16 v[156:159], v[92:95], v[164:167], v[156:159]
	v_mfma_f32_16x16x32_bf16 v[140:143], v[68:71], v[172:175], v[140:143]
	v_mfma_f32_16x16x32_bf16 v[136:139], v[92:95], v[172:175], v[136:139]
	v_mfma_f32_16x16x32_bf16 v[116:119], v[68:71], v[180:183], v[116:119]
	v_mfma_f32_16x16x32_bf16 v[112:115], v[92:95], v[180:183], v[112:115]
	v_mfma_f32_16x16x32_bf16 v[88:91], v[68:71], v[188:191], v[88:91]
	v_mfma_f32_16x16x32_bf16 v[84:87], v[92:95], v[188:191], v[84:87]
	s_setprio 0
	s_setprio 1
	v_mfma_f32_16x16x32_bf16 v[148:151], v[104:107], v[152:155], v[148:151]
	v_mfma_f32_16x16x32_bf16 v[144:147], v[120:123], v[152:155], v[144:147]
	v_mfma_f32_16x16x32_bf16 v[128:131], v[104:107], v[168:171], v[128:131]
	v_mfma_f32_16x16x32_bf16 v[124:127], v[120:123], v[168:171], v[124:127]
	v_mfma_f32_16x16x32_bf16 v[100:103], v[104:107], v[176:179], v[100:103]
	v_mfma_f32_16x16x32_bf16 v[96:99], v[120:123], v[176:179], v[96:99]
	v_mfma_f32_16x16x32_bf16 v[76:79], v[104:107], v[184:187], v[76:79]
	v_mfma_f32_16x16x32_bf16 v[72:75], v[120:123], v[184:187], v[72:75]
	v_mfma_f32_16x16x32_bf16 v[148:151], v[108:111], v[164:167], v[148:151]
	v_mfma_f32_16x16x32_bf16 v[144:147], v[132:135], v[164:167], v[144:147]
	v_mfma_f32_16x16x32_bf16 v[128:131], v[108:111], v[172:175], v[128:131]
	v_mfma_f32_16x16x32_bf16 v[124:127], v[132:135], v[172:175], v[124:127]
	v_mfma_f32_16x16x32_bf16 v[100:103], v[108:111], v[180:183], v[100:103]
	v_mfma_f32_16x16x32_bf16 v[96:99], v[132:135], v[180:183], v[96:99]
	v_mfma_f32_16x16x32_bf16 v[76:79], v[108:111], v[188:191], v[76:79]
	v_mfma_f32_16x16x32_bf16 v[72:75], v[132:135], v[188:191], v[72:75]
	s_setprio 0
	s_barrier
	s_add_i32 s34, s48, s65
	v_lshl_add_u64 v[208:209], v[208:209], 0, s[22:23]
	s_mov_b32 m0, s34
	ds_read_b128 v[152:155], v235 offset:49152
	ds_read_b128 v[164:167], v235 offset:50176
	ds_read_b128 v[168:171], v235 offset:51200
	ds_read_b128 v[172:175], v235 offset:52224
	ds_read_b128 v[176:179], v235 offset:53248
	ds_read_b128 v[180:183], v235 offset:54272
	ds_read_b128 v[184:187], v235 offset:55296
	ds_read_b128 v[188:191], v235 offset:56320
	global_load_lds_dwordx4 v[208:209], off
	s_add_i32 m0, s34, 0x2000
	s_add_u32 s28, s28, 0x20080
	v_lshl_add_u64 v[208:209], v[210:211], 0, s[22:23]
	s_addc_u32 s29, s29, 0
	s_add_i32 s34, s49, s65
	global_load_lds_dwordx4 v[208:209], off
	v_lshl_add_u64 v[208:209], s[28:29], 0, v[192:193]
	s_mov_b32 m0, s34
	s_nop 0
	global_load_lds_dwordx4 v[208:209], off
	v_lshl_add_u64 v[208:209], s[28:29], 0, v[198:199]
	s_add_i32 m0, s34, 0x2000
	s_nop 0
	global_load_lds_dwordx4 v[208:209], off
	v_lshl_add_u64 v[208:209], v[212:213], 0, s[22:23]
	s_mov_b32 m0, s72
	s_nop 0
	global_load_lds_dwordx4 v[208:209], off
	v_lshl_add_u64 v[208:209], v[214:215], 0, s[22:23]
	s_mov_b32 m0, s73
	s_nop 0
	global_load_lds_dwordx4 v[208:209], off
	s_waitcnt vmcnt(8)
	s_cmp_lg_u32 s98, 0
	s_cbranch_scc0 .Llk_20
	s_waitcnt lgkmcnt(0)
.Llk_20:
	s_barrier
	s_setprio 1
	s_waitcnt lgkmcnt(0)
	v_mfma_f32_16x16x32_bf16 v[60:63], v[64:67], v[152:155], v[60:63]
	v_mfma_f32_16x16x32_bf16 v[56:59], v[80:83], v[152:155], v[56:59]
	v_mfma_f32_16x16x32_bf16 v[44:47], v[64:67], v[168:171], v[44:47]
	v_mfma_f32_16x16x32_bf16 v[40:43], v[80:83], v[168:171], v[40:43]
	v_mfma_f32_16x16x32_bf16 v[28:31], v[64:67], v[176:179], v[28:31]
	v_mfma_f32_16x16x32_bf16 v[24:27], v[80:83], v[176:179], v[24:27]
	v_mfma_f32_16x16x32_bf16 v[12:15], v[64:67], v[184:187], v[12:15]
	v_mfma_f32_16x16x32_bf16 v[8:11], v[80:83], v[184:187], v[8:11]
	v_mfma_f32_16x16x32_bf16 v[60:63], v[68:71], v[164:167], v[60:63]
	v_mfma_f32_16x16x32_bf16 v[56:59], v[92:95], v[164:167], v[56:59]
	v_mfma_f32_16x16x32_bf16 v[44:47], v[68:71], v[172:175], v[44:47]
	v_mfma_f32_16x16x32_bf16 v[40:43], v[92:95], v[172:175], v[40:43]
	v_mfma_f32_16x16x32_bf16 v[28:31], v[68:71], v[180:183], v[28:31]
	v_mfma_f32_16x16x32_bf16 v[24:27], v[92:95], v[180:183], v[24:27]
	v_mfma_f32_16x16x32_bf16 v[12:15], v[68:71], v[188:191], v[12:15]
	v_mfma_f32_16x16x32_bf16 v[8:11], v[92:95], v[188:191], v[8:11]
	s_setprio 0
	s_setprio 1
	v_mfma_f32_16x16x32_bf16 v[52:55], v[104:107], v[152:155], v[52:55]
	v_mfma_f32_16x16x32_bf16 v[48:51], v[120:123], v[152:155], v[48:51]
	v_mfma_f32_16x16x32_bf16 v[36:39], v[104:107], v[168:171], v[36:39]
	v_mfma_f32_16x16x32_bf16 v[32:35], v[120:123], v[168:171], v[32:35]
	v_mfma_f32_16x16x32_bf16 v[20:23], v[104:107], v[176:179], v[20:23]
	v_mfma_f32_16x16x32_bf16 v[16:19], v[120:123], v[176:179], v[16:19]
	v_mfma_f32_16x16x32_bf16 v[4:7], v[104:107], v[184:187], v[4:7]
	v_mfma_f32_16x16x32_bf16 v[0:3], v[120:123], v[184:187], v[0:3]
	v_mfma_f32_16x16x32_bf16 v[52:55], v[108:111], v[164:167], v[52:55]
	v_mfma_f32_16x16x32_bf16 v[48:51], v[132:135], v[164:167], v[48:51]
	v_mfma_f32_16x16x32_bf16 v[36:39], v[108:111], v[172:175], v[36:39]
	v_mfma_f32_16x16x32_bf16 v[32:35], v[132:135], v[172:175], v[32:35]
	v_mfma_f32_16x16x32_bf16 v[20:23], v[108:111], v[180:183], v[20:23]
	v_mfma_f32_16x16x32_bf16 v[16:19], v[132:135], v[180:183], v[16:19]
	v_mfma_f32_16x16x32_bf16 v[4:7], v[108:111], v[188:191], v[4:7]
	v_mfma_f32_16x16x32_bf16 v[0:3], v[132:135], v[188:191], v[0:3]
	s_setprio 0
	s_barrier
	s_add_i32 s81, s81, 2
	s_add_u32 s6, s6, 0x100
	s_addc_u32 s7, s7, 0
	s_add_u32 s79, s79, 0x100
	s_addc_u32 s80, s80, 0
	s_cmp_gt_u32 s81, 5
	s_cbranch_scc0 .LBB0_963
	s_and_b64 vcc, exec, s[38:39]
	s_cbranch_vccz .LBB0_966
	s_barrier

; #define PG8_STAGE(bufoff, gbase, voff) do { _Pragma("unroll") for (int _i = 0; _i < 2; ++_i) \
;         __builtin_amdgcn_global_load_lds((const unsigned*)((const char*)(gbase) + (voff)[_i]), (PG8_LAS unsigned*)(lds + (bufoff) + ldsw + _i * 8192), 16, 0, 0); } while (0)
; #define PG8_LDA(dst, b, h) do { _Pragma("unroll") for (int m = 0; m < 4; ++m) _Pragma("unroll") for (int k = 0; k < 2; ++k) dst[m][k] = *(const PG8_LAS bf16x8*)(lds + PG8_SA(b, h) + aoff + m * 2048 + k * 1024); } while (0)
; #define PG8_LDB(dst, b, h) do { _Pragma("unroll") for (int n = 0; n < 2; ++n) _Pragma("unroll") for (int k = 0; k < 2; ++k) dst[n][k] = *(const PG8_LAS bf16x8*)(lds + PG8_SB(b, h) + boff + n * 2048 + k * 1024); } while (0)
; #define PG8_WAIT_V(n) asm volatile("s_waitcnt vmcnt(" #n ")" ::: "memory")
; #define PG8_WAIT_L(n) asm volatile("s_waitcnt lgkmcnt(" #n ")" ::: "memory")
; #define PG8_BAR __builtin_amdgcn_s_barrier()
;     ...
;         for (int t = 0; t < nt; t += 2) {
;             const bool last = (t == nt - 2);
;             const char* a1 = cA + (size_t)(t + 1) * kstep;
;             const char* a2 = last ? nA : cA + (size_t)(t + 2) * kstep; const char* b2 = last ? nB : cB + (size_t)(t + 2) * kstep;
;             const char* a3 = a2 + kstep; const char* b3 = b2 + kstep;
;             if (last && has_next) S.a_ready(nxt);
;             if constexpr (SP2) {
;             PG8_LDB(B0, 0, 0); PG8_LDB(B1, 0, 1); PG8_SCHED; PG8_LDA(At, 0, 0); PG8_STAGE(PG8_SA(1, 1), a1 + hstepA, voffA);
;             PG8_WAIT_V(8); PG8_WAIT_L(0); PG8_BAR; PG8_MMA(0, 0, At, B0); PG8_MMA(0, 1, At, B1); PG8_BAR; PG8_SCHED;
;             PG8_LDA(At, 0, 1); PG8_STAGE(PG8_SB(0, 0), b2, voffB); PG8_STAGE(PG8_SB(0, 1), b2 + hstepB, voffB); PG8_STAGE(PG8_SA(0, 0), a2, voffA);
;             PG8_WAIT_V(8); PG8_WAIT_L(0); PG8_BAR; PG8_MMA(1, 0, At, B0); PG8_MMA(1, 1, At, B1); PG8_BAR; PG8_SCHED;
;             PG8_LDB(B0, 1, 0); PG8_LDB(B1, 1, 1); PG8_SCHED; PG8_LDA(At, 1, 0); PG8_STAGE(PG8_SA(0, 1), a2 + hstepA, voffA);
;             PG8_WAIT_V(8); PG8_WAIT_L(0); PG8_BAR; PG8_MMA(0, 0, At, B0); PG8_MMA(0, 1, At, B1); PG8_BAR; PG8_SCHED;
;             PG8_LDA(At, 1, 1); PG8_STAGE(PG8_SB(1, 0), b3, voffB); PG8_STAGE(PG8_SB(1, 1), b3 + hstepB, voffB); PG8_STAGE(PG8_SA(1, 0), a3, voffA);
;             PG8_WAIT_V(8); PG8_WAIT_L(0); PG8_BAR; PG8_MMA(1, 0, At, B0); PG8_MMA(1, 1, At, B1); PG8_BAR; PG8_SCHED;
.LBB0_1083:
	s_add_u32 s6, s28, 0x100
	s_addc_u32 s7, s29, 0
	s_add_i32 s48, 0, 0x10000
	s_cmp_eq_u32 s76, 12
	s_cselect_b32 s41, s53, s7
	s_cselect_b32 s40, s52, s6
	s_cselect_b32 s35, s51, s75
	s_cselect_b32 s34, s73, s74
	s_add_i32 s49, 0, 0x14000
	v_add_u32_e32 v92, s48, v234
	v_add_u32_e32 v132, s49, v234
	ds_read_b128 v[64:67], v92
	ds_read_b128 v[68:71], v92 offset:1024
	ds_read_b128 v[80:83], v92 offset:2048
	ds_read_b128 v[92:95], v92 offset:3072
	ds_read_b128 v[104:107], v132
	ds_read_b128 v[108:111], v132 offset:1024
	ds_read_b128 v[120:123], v132 offset:2048
	ds_read_b128 v[132:135], v132 offset:3072
	v_lshl_add_u64 v[208:209], s[28:29], 0, v[204:205]
	s_add_i32 m0, s61, 0xc000
	ds_read_b128 v[152:155], v235
	ds_read_b128 v[164:167], v235 offset:1024
	ds_read_b128 v[168:171], v235 offset:2048
	ds_read_b128 v[172:175], v235 offset:3072
	ds_read_b128 v[176:179], v235 offset:4096
	ds_read_b128 v[180:183], v235 offset:5120
	ds_read_b128 v[184:187], v235 offset:6144
	ds_read_b128 v[188:191], v235 offset:7168
	global_load_lds_dwordx4 v[208:209], off
	v_lshl_add_u64 v[208:209], s[28:29], 0, v[206:207]
	s_add_i32 m0, s61, 0xe000
	s_nop 0
	global_load_lds_dwordx4 v[208:209], off
	s_waitcnt vmcnt(8)
	s_cmp_lg_u32 s98, 0
	s_cbranch_scc0 .Llk_21
	s_waitcnt lgkmcnt(0)
.Llk_21:
	s_barrier
	s_setprio 1
	s_waitcnt lgkmcnt(0)
	v_mfma_f32_16x16x32_bf16 v[160:163], v[64:67], v[152:155], v[160:163]
	v_mfma_f32_16x16x32_bf16 v[156:159], v[80:83], v[152:155], v[156:159]
	v_mfma_f32_16x16x32_bf16 v[140:143], v[64:67], v[168:171], v[140:143]
	v_mfma_f32_16x16x32_bf16 v[136:139], v[80:83], v[168:171], v[136:139]
	v_mfma_f32_16x16x32_bf16 v[116:119], v[64:67], v[176:179], v[116:119]
	v_mfma_f32_16x16x32_bf16 v[112:115], v[80:83], v[176:179], v[112:115]
	v_mfma_f32_16x16x32_bf16 v[88:91], v[64:67], v[184:187], v[88:91]
	v_mfma_f32_16x16x32_bf16 v[84:87], v[80:83], v[184:187], v[84:87]
	v_mfma_f32_16x16x32_bf16 v[160:163], v[68:71], v[164:167], v[160:163]
	v_mfma_f32_16x16x32_bf16 v[156:159], v[92:95], v[164:167], v[156:159]
	v_mfma_f32_16x16x32_bf16 v[140:143], v[68:71], v[172:175], v[140:143]
	v_mfma_f32_16x16x32_bf16 v[136:139], v[92:95], v[172:175], v[136:139]
	v_mfma_f32_16x16x32_bf16 v[116:119], v[68:71], v[180:183], v[116:119]
	v_mfma_f32_16x16x32_bf16 v[112:115], v[92:95], v[180:183], v[112:115]
	v_mfma_f32_16x16x32_bf16 v[88:91], v[68:71], v[188:191], v[88:91]
	v_mfma_f32_16x16x32_bf16 v[84:87], v[92:95], v[188:191], v[84:87]
	s_setprio 0
	s_setprio 1
	v_mfma_f32_16x16x32_bf16 v[148:151], v[104:107], v[152:155], v[148:151]
	v_mfma_f32_16x16x32_bf16 v[144:147], v[120:123], v[152:155], v[144:147]
	v_mfma_f32_16x16x32_bf16 v[128:131], v[104:107], v[168:171], v[128:131]
	v_mfma_f32_16x16x32_bf16 v[124:127], v[120:123], v[168:171], v[124:127]
	v_mfma_f32_16x16x32_bf16 v[100:103], v[104:107], v[176:179], v[100:103]
	v_mfma_f32_16x16x32_bf16 v[96:99], v[120:123], v[176:179], v[96:99]
	v_mfma_f32_16x16x32_bf16 v[76:79], v[104:107], v[184:187], v[76:79]
	v_mfma_f32_16x16x32_bf16 v[72:75], v[120:123], v[184:187], v[72:75]
	v_mfma_f32_16x16x32_bf16 v[148:151], v[108:111], v[164:167], v[148:151]
	v_mfma_f32_16x16x32_bf16 v[144:147], v[132:135], v[164:167], v[144:147]
	v_mfma_f32_16x16x32_bf16 v[128:131], v[108:111], v[172:175], v[128:131]
	v_mfma_f32_16x16x32_bf16 v[124:127], v[132:135], v[172:175], v[124:127]
	v_mfma_f32_16x16x32_bf16 v[100:103], v[108:111], v[180:183], v[100:103]
	v_mfma_f32_16x16x32_bf16 v[96:99], v[132:135], v[180:183], v[96:99]
	v_mfma_f32_16x16x32_bf16 v[76:79], v[108:111], v[188:191], v[76:79]
	v_mfma_f32_16x16x32_bf16 v[72:75], v[132:135], v[188:191], v[72:75]
	s_setprio 0
	s_barrier
	s_add_i32 s28, s48, s58
	v_lshl_add_u64 v[208:209], s[34:35], 0, v[192:193]
	s_mov_b32 m0, s28
	ds_read_b128 v[152:155], v235 offset:16384
	ds_read_b128 v[164:167], v235 offset:17408
	ds_read_b128 v[168:171], v235 offset:18432
	ds_read_b128 v[172:175], v235 offset:19456
	ds_read_b128 v[176:179], v235 offset:20480
	ds_read_b128 v[180:183], v235 offset:21504
	ds_read_b128 v[184:187], v235 offset:22528
	ds_read_b128 v[188:191], v235 offset:23552
	global_load_lds_dwordx4 v[208:209], off
	s_add_i32 m0, s28, 0x2000
	s_add_u32 s28, s34, 0x40000
	v_lshl_add_u64 v[210:211], s[34:35], 0, v[198:199]
	s_addc_u32 s29, s35, 0
	s_add_i32 s48, s49, s58
	global_load_lds_dwordx4 v[210:211], off
	v_lshl_add_u64 v[212:213], s[28:29], 0, v[192:193]
	s_mov_b32 m0, s48
	v_lshl_add_u64 v[214:215], s[40:41], 0, v[200:201]
	global_load_lds_dwordx4 v[212:213], off
	v_lshl_add_u64 v[212:213], s[28:29], 0, v[198:199]
	s_add_i32 m0, s48, 0x2000
	s_nop 0
	global_load_lds_dwordx4 v[212:213], off
	v_lshl_add_u64 v[212:213], s[40:41], 0, v[202:203]
	s_mov_b32 m0, s61
	s_nop 0
	global_load_lds_dwordx4 v[212:213], off
	s_mov_b32 m0, s62
	s_nop 0
	global_load_lds_dwordx4 v[214:215], off
	s_waitcnt vmcnt(8)
	s_cmp_lg_u32 s98, 0
	s_cbranch_scc0 .Llk_22
	s_waitcnt lgkmcnt(0)
; #define PG8_STAGE(bufoff, gbase, voff) do { _Pragma("unroll") for (int _i = 0; _i < 2; ++_i) \
;         __builtin_amdgcn_global_load_lds((const unsigned*)((const char*)(gbase) + (voff)[_i]), (PG8_LAS unsigned*)(lds + (bufoff) + ldsw + _i * 8192), 16, 0, 0); } while (0)
; #define PG8_LDA(dst, b, h) do { _Pragma("unroll") for (int m = 0; m < 4; ++m) _Pragma("unroll") for (int k = 0; k < 2; ++k) dst[m][k] = *(const PG8_LAS bf16x8*)(lds + PG8_SA(b, h) + aoff + m * 2048 + k * 1024); } while (0)
; #define PG8_LDB(dst, b, h) do { _Pragma("unroll") for (int n = 0; n < 2; ++n) _Pragma("unroll") for (int k = 0; k < 2; ++k) dst[n][k] = *(const PG8_LAS bf16x8*)(lds + PG8_SB(b, h) + boff + n * 2048 + k * 1024); } while (0)
; #define PG8_MMA(ai, bj, At, Bt) do { __builtin_amdgcn_s_setprio(1); _Pragma("unroll") for (int m = 0; m < 4; ++m) _Pragma("unroll") for (int n = 0; n < 2; ++n) _Pragma("unroll") for (int k = 0; k < 2; ++k) \
;         acc[ai][bj][m][n] = __builtin_amdgcn_mfma_f32_16x16x32_bf16(Bt[n][k], At[m][k], acc[ai][bj][m][n], 0, 0, 0); __builtin_amdgcn_s_setprio(0); } while (0)
; #define PG8_WAIT_V(n) asm volatile("s_waitcnt vmcnt(" #n ")" ::: "memory")
; #define PG8_WAIT_L(n) asm volatile("s_waitcnt lgkmcnt(" #n ")" ::: "memory")
; #define PG8_BAR __builtin_amdgcn_s_barrier()
; #define PG8_SCHED __builtin_amdgcn_sched_barrier(0)
;     ...
;             PG8_LDB(B0, 0, 0); PG8_LDB(B1, 0, 1); PG8_SCHED; PG8_LDA(At, 0, 0); PG8_STAGE(PG8_SA(1, 1), a1 + hstepA, voffA);
;             PG8_WAIT_V(8); PG8_WAIT_L(0); PG8_BAR; PG8_MMA(0, 0, At, B0); PG8_MMA(0, 1, At, B1); PG8_BAR; PG8_SCHED;
;             PG8_LDA(At, 0, 1); PG8_STAGE(PG8_SB(0, 0), b2, voffB); PG8_STAGE(PG8_SB(0, 1), b2 + hstepB, voffB); PG8_STAGE(PG8_SA(0, 0), a2, voffA);
;             PG8_WAIT_V(8); PG8_WAIT_L(0); PG8_BAR; PG8_MMA(1, 0, At, B0); PG8_MMA(1, 1, At, B1); PG8_BAR; PG8_SCHED;
;             PG8_LDB(B0, 1, 0); PG8_LDB(B1, 1, 1); PG8_SCHED; PG8_LDA(At, 1, 0); PG8_STAGE(PG8_SA(0, 1), a2 + hstepA, voffA);
;             PG8_WAIT_V(8); PG8_WAIT_L(0); PG8_BAR; PG8_MMA(0, 0, At, B0); PG8_MMA(0, 1, At, B1); PG8_BAR; PG8_SCHED;
;             PG8_LDA(At, 1, 1); PG8_STAGE(PG8_SB(1, 0), b3, voffB); PG8_STAGE(PG8_SB(1, 1), b3 + hstepB, voffB); PG8_STAGE(PG8_SA(1, 0), a3, voffA);
;             PG8_WAIT_V(8); PG8_WAIT_L(0); PG8_BAR; PG8_MMA(1, 0, At, B0); PG8_MMA(1, 1, At, B1); PG8_BAR; PG8_SCHED;
.Llk_22:
	s_barrier
	s_setprio 1
	s_waitcnt lgkmcnt(0)
	v_mfma_f32_16x16x32_bf16 v[60:63], v[64:67], v[152:155], v[60:63]
	v_mfma_f32_16x16x32_bf16 v[56:59], v[80:83], v[152:155], v[56:59]
	v_mfma_f32_16x16x32_bf16 v[44:47], v[64:67], v[168:171], v[44:47]
	v_mfma_f32_16x16x32_bf16 v[40:43], v[80:83], v[168:171], v[40:43]
	v_mfma_f32_16x16x32_bf16 v[28:31], v[64:67], v[176:179], v[28:31]
	v_mfma_f32_16x16x32_bf16 v[24:27], v[80:83], v[176:179], v[24:27]
	v_mfma_f32_16x16x32_bf16 v[12:15], v[64:67], v[184:187], v[12:15]
	v_mfma_f32_16x16x32_bf16 v[8:11], v[80:83], v[184:187], v[8:11]
	v_mfma_f32_16x16x32_bf16 v[60:63], v[68:71], v[164:167], v[60:63]
	v_mfma_f32_16x16x32_bf16 v[56:59], v[92:95], v[164:167], v[56:59]
	v_mfma_f32_16x16x32_bf16 v[44:47], v[68:71], v[172:175], v[44:47]
	v_mfma_f32_16x16x32_bf16 v[40:43], v[92:95], v[172:175], v[40:43]
	v_mfma_f32_16x16x32_bf16 v[28:31], v[68:71], v[180:183], v[28:31]
	v_mfma_f32_16x16x32_bf16 v[24:27], v[92:95], v[180:183], v[24:27]
	v_mfma_f32_16x16x32_bf16 v[12:15], v[68:71], v[188:191], v[12:15]
	v_mfma_f32_16x16x32_bf16 v[8:11], v[92:95], v[188:191], v[8:11]
	s_setprio 0
	s_setprio 1
	v_mfma_f32_16x16x32_bf16 v[52:55], v[104:107], v[152:155], v[52:55]
	v_mfma_f32_16x16x32_bf16 v[48:51], v[120:123], v[152:155], v[48:51]
	v_mfma_f32_16x16x32_bf16 v[36:39], v[104:107], v[168:171], v[36:39]
	v_mfma_f32_16x16x32_bf16 v[32:35], v[120:123], v[168:171], v[32:35]
	v_mfma_f32_16x16x32_bf16 v[20:23], v[104:107], v[176:179], v[20:23]
	v_mfma_f32_16x16x32_bf16 v[16:19], v[120:123], v[176:179], v[16:19]
	v_mfma_f32_16x16x32_bf16 v[4:7], v[104:107], v[184:187], v[4:7]
	v_mfma_f32_16x16x32_bf16 v[0:3], v[120:123], v[184:187], v[0:3]
	v_mfma_f32_16x16x32_bf16 v[52:55], v[108:111], v[164:167], v[52:55]
	v_mfma_f32_16x16x32_bf16 v[48:51], v[132:135], v[164:167], v[48:51]
	v_mfma_f32_16x16x32_bf16 v[36:39], v[108:111], v[172:175], v[36:39]
	v_mfma_f32_16x16x32_bf16 v[32:35], v[132:135], v[172:175], v[32:35]
	v_mfma_f32_16x16x32_bf16 v[20:23], v[108:111], v[180:183], v[20:23]
	v_mfma_f32_16x16x32_bf16 v[16:19], v[132:135], v[180:183], v[16:19]
	v_mfma_f32_16x16x32_bf16 v[4:7], v[108:111], v[188:191], v[4:7]
	v_mfma_f32_16x16x32_bf16 v[0:3], v[132:135], v[188:191], v[0:3]
	s_setprio 0
	s_barrier
	s_add_i32 s48, 0, 0x18000
	s_add_i32 s49, 0, 0x1c000
	v_add_u32_e32 v92, s48, v234
	v_add_u32_e32 v132, s49, v234
	ds_read_b128 v[64:67], v92
	ds_read_b128 v[68:71], v92 offset:1024
	ds_read_b128 v[80:83], v92 offset:2048
	ds_read_b128 v[92:95], v92 offset:3072
	ds_read_b128 v[104:107], v132
	ds_read_b128 v[108:111], v132 offset:1024
	ds_read_b128 v[120:123], v132 offset:2048
	ds_read_b128 v[132:135], v132 offset:3072
	s_add_u32 s28, s40, 0x60000
	s_addc_u32 s29, s41, 0
	s_mov_b32 m0, s63
	v_lshl_add_u64 v[216:217], s[28:29], 0, v[202:203]
	ds_read_b128 v[152:155], v235 offset:32768
	ds_read_b128 v[164:167], v235 offset:33792
	ds_read_b128 v[168:171], v235 offset:34816
	ds_read_b128 v[172:175], v235 offset:35840
	ds_read_b128 v[176:179], v235 offset:36864
	ds_read_b128 v[180:183], v235 offset:37888
	ds_read_b128 v[184:187], v235 offset:38912
	ds_read_b128 v[188:191], v235 offset:39936
	global_load_lds_dwordx4 v[216:217], off
	v_lshl_add_u64 v[216:217], s[28:29], 0, v[200:201]
	s_mov_b32 m0, s64
	s_nop 0
	global_load_lds_dwordx4 v[216:217], off
	s_waitcnt vmcnt(8)
	s_cmp_lg_u32 s98, 0
	s_cbranch_scc0 .Llk_23
	s_waitcnt lgkmcnt(0)
; #define PG8_STAGE(bufoff, gbase, voff) do { _Pragma("unroll") for (int _i = 0; _i < 2; ++_i) \
;         __builtin_amdgcn_global_load_lds((const unsigned*)((const char*)(gbase) + (voff)[_i]), (PG8_LAS unsigned*)(lds + (bufoff) + ldsw + _i * 8192), 16, 0, 0); } while (0)
; #define PG8_LDA(dst, b, h) do { _Pragma("unroll") for (int m = 0; m < 4; ++m) _Pragma("unroll") for (int k = 0; k < 2; ++k) dst[m][k] = *(const PG8_LAS bf16x8*)(lds + PG8_SA(b, h) + aoff + m * 2048 + k * 1024); } while (0)
; #define PG8_LDB(dst, b, h) do { _Pragma("unroll") for (int n = 0; n < 2; ++n) _Pragma("unroll") for (int k = 0; k < 2; ++k) dst[n][k] = *(const PG8_LAS bf16x8*)(lds + PG8_SB(b, h) + boff + n * 2048 + k * 1024); } while (0)
; #define PG8_WAIT_V(n) asm volatile("s_waitcnt vmcnt(" #n ")" ::: "memory")
; #define PG8_WAIT_L(n) asm volatile("s_waitcnt lgkmcnt(" #n ")" ::: "memory")
; #define PG8_BAR __builtin_amdgcn_s_barrier()
;     ...
;         for (int t = 0; t < nt; t += 2) {
;             const bool last = (t == nt - 2);
;             const char* a1 = cA + (size_t)(t + 1) * kstep;
;             const char* a2 = last ? nA : cA + (size_t)(t + 2) * kstep; const char* b2 = last ? nB : cB + (size_t)(t + 2) * kstep;
;             const char* a3 = a2 + kstep; const char* b3 = b2 + kstep;
;             if (last && has_next) S.a_ready(nxt);
;     ...
;             PG8_LDB(B0, 0, 0); PG8_LDB(B1, 0, 1); PG8_SCHED; PG8_LDA(At, 0, 0); PG8_STAGE(PG8_SA(1, 1), a1 + hstepA, voffA);
;             PG8_WAIT_V(8); PG8_WAIT_L(0); PG8_BAR; PG8_MMA(0, 0, At, B0); PG8_MMA(0, 1, At, B1); PG8_BAR; PG8_SCHED;
;             PG8_LDA(At, 0, 1); PG8_STAGE(PG8_SB(0, 0), b2, voffB); PG8_STAGE(PG8_SB(0, 1), b2 + hstepB, voffB); PG8_STAGE(PG8_SA(0, 0), a2, voffA);
;             PG8_WAIT_V(8); PG8_WAIT_L(0); PG8_BAR; PG8_MMA(1, 0, At, B0); PG8_MMA(1, 1, At, B1); PG8_BAR; PG8_SCHED;
;             PG8_LDB(B0, 1, 0); PG8_LDB(B1, 1, 1); PG8_SCHED; PG8_LDA(At, 1, 0); PG8_STAGE(PG8_SA(0, 1), a2 + hstepA, voffA);
;             PG8_WAIT_V(8); PG8_WAIT_L(0); PG8_BAR; PG8_MMA(0, 0, At, B0); PG8_MMA(0, 1, At, B1); PG8_BAR; PG8_SCHED;
;             PG8_LDA(At, 1, 1); PG8_STAGE(PG8_SB(1, 0), b3, voffB); PG8_STAGE(PG8_SB(1, 1), b3 + hstepB, voffB); PG8_STAGE(PG8_SA(1, 0), a3, voffA);
;             PG8_WAIT_V(8); PG8_WAIT_L(0); PG8_BAR; PG8_MMA(1, 0, At, B0); PG8_MMA(1, 1, At, B1); PG8_BAR; PG8_SCHED;
.Llk_23:
	s_barrier
	s_setprio 1
	s_waitcnt lgkmcnt(0)
	v_mfma_f32_16x16x32_bf16 v[160:163], v[64:67], v[152:155], v[160:163]
	v_mfma_f32_16x16x32_bf16 v[156:159], v[80:83], v[152:155], v[156:159]
	v_mfma_f32_16x16x32_bf16 v[140:143], v[64:67], v[168:171], v[140:143]
	v_mfma_f32_16x16x32_bf16 v[136:139], v[80:83], v[168:171], v[136:139]
	v_mfma_f32_16x16x32_bf16 v[116:119], v[64:67], v[176:179], v[116:119]
	v_mfma_f32_16x16x32_bf16 v[112:115], v[80:83], v[176:179], v[112:115]
	v_mfma_f32_16x16x32_bf16 v[88:91], v[64:67], v[184:187], v[88:91]
	v_mfma_f32_16x16x32_bf16 v[84:87], v[80:83], v[184:187], v[84:87]
	v_mfma_f32_16x16x32_bf16 v[160:163], v[68:71], v[164:167], v[160:163]
	v_mfma_f32_16x16x32_bf16 v[156:159], v[92:95], v[164:167], v[156:159]
	v_mfma_f32_16x16x32_bf16 v[140:143], v[68:71], v[172:175], v[140:143]
	v_mfma_f32_16x16x32_bf16 v[136:139], v[92:95], v[172:175], v[136:139]
	v_mfma_f32_16x16x32_bf16 v[116:119], v[68:71], v[180:183], v[116:119]
	v_mfma_f32_16x16x32_bf16 v[112:115], v[92:95], v[180:183], v[112:115]
	v_mfma_f32_16x16x32_bf16 v[88:91], v[68:71], v[188:191], v[88:91]
	v_mfma_f32_16x16x32_bf16 v[84:87], v[92:95], v[188:191], v[84:87]
	s_setprio 0
	s_setprio 1
	v_mfma_f32_16x16x32_bf16 v[148:151], v[104:107], v[152:155], v[148:151]
	v_mfma_f32_16x16x32_bf16 v[144:147], v[120:123], v[152:155], v[144:147]
	v_mfma_f32_16x16x32_bf16 v[128:131], v[104:107], v[168:171], v[128:131]
	v_mfma_f32_16x16x32_bf16 v[124:127], v[120:123], v[168:171], v[124:127]
	v_mfma_f32_16x16x32_bf16 v[100:103], v[104:107], v[176:179], v[100:103]
	v_mfma_f32_16x16x32_bf16 v[96:99], v[120:123], v[176:179], v[96:99]
	v_mfma_f32_16x16x32_bf16 v[76:79], v[104:107], v[184:187], v[76:79]
	v_mfma_f32_16x16x32_bf16 v[72:75], v[120:123], v[184:187], v[72:75]
	v_mfma_f32_16x16x32_bf16 v[148:151], v[108:111], v[164:167], v[148:151]
	v_mfma_f32_16x16x32_bf16 v[144:147], v[132:135], v[164:167], v[144:147]
	v_mfma_f32_16x16x32_bf16 v[128:131], v[108:111], v[172:175], v[128:131]
	v_mfma_f32_16x16x32_bf16 v[124:127], v[132:135], v[172:175], v[124:127]
	v_mfma_f32_16x16x32_bf16 v[100:103], v[108:111], v[180:183], v[100:103]
	v_mfma_f32_16x16x32_bf16 v[96:99], v[132:135], v[180:183], v[96:99]
	v_mfma_f32_16x16x32_bf16 v[76:79], v[108:111], v[188:191], v[76:79]
	v_mfma_f32_16x16x32_bf16 v[72:75], v[132:135], v[188:191], v[72:75]
	s_setprio 0
	s_barrier
	s_add_i32 s28, s48, s58
	v_lshl_add_u64 v[208:209], v[208:209], 0, s[22:23]
	s_mov_b32 m0, s28
	ds_read_b128 v[152:155], v235 offset:49152
	ds_read_b128 v[164:167], v235 offset:50176
	ds_read_b128 v[168:171], v235 offset:51200
	ds_read_b128 v[172:175], v235 offset:52224
	ds_read_b128 v[176:179], v235 offset:53248
	ds_read_b128 v[180:183], v235 offset:54272
	ds_read_b128 v[184:187], v235 offset:55296
	ds_read_b128 v[188:191], v235 offset:56320
	global_load_lds_dwordx4 v[208:209], off
	s_add_i32 m0, s28, 0x2000
	s_add_u32 s28, s34, 0x40080
	v_lshl_add_u64 v[208:209], v[210:211], 0, s[22:23]
	s_addc_u32 s29, s35, 0
	s_add_i32 s34, s49, s58
	global_load_lds_dwordx4 v[208:209], off
	v_lshl_add_u64 v[208:209], s[28:29], 0, v[192:193]
	s_mov_b32 m0, s34
	s_nop 0
	global_load_lds_dwordx4 v[208:209], off
	v_lshl_add_u64 v[208:209], s[28:29], 0, v[198:199]
	s_add_i32 m0, s34, 0x2000
	s_nop 0
	global_load_lds_dwordx4 v[208:209], off
	v_lshl_add_u64 v[208:209], v[212:213], 0, s[22:23]
	s_mov_b32 m0, s67
	s_nop 0
	global_load_lds_dwordx4 v[208:209], off
	v_lshl_add_u64 v[208:209], v[214:215], 0, s[22:23]
	s_mov_b32 m0, s68
	s_nop 0
	global_load_lds_dwordx4 v[208:209], off
	s_waitcnt vmcnt(8)
	s_cmp_lg_u32 s98, 0
	s_cbranch_scc0 .Llk_24
	s_waitcnt lgkmcnt(0)
.Llk_24:
	s_barrier
	s_setprio 1
	s_waitcnt lgkmcnt(0)
	v_mfma_f32_16x16x32_bf16 v[60:63], v[64:67], v[152:155], v[60:63]
	v_mfma_f32_16x16x32_bf16 v[56:59], v[80:83], v[152:155], v[56:59]
	v_mfma_f32_16x16x32_bf16 v[44:47], v[64:67], v[168:171], v[44:47]
	v_mfma_f32_16x16x32_bf16 v[40:43], v[80:83], v[168:171], v[40:43]
	v_mfma_f32_16x16x32_bf16 v[28:31], v[64:67], v[176:179], v[28:31]
	v_mfma_f32_16x16x32_bf16 v[24:27], v[80:83], v[176:179], v[24:27]
	v_mfma_f32_16x16x32_bf16 v[12:15], v[64:67], v[184:187], v[12:15]
	v_mfma_f32_16x16x32_bf16 v[8:11], v[80:83], v[184:187], v[8:11]
	v_mfma_f32_16x16x32_bf16 v[60:63], v[68:71], v[164:167], v[60:63]
	v_mfma_f32_16x16x32_bf16 v[56:59], v[92:95], v[164:167], v[56:59]
	v_mfma_f32_16x16x32_bf16 v[44:47], v[68:71], v[172:175], v[44:47]
	v_mfma_f32_16x16x32_bf16 v[40:43], v[92:95], v[172:175], v[40:43]
	v_mfma_f32_16x16x32_bf16 v[28:31], v[68:71], v[180:183], v[28:31]
	v_mfma_f32_16x16x32_bf16 v[24:27], v[92:95], v[180:183], v[24:27]
	v_mfma_f32_16x16x32_bf16 v[12:15], v[68:71], v[188:191], v[12:15]
	v_mfma_f32_16x16x32_bf16 v[8:11], v[92:95], v[188:191], v[8:11]
	s_setprio 0
	s_setprio 1
	v_mfma_f32_16x16x32_bf16 v[52:55], v[104:107], v[152:155], v[52:55]
	v_mfma_f32_16x16x32_bf16 v[48:51], v[120:123], v[152:155], v[48:51]
	v_mfma_f32_16x16x32_bf16 v[36:39], v[104:107], v[168:171], v[36:39]
	v_mfma_f32_16x16x32_bf16 v[32:35], v[120:123], v[168:171], v[32:35]
	v_mfma_f32_16x16x32_bf16 v[20:23], v[104:107], v[176:179], v[20:23]
	v_mfma_f32_16x16x32_bf16 v[16:19], v[120:123], v[176:179], v[16:19]
	v_mfma_f32_16x16x32_bf16 v[4:7], v[104:107], v[184:187], v[4:7]
	v_mfma_f32_16x16x32_bf16 v[0:3], v[120:123], v[184:187], v[0:3]
	v_mfma_f32_16x16x32_bf16 v[52:55], v[108:111], v[164:167], v[52:55]
	v_mfma_f32_16x16x32_bf16 v[48:51], v[132:135], v[164:167], v[48:51]
	v_mfma_f32_16x16x32_bf16 v[36:39], v[108:111], v[172:175], v[36:39]
	v_mfma_f32_16x16x32_bf16 v[32:35], v[132:135], v[172:175], v[32:35]
	v_mfma_f32_16x16x32_bf16 v[20:23], v[108:111], v[180:183], v[20:23]
	v_mfma_f32_16x16x32_bf16 v[16:19], v[132:135], v[180:183], v[16:19]
	v_mfma_f32_16x16x32_bf16 v[4:7], v[108:111], v[188:191], v[4:7]
	v_mfma_f32_16x16x32_bf16 v[0:3], v[132:135], v[188:191], v[0:3]
	s_setprio 0
	s_barrier
	s_add_i32 s76, s76, 2
	s_add_u32 s74, s74, 0x100
	s_addc_u32 s75, s75, 0
	s_cmp_gt_u32 s76, 13
	s_mov_b64 s[28:29], s[6:7]
	s_cbranch_scc0 .LBB0_1083
	s_and_b64 vcc, exec, s[36:37]
	s_cbranch_vccz .LBB0_1086
	s_barrier

; #define PG8_STAGE(bufoff, gbase, voff) do { _Pragma("unroll") for (int _i = 0; _i < 2; ++_i) \
;         __builtin_amdgcn_global_load_lds((const unsigned*)((const char*)(gbase) + (voff)[_i]), (PG8_LAS unsigned*)(lds + (bufoff) + ldsw + _i * 8192), 16, 0, 0); } while (0)
; #define PG8_LDA(dst, b, h) do { _Pragma("unroll") for (int m = 0; m < 4; ++m) _Pragma("unroll") for (int k = 0; k < 2; ++k) dst[m][k] = *(const PG8_LAS bf16x8*)(lds + PG8_SA(b, h) + aoff + m * 2048 + k * 1024); } while (0)
; #define PG8_LDB(dst, b, h) do { _Pragma("unroll") for (int n = 0; n < 2; ++n) _Pragma("unroll") for (int k = 0; k < 2; ++k) dst[n][k] = *(const PG8_LAS bf16x8*)(lds + PG8_SB(b, h) + boff + n * 2048 + k * 1024); } while (0)
; #define PG8_WAIT_V(n) asm volatile("s_waitcnt vmcnt(" #n ")" ::: "memory")
; #define PG8_WAIT_L(n) asm volatile("s_waitcnt lgkmcnt(" #n ")" ::: "memory")
; #define PG8_BAR __builtin_amdgcn_s_barrier()
;     ...
;         for (int t = 0; t < nt; t += 2) {
;             const bool last = (t == nt - 2);
;             const char* a1 = cA + (size_t)(t + 1) * kstep;
;             const char* a2 = last ? nA : cA + (size_t)(t + 2) * kstep; const char* b2 = last ? nB : cB + (size_t)(t + 2) * kstep;
;             const char* a3 = a2 + kstep; const char* b3 = b2 + kstep;
;             if (last && has_next) S.a_ready(nxt);
;             if constexpr (SP2) {
;             PG8_LDB(B0, 0, 0); PG8_LDB(B1, 0, 1); PG8_SCHED; PG8_LDA(At, 0, 0); PG8_STAGE(PG8_SA(1, 1), a1 + hstepA, voffA);
;             PG8_WAIT_V(8); PG8_WAIT_L(0); PG8_BAR; PG8_MMA(0, 0, At, B0); PG8_MMA(0, 1, At, B1); PG8_BAR; PG8_SCHED;
;             PG8_LDA(At, 0, 1); PG8_STAGE(PG8_SB(0, 0), b2, voffB); PG8_STAGE(PG8_SB(0, 1), b2 + hstepB, voffB); PG8_STAGE(PG8_SA(0, 0), a2, voffA);
;             PG8_WAIT_V(8); PG8_WAIT_L(0); PG8_BAR; PG8_MMA(1, 0, At, B0); PG8_MMA(1, 1, At, B1); PG8_BAR; PG8_SCHED;
;             PG8_LDB(B0, 1, 0); PG8_LDB(B1, 1, 1); PG8_SCHED; PG8_LDA(At, 1, 0); PG8_STAGE(PG8_SA(0, 1), a2 + hstepA, voffA);
;             PG8_WAIT_V(8); PG8_WAIT_L(0); PG8_BAR; PG8_MMA(0, 0, At, B0); PG8_MMA(0, 1, At, B1); PG8_BAR; PG8_SCHED;
;             PG8_LDA(At, 1, 1); PG8_STAGE(PG8_SB(1, 0), b3, voffB); PG8_STAGE(PG8_SB(1, 1), b3 + hstepB, voffB); PG8_STAGE(PG8_SA(1, 0), a3, voffA);
;             PG8_WAIT_V(8); PG8_WAIT_L(0); PG8_BAR; PG8_MMA(1, 0, At, B0); PG8_MMA(1, 1, At, B1); PG8_BAR; PG8_SCHED;
.LBB0_1252:
	ds_read_b128 v[128:131], v203
	ds_read_b128 v[132:135], v203 offset:1024
	ds_read_b128 v[136:139], v203 offset:2048
	ds_read_b128 v[140:143], v203 offset:3072
	ds_read_b128 v[144:147], v204
	ds_read_b128 v[148:151], v204 offset:1024
	ds_read_b128 v[152:155], v204 offset:2048
	ds_read_b128 v[156:159], v204 offset:3072
	s_add_u32 s34, s28, 0xfffc0080
	s_addc_u32 s35, s29, -1
	s_cmp_eq_u32 s61, 12
	s_cselect_b32 s41, s25, s35
	s_cselect_b32 s40, s57, s34
	s_cselect_b32 s35, s23, s60
	s_cselect_b32 s34, s58, s59
	v_lshl_add_u64 v[200:201], s[28:29], 0, v[184:185]
	s_add_i32 m0, s39, 0xc000
	ds_read_b128 v[160:163], v205
	ds_read_b128 v[164:167], v205 offset:1024
	ds_read_b128 v[168:171], v205 offset:2048
	ds_read_b128 v[172:175], v205 offset:3072
	ds_read_b128 v[192:195], v205 offset:4096
	ds_read_b128 v[196:199], v205 offset:5120
	ds_read_b128 v[206:209], v205 offset:6144
	ds_read_b128 v[210:213], v205 offset:7168
	global_load_lds_dwordx4 v[200:201], off
	v_lshl_add_u64 v[200:201], s[28:29], 0, v[186:187]
	s_add_i32 m0, s39, 0xe000
	s_nop 0
	global_load_lds_dwordx4 v[200:201], off
	s_waitcnt vmcnt(8)
	s_cmp_lg_u32 s98, 0
	s_cbranch_scc0 .Llk_25
	s_waitcnt lgkmcnt(0)
.Llk_25:
	s_barrier
	s_setprio 1
	s_waitcnt lgkmcnt(0)
	v_mfma_f32_16x16x32_bf16 v[124:127], v[128:131], v[160:163], v[124:127]
	v_mfma_f32_16x16x32_bf16 v[120:123], v[136:139], v[160:163], v[120:123]
	v_mfma_f32_16x16x32_bf16 v[108:111], v[128:131], v[168:171], v[108:111]
	v_mfma_f32_16x16x32_bf16 v[104:107], v[136:139], v[168:171], v[104:107]
	v_mfma_f32_16x16x32_bf16 v[92:95], v[128:131], v[192:195], v[92:95]
	v_mfma_f32_16x16x32_bf16 v[88:91], v[136:139], v[192:195], v[88:91]
	v_mfma_f32_16x16x32_bf16 v[76:79], v[128:131], v[206:209], v[76:79]
	v_mfma_f32_16x16x32_bf16 v[72:75], v[136:139], v[206:209], v[72:75]
	v_mfma_f32_16x16x32_bf16 v[124:127], v[132:135], v[164:167], v[124:127]
	v_mfma_f32_16x16x32_bf16 v[120:123], v[140:143], v[164:167], v[120:123]
	v_mfma_f32_16x16x32_bf16 v[108:111], v[132:135], v[172:175], v[108:111]
	v_mfma_f32_16x16x32_bf16 v[104:107], v[140:143], v[172:175], v[104:107]
	v_mfma_f32_16x16x32_bf16 v[92:95], v[132:135], v[196:199], v[92:95]
	v_mfma_f32_16x16x32_bf16 v[88:91], v[140:143], v[196:199], v[88:91]
	v_mfma_f32_16x16x32_bf16 v[76:79], v[132:135], v[210:213], v[76:79]
	v_mfma_f32_16x16x32_bf16 v[72:75], v[140:143], v[210:213], v[72:75]
	s_setprio 0
	s_setprio 1
	v_mfma_f32_16x16x32_bf16 v[116:119], v[144:147], v[160:163], v[116:119]
	v_mfma_f32_16x16x32_bf16 v[112:115], v[152:155], v[160:163], v[112:115]
	v_mfma_f32_16x16x32_bf16 v[100:103], v[144:147], v[168:171], v[100:103]
	v_mfma_f32_16x16x32_bf16 v[96:99], v[152:155], v[168:171], v[96:99]
	v_mfma_f32_16x16x32_bf16 v[84:87], v[144:147], v[192:195], v[84:87]
	v_mfma_f32_16x16x32_bf16 v[80:83], v[152:155], v[192:195], v[80:83]
	v_mfma_f32_16x16x32_bf16 v[68:71], v[144:147], v[206:209], v[68:71]
	v_mfma_f32_16x16x32_bf16 v[64:67], v[152:155], v[206:209], v[64:67]
	v_mfma_f32_16x16x32_bf16 v[116:119], v[148:151], v[164:167], v[116:119]
	v_mfma_f32_16x16x32_bf16 v[112:115], v[156:159], v[164:167], v[112:115]
	v_mfma_f32_16x16x32_bf16 v[100:103], v[148:151], v[172:175], v[100:103]
	v_mfma_f32_16x16x32_bf16 v[96:99], v[156:159], v[172:175], v[96:99]
	v_mfma_f32_16x16x32_bf16 v[84:87], v[148:151], v[196:199], v[84:87]
	v_mfma_f32_16x16x32_bf16 v[80:83], v[156:159], v[196:199], v[80:83]
	v_mfma_f32_16x16x32_bf16 v[68:71], v[148:151], v[210:213], v[68:71]
	v_mfma_f32_16x16x32_bf16 v[64:67], v[156:159], v[210:213], v[64:67]
	s_setprio 0
	s_barrier
	s_add_i32 s48, s55, s43
	v_lshl_add_u64 v[200:201], s[34:35], 0, v[178:179]
	s_mov_b32 m0, s48
	ds_read_b128 v[160:163], v205 offset:16384
	ds_read_b128 v[164:167], v205 offset:17408
	ds_read_b128 v[168:171], v205 offset:18432
	ds_read_b128 v[172:175], v205 offset:19456
	ds_read_b128 v[192:195], v205 offset:20480
	ds_read_b128 v[196:199], v205 offset:21504
	ds_read_b128 v[206:209], v205 offset:22528
	ds_read_b128 v[210:213], v205 offset:23552
	global_load_lds_dwordx4 v[200:201], off
	s_add_i32 m0, s48, 0x2000
	s_add_u32 s48, s34, 0x40000
	v_lshl_add_u64 v[214:215], s[34:35], 0, v[182:183]
	s_addc_u32 s49, s35, 0
	s_add_i32 s62, s56, s43
	global_load_lds_dwordx4 v[214:215], off
	v_lshl_add_u64 v[216:217], s[48:49], 0, v[178:179]
	s_mov_b32 m0, s62
	v_lshl_add_u64 v[218:219], s[40:41], 0, v[180:181]
	global_load_lds_dwordx4 v[216:217], off
	v_lshl_add_u64 v[216:217], s[48:49], 0, v[182:183]
	s_add_i32 m0, s62, 0x2000
	s_nop 0
	global_load_lds_dwordx4 v[216:217], off
	v_lshl_add_u64 v[216:217], s[40:41], 0, v[176:177]
	s_mov_b32 m0, s39
	s_nop 0
	global_load_lds_dwordx4 v[216:217], off
	s_mov_b32 m0, s45
	s_nop 0
	global_load_lds_dwordx4 v[218:219], off
	s_waitcnt vmcnt(8)
	s_cmp_lg_u32 s98, 0
	s_cbranch_scc0 .Llk_26
	s_waitcnt lgkmcnt(0)
; #define PG8_STAGE(bufoff, gbase, voff) do { _Pragma("unroll") for (int _i = 0; _i < 2; ++_i) \
;         __builtin_amdgcn_global_load_lds((const unsigned*)((const char*)(gbase) + (voff)[_i]), (PG8_LAS unsigned*)(lds + (bufoff) + ldsw + _i * 8192), 16, 0, 0); } while (0)
; #define PG8_LDA(dst, b, h) do { _Pragma("unroll") for (int m = 0; m < 4; ++m) _Pragma("unroll") for (int k = 0; k < 2; ++k) dst[m][k] = *(const PG8_LAS bf16x8*)(lds + PG8_SA(b, h) + aoff + m * 2048 + k * 1024); } while (0)
; #define PG8_LDB(dst, b, h) do { _Pragma("unroll") for (int n = 0; n < 2; ++n) _Pragma("unroll") for (int k = 0; k < 2; ++k) dst[n][k] = *(const PG8_LAS bf16x8*)(lds + PG8_SB(b, h) + boff + n * 2048 + k * 1024); } while (0)
; #define PG8_MMA(ai, bj, At, Bt) do { __builtin_amdgcn_s_setprio(1); _Pragma("unroll") for (int m = 0; m < 4; ++m) _Pragma("unroll") for (int n = 0; n < 2; ++n) _Pragma("unroll") for (int k = 0; k < 2; ++k) \
;         acc[ai][bj][m][n] = __builtin_amdgcn_mfma_f32_16x16x32_bf16(Bt[n][k], At[m][k], acc[ai][bj][m][n], 0, 0, 0); __builtin_amdgcn_s_setprio(0); } while (0)
; #define PG8_WAIT_V(n) asm volatile("s_waitcnt vmcnt(" #n ")" ::: "memory")
; #define PG8_WAIT_L(n) asm volatile("s_waitcnt lgkmcnt(" #n ")" ::: "memory")
; #define PG8_BAR __builtin_amdgcn_s_barrier()
; #define PG8_SCHED __builtin_amdgcn_sched_barrier(0)
;     ...
;             PG8_LDB(B0, 0, 0); PG8_LDB(B1, 0, 1); PG8_SCHED; PG8_LDA(At, 0, 0); PG8_STAGE(PG8_SA(1, 1), a1 + hstepA, voffA);
;             PG8_WAIT_V(8); PG8_WAIT_L(0); PG8_BAR; PG8_MMA(0, 0, At, B0); PG8_MMA(0, 1, At, B1); PG8_BAR; PG8_SCHED;
;             PG8_LDA(At, 0, 1); PG8_STAGE(PG8_SB(0, 0), b2, voffB); PG8_STAGE(PG8_SB(0, 1), b2 + hstepB, voffB); PG8_STAGE(PG8_SA(0, 0), a2, voffA);
;             PG8_WAIT_V(8); PG8_WAIT_L(0); PG8_BAR; PG8_MMA(1, 0, At, B0); PG8_MMA(1, 1, At, B1); PG8_BAR; PG8_SCHED;
;             PG8_LDB(B0, 1, 0); PG8_LDB(B1, 1, 1); PG8_SCHED; PG8_LDA(At, 1, 0); PG8_STAGE(PG8_SA(0, 1), a2 + hstepA, voffA);
;             PG8_WAIT_V(8); PG8_WAIT_L(0); PG8_BAR; PG8_MMA(0, 0, At, B0); PG8_MMA(0, 1, At, B1); PG8_BAR; PG8_SCHED;
;             PG8_LDA(At, 1, 1); PG8_STAGE(PG8_SB(1, 0), b3, voffB); PG8_STAGE(PG8_SB(1, 1), b3 + hstepB, voffB); PG8_STAGE(PG8_SA(1, 0), a3, voffA);
;             PG8_WAIT_V(8); PG8_WAIT_L(0); PG8_BAR; PG8_MMA(1, 0, At, B0); PG8_MMA(1, 1, At, B1); PG8_BAR; PG8_SCHED;
.Llk_26:
	s_barrier
	s_setprio 1
	s_waitcnt lgkmcnt(0)
	v_mfma_f32_16x16x32_bf16 v[60:63], v[128:131], v[160:163], v[60:63]
	v_mfma_f32_16x16x32_bf16 v[56:59], v[136:139], v[160:163], v[56:59]
	v_mfma_f32_16x16x32_bf16 v[44:47], v[128:131], v[168:171], v[44:47]
	v_mfma_f32_16x16x32_bf16 v[40:43], v[136:139], v[168:171], v[40:43]
	v_mfma_f32_16x16x32_bf16 v[28:31], v[128:131], v[192:195], v[28:31]
	v_mfma_f32_16x16x32_bf16 v[24:27], v[136:139], v[192:195], v[24:27]
	v_mfma_f32_16x16x32_bf16 v[12:15], v[128:131], v[206:209], v[12:15]
	v_mfma_f32_16x16x32_bf16 v[8:11], v[136:139], v[206:209], v[8:11]
	v_mfma_f32_16x16x32_bf16 v[60:63], v[132:135], v[164:167], v[60:63]
	v_mfma_f32_16x16x32_bf16 v[56:59], v[140:143], v[164:167], v[56:59]
	v_mfma_f32_16x16x32_bf16 v[44:47], v[132:135], v[172:175], v[44:47]
	v_mfma_f32_16x16x32_bf16 v[40:43], v[140:143], v[172:175], v[40:43]
	v_mfma_f32_16x16x32_bf16 v[28:31], v[132:135], v[196:199], v[28:31]
	v_mfma_f32_16x16x32_bf16 v[24:27], v[140:143], v[196:199], v[24:27]
	v_mfma_f32_16x16x32_bf16 v[12:15], v[132:135], v[210:213], v[12:15]
	v_mfma_f32_16x16x32_bf16 v[8:11], v[140:143], v[210:213], v[8:11]
	s_setprio 0
	s_setprio 1
	v_mfma_f32_16x16x32_bf16 v[52:55], v[144:147], v[160:163], v[52:55]
	v_mfma_f32_16x16x32_bf16 v[48:51], v[152:155], v[160:163], v[48:51]
	v_mfma_f32_16x16x32_bf16 v[36:39], v[144:147], v[168:171], v[36:39]
	v_mfma_f32_16x16x32_bf16 v[32:35], v[152:155], v[168:171], v[32:35]
	v_mfma_f32_16x16x32_bf16 v[20:23], v[144:147], v[192:195], v[20:23]
	v_mfma_f32_16x16x32_bf16 v[16:19], v[152:155], v[192:195], v[16:19]
	v_mfma_f32_16x16x32_bf16 v[4:7], v[144:147], v[206:209], v[4:7]
	v_mfma_f32_16x16x32_bf16 v[0:3], v[152:155], v[206:209], v[0:3]
	v_mfma_f32_16x16x32_bf16 v[52:55], v[148:151], v[164:167], v[52:55]
	v_mfma_f32_16x16x32_bf16 v[48:51], v[156:159], v[164:167], v[48:51]
	v_mfma_f32_16x16x32_bf16 v[36:39], v[148:151], v[172:175], v[36:39]
	v_mfma_f32_16x16x32_bf16 v[32:35], v[156:159], v[172:175], v[32:35]
	v_mfma_f32_16x16x32_bf16 v[20:23], v[148:151], v[196:199], v[20:23]
	v_mfma_f32_16x16x32_bf16 v[16:19], v[156:159], v[196:199], v[16:19]
	v_mfma_f32_16x16x32_bf16 v[4:7], v[148:151], v[210:213], v[4:7]
	v_mfma_f32_16x16x32_bf16 v[0:3], v[156:159], v[210:213], v[0:3]
	s_setprio 0
	s_barrier
	s_add_i32 s48, 0, 0x18000
	s_add_i32 s49, 0, 0x1c000
	v_add_u32_e32 v140, s48, v202
	v_add_u32_e32 v156, s49, v202
	ds_read_b128 v[128:131], v140
	ds_read_b128 v[132:135], v140 offset:1024
	ds_read_b128 v[136:139], v140 offset:2048
	ds_read_b128 v[140:143], v140 offset:3072
	ds_read_b128 v[144:147], v156
	ds_read_b128 v[148:151], v156 offset:1024
	ds_read_b128 v[152:155], v156 offset:2048
	ds_read_b128 v[156:159], v156 offset:3072
	s_add_u32 s40, s40, 0x40000
	s_addc_u32 s41, s41, 0
	s_mov_b32 m0, s46
	v_lshl_add_u64 v[220:221], s[40:41], 0, v[176:177]
	ds_read_b128 v[160:163], v205 offset:32768
	ds_read_b128 v[164:167], v205 offset:33792
	ds_read_b128 v[168:171], v205 offset:34816
	ds_read_b128 v[172:175], v205 offset:35840
	ds_read_b128 v[192:195], v205 offset:36864
	ds_read_b128 v[196:199], v205 offset:37888
	ds_read_b128 v[206:209], v205 offset:38912
	ds_read_b128 v[210:213], v205 offset:39936
	global_load_lds_dwordx4 v[220:221], off
	v_lshl_add_u64 v[220:221], s[40:41], 0, v[180:181]
	s_mov_b32 m0, s47
	s_nop 0
	global_load_lds_dwordx4 v[220:221], off
	s_waitcnt vmcnt(8)
	s_cmp_lg_u32 s98, 0
	s_cbranch_scc0 .Llk_27
	s_waitcnt lgkmcnt(0)
; #define PG8_STAGE(bufoff, gbase, voff) do { _Pragma("unroll") for (int _i = 0; _i < 2; ++_i) \
;         __builtin_amdgcn_global_load_lds((const unsigned*)((const char*)(gbase) + (voff)[_i]), (PG8_LAS unsigned*)(lds + (bufoff) + ldsw + _i * 8192), 16, 0, 0); } while (0)
; #define PG8_LDA(dst, b, h) do { _Pragma("unroll") for (int m = 0; m < 4; ++m) _Pragma("unroll") for (int k = 0; k < 2; ++k) dst[m][k] = *(const PG8_LAS bf16x8*)(lds + PG8_SA(b, h) + aoff + m * 2048 + k * 1024); } while (0)
; #define PG8_LDB(dst, b, h) do { _Pragma("unroll") for (int n = 0; n < 2; ++n) _Pragma("unroll") for (int k = 0; k < 2; ++k) dst[n][k] = *(const PG8_LAS bf16x8*)(lds + PG8_SB(b, h) + boff + n * 2048 + k * 1024); } while (0)
; #define PG8_WAIT_V(n) asm volatile("s_waitcnt vmcnt(" #n ")" ::: "memory")
; #define PG8_WAIT_L(n) asm volatile("s_waitcnt lgkmcnt(" #n ")" ::: "memory")
; #define PG8_BAR __builtin_amdgcn_s_barrier()
;     ...
;         for (int t = 0; t < nt; t += 2) {
;             const bool last = (t == nt - 2);
;             const char* a1 = cA + (size_t)(t + 1) * kstep;
;             const char* a2 = last ? nA : cA + (size_t)(t + 2) * kstep; const char* b2 = last ? nB : cB + (size_t)(t + 2) * kstep;
;             const char* a3 = a2 + kstep; const char* b3 = b2 + kstep;
;             if (last && has_next) S.a_ready(nxt);
;     ...
;             PG8_LDB(B0, 0, 0); PG8_LDB(B1, 0, 1); PG8_SCHED; PG8_LDA(At, 0, 0); PG8_STAGE(PG8_SA(1, 1), a1 + hstepA, voffA);
;             PG8_WAIT_V(8); PG8_WAIT_L(0); PG8_BAR; PG8_MMA(0, 0, At, B0); PG8_MMA(0, 1, At, B1); PG8_BAR; PG8_SCHED;
;             PG8_LDA(At, 0, 1); PG8_STAGE(PG8_SB(0, 0), b2, voffB); PG8_STAGE(PG8_SB(0, 1), b2 + hstepB, voffB); PG8_STAGE(PG8_SA(0, 0), a2, voffA);
;             PG8_WAIT_V(8); PG8_WAIT_L(0); PG8_BAR; PG8_MMA(1, 0, At, B0); PG8_MMA(1, 1, At, B1); PG8_BAR; PG8_SCHED;
;             PG8_LDB(B0, 1, 0); PG8_LDB(B1, 1, 1); PG8_SCHED; PG8_LDA(At, 1, 0); PG8_STAGE(PG8_SA(0, 1), a2 + hstepA, voffA);
;             PG8_WAIT_V(8); PG8_WAIT_L(0); PG8_BAR; PG8_MMA(0, 0, At, B0); PG8_MMA(0, 1, At, B1); PG8_BAR; PG8_SCHED;
;             PG8_LDA(At, 1, 1); PG8_STAGE(PG8_SB(1, 0), b3, voffB); PG8_STAGE(PG8_SB(1, 1), b3 + hstepB, voffB); PG8_STAGE(PG8_SA(1, 0), a3, voffA);
;             PG8_WAIT_V(8); PG8_WAIT_L(0); PG8_BAR; PG8_MMA(1, 0, At, B0); PG8_MMA(1, 1, At, B1); PG8_BAR; PG8_SCHED;
.Llk_27:
	s_barrier
	s_setprio 1
	s_waitcnt lgkmcnt(0)
	v_mfma_f32_16x16x32_bf16 v[124:127], v[128:131], v[160:163], v[124:127]
	v_mfma_f32_16x16x32_bf16 v[120:123], v[136:139], v[160:163], v[120:123]
	v_mfma_f32_16x16x32_bf16 v[108:111], v[128:131], v[168:171], v[108:111]
	v_mfma_f32_16x16x32_bf16 v[104:107], v[136:139], v[168:171], v[104:107]
	v_mfma_f32_16x16x32_bf16 v[92:95], v[128:131], v[192:195], v[92:95]
	v_mfma_f32_16x16x32_bf16 v[88:91], v[136:139], v[192:195], v[88:91]
	v_mfma_f32_16x16x32_bf16 v[76:79], v[128:131], v[206:209], v[76:79]
	v_mfma_f32_16x16x32_bf16 v[72:75], v[136:139], v[206:209], v[72:75]
	v_mfma_f32_16x16x32_bf16 v[124:127], v[132:135], v[164:167], v[124:127]
	v_mfma_f32_16x16x32_bf16 v[120:123], v[140:143], v[164:167], v[120:123]
	v_mfma_f32_16x16x32_bf16 v[108:111], v[132:135], v[172:175], v[108:111]
	v_mfma_f32_16x16x32_bf16 v[104:107], v[140:143], v[172:175], v[104:107]
	v_mfma_f32_16x16x32_bf16 v[92:95], v[132:135], v[196:199], v[92:95]
	v_mfma_f32_16x16x32_bf16 v[88:91], v[140:143], v[196:199], v[88:91]
	v_mfma_f32_16x16x32_bf16 v[76:79], v[132:135], v[210:213], v[76:79]
	v_mfma_f32_16x16x32_bf16 v[72:75], v[140:143], v[210:213], v[72:75]
	s_setprio 0
	s_setprio 1
	v_mfma_f32_16x16x32_bf16 v[116:119], v[144:147], v[160:163], v[116:119]
	v_mfma_f32_16x16x32_bf16 v[112:115], v[152:155], v[160:163], v[112:115]
	v_mfma_f32_16x16x32_bf16 v[100:103], v[144:147], v[168:171], v[100:103]
	v_mfma_f32_16x16x32_bf16 v[96:99], v[152:155], v[168:171], v[96:99]
	v_mfma_f32_16x16x32_bf16 v[84:87], v[144:147], v[192:195], v[84:87]
	v_mfma_f32_16x16x32_bf16 v[80:83], v[152:155], v[192:195], v[80:83]
	v_mfma_f32_16x16x32_bf16 v[68:71], v[144:147], v[206:209], v[68:71]
	v_mfma_f32_16x16x32_bf16 v[64:67], v[152:155], v[206:209], v[64:67]
	v_mfma_f32_16x16x32_bf16 v[116:119], v[148:151], v[164:167], v[116:119]
	v_mfma_f32_16x16x32_bf16 v[112:115], v[156:159], v[164:167], v[112:115]
	v_mfma_f32_16x16x32_bf16 v[100:103], v[148:151], v[172:175], v[100:103]
	v_mfma_f32_16x16x32_bf16 v[96:99], v[156:159], v[172:175], v[96:99]
	v_mfma_f32_16x16x32_bf16 v[84:87], v[148:151], v[196:199], v[84:87]
	v_mfma_f32_16x16x32_bf16 v[80:83], v[156:159], v[196:199], v[80:83]
	v_mfma_f32_16x16x32_bf16 v[68:71], v[148:151], v[210:213], v[68:71]
	v_mfma_f32_16x16x32_bf16 v[64:67], v[156:159], v[210:213], v[64:67]
	s_setprio 0
	s_barrier
	s_add_i32 s40, s48, s43
	v_lshl_add_u64 v[200:201], v[200:201], 0, s[18:19]
	s_mov_b32 m0, s40
	ds_read_b128 v[160:163], v205 offset:49152
	ds_read_b128 v[164:167], v205 offset:50176
	ds_read_b128 v[168:171], v205 offset:51200
	ds_read_b128 v[172:175], v205 offset:52224
	ds_read_b128 v[192:195], v205 offset:53248
	ds_read_b128 v[196:199], v205 offset:54272
	ds_read_b128 v[206:209], v205 offset:55296
	ds_read_b128 v[210:213], v205 offset:56320
	global_load_lds_dwordx4 v[200:201], off
	s_add_i32 m0, s40, 0x2000
	s_add_u32 s34, s34, 0x40080
	v_lshl_add_u64 v[200:201], v[214:215], 0, s[18:19]
	s_addc_u32 s35, s35, 0
	s_add_i32 s40, s49, s43
	global_load_lds_dwordx4 v[200:201], off
	v_lshl_add_u64 v[200:201], s[34:35], 0, v[178:179]
	s_mov_b32 m0, s40
	s_nop 0
	global_load_lds_dwordx4 v[200:201], off
	v_lshl_add_u64 v[200:201], s[34:35], 0, v[182:183]
	s_add_i32 m0, s40, 0x2000
	s_nop 0
	global_load_lds_dwordx4 v[200:201], off
	v_lshl_add_u64 v[200:201], v[216:217], 0, s[18:19]
	s_mov_b32 m0, s53
	s_nop 0
	global_load_lds_dwordx4 v[200:201], off
	v_lshl_add_u64 v[200:201], v[218:219], 0, s[18:19]
	s_mov_b32 m0, s54
	s_nop 0
	global_load_lds_dwordx4 v[200:201], off
	s_waitcnt vmcnt(8)
	s_cmp_lg_u32 s98, 0
	s_cbranch_scc0 .Llk_28
	s_waitcnt lgkmcnt(0)
.Llk_28:
	s_barrier
	s_setprio 1
	s_waitcnt lgkmcnt(0)
	v_mfma_f32_16x16x32_bf16 v[60:63], v[128:131], v[160:163], v[60:63]
	v_mfma_f32_16x16x32_bf16 v[56:59], v[136:139], v[160:163], v[56:59]
	v_mfma_f32_16x16x32_bf16 v[44:47], v[128:131], v[168:171], v[44:47]
	v_mfma_f32_16x16x32_bf16 v[40:43], v[136:139], v[168:171], v[40:43]
	v_mfma_f32_16x16x32_bf16 v[28:31], v[128:131], v[192:195], v[28:31]
	v_mfma_f32_16x16x32_bf16 v[24:27], v[136:139], v[192:195], v[24:27]
	v_mfma_f32_16x16x32_bf16 v[12:15], v[128:131], v[206:209], v[12:15]
	v_mfma_f32_16x16x32_bf16 v[8:11], v[136:139], v[206:209], v[8:11]
	v_mfma_f32_16x16x32_bf16 v[60:63], v[132:135], v[164:167], v[60:63]
	v_mfma_f32_16x16x32_bf16 v[56:59], v[140:143], v[164:167], v[56:59]
	v_mfma_f32_16x16x32_bf16 v[44:47], v[132:135], v[172:175], v[44:47]
	v_mfma_f32_16x16x32_bf16 v[40:43], v[140:143], v[172:175], v[40:43]
	v_mfma_f32_16x16x32_bf16 v[28:31], v[132:135], v[196:199], v[28:31]
	v_mfma_f32_16x16x32_bf16 v[24:27], v[140:143], v[196:199], v[24:27]
	v_mfma_f32_16x16x32_bf16 v[12:15], v[132:135], v[210:213], v[12:15]
	v_mfma_f32_16x16x32_bf16 v[8:11], v[140:143], v[210:213], v[8:11]
	s_setprio 0
	s_setprio 1
	v_mfma_f32_16x16x32_bf16 v[52:55], v[144:147], v[160:163], v[52:55]
	v_mfma_f32_16x16x32_bf16 v[48:51], v[152:155], v[160:163], v[48:51]
	v_mfma_f32_16x16x32_bf16 v[36:39], v[144:147], v[168:171], v[36:39]
	v_mfma_f32_16x16x32_bf16 v[32:35], v[152:155], v[168:171], v[32:35]
	v_mfma_f32_16x16x32_bf16 v[20:23], v[144:147], v[192:195], v[20:23]
	v_mfma_f32_16x16x32_bf16 v[16:19], v[152:155], v[192:195], v[16:19]
	v_mfma_f32_16x16x32_bf16 v[4:7], v[144:147], v[206:209], v[4:7]
	v_mfma_f32_16x16x32_bf16 v[0:3], v[152:155], v[206:209], v[0:3]
	v_mfma_f32_16x16x32_bf16 v[52:55], v[148:151], v[164:167], v[52:55]
	v_mfma_f32_16x16x32_bf16 v[48:51], v[156:159], v[164:167], v[48:51]
	v_mfma_f32_16x16x32_bf16 v[36:39], v[148:151], v[172:175], v[36:39]
	v_mfma_f32_16x16x32_bf16 v[32:35], v[156:159], v[172:175], v[32:35]
	v_mfma_f32_16x16x32_bf16 v[20:23], v[148:151], v[196:199], v[20:23]
	v_mfma_f32_16x16x32_bf16 v[16:19], v[156:159], v[196:199], v[16:19]
	v_mfma_f32_16x16x32_bf16 v[4:7], v[148:151], v[210:213], v[4:7]
	v_mfma_f32_16x16x32_bf16 v[0:3], v[156:159], v[210:213], v[0:3]
	s_setprio 0
	s_barrier
	s_add_i32 s61, s61, 2
	s_add_u32 s28, s28, 0x100
	s_addc_u32 s29, s29, 0
	s_add_u32 s59, s59, 0x100
	s_addc_u32 s60, s60, 0
	s_cmp_gt_u32 s61, 13
	s_cbranch_scc0 .LBB0_1252
	s_and_b64 vcc, exec, s[20:21]
	s_cbranch_vccz .LBB0_1255
	s_barrier

; #define PG8_STAGE(bufoff, gbase, voff) do { _Pragma("unroll") for (int _i = 0; _i < 2; ++_i) \
;         __builtin_amdgcn_global_load_lds((const unsigned*)((const char*)(gbase) + (voff)[_i]), (PG8_LAS unsigned*)(lds + (bufoff) + ldsw + _i * 8192), 16, 0, 0); } while (0)
; #define PG8_LDA(dst, b, h) do { _Pragma("unroll") for (int m = 0; m < 4; ++m) _Pragma("unroll") for (int k = 0; k < 2; ++k) dst[m][k] = *(const PG8_LAS bf16x8*)(lds + PG8_SA(b, h) + aoff + m * 2048 + k * 1024); } while (0)
; #define PG8_LDB(dst, b, h) do { _Pragma("unroll") for (int n = 0; n < 2; ++n) _Pragma("unroll") for (int k = 0; k < 2; ++k) dst[n][k] = *(const PG8_LAS bf16x8*)(lds + PG8_SB(b, h) + boff + n * 2048 + k * 1024); } while (0)
; #define PG8_WAIT_V(n) asm volatile("s_waitcnt vmcnt(" #n ")" ::: "memory")
; #define PG8_WAIT_L(n) asm volatile("s_waitcnt lgkmcnt(" #n ")" ::: "memory")
; #define PG8_BAR __builtin_amdgcn_s_barrier()
;     ...
;         for (int t = 0; t < nt; t += 2) {
;             const bool last = (t == nt - 2);
;             const char* a1 = cA + (size_t)(t + 1) * kstep;
;             const char* a2 = last ? nA : cA + (size_t)(t + 2) * kstep; const char* b2 = last ? nB : cB + (size_t)(t + 2) * kstep;
;             const char* a3 = a2 + kstep; const char* b3 = b2 + kstep;
;             if (last && has_next) S.a_ready(nxt);
;             if constexpr (SP2) {
;             PG8_LDB(B0, 0, 0); PG8_LDB(B1, 0, 1); PG8_SCHED; PG8_LDA(At, 0, 0); PG8_STAGE(PG8_SA(1, 1), a1 + hstepA, voffA);
;             PG8_WAIT_V(8); PG8_WAIT_L(0); PG8_BAR; PG8_MMA(0, 0, At, B0); PG8_MMA(0, 1, At, B1); PG8_BAR; PG8_SCHED;
;             PG8_LDA(At, 0, 1); PG8_STAGE(PG8_SB(0, 0), b2, voffB); PG8_STAGE(PG8_SB(0, 1), b2 + hstepB, voffB); PG8_STAGE(PG8_SA(0, 0), a2, voffA);
;             PG8_WAIT_V(8); PG8_WAIT_L(0); PG8_BAR; PG8_MMA(1, 0, At, B0); PG8_MMA(1, 1, At, B1); PG8_BAR; PG8_SCHED;
;             PG8_LDB(B0, 1, 0); PG8_LDB(B1, 1, 1); PG8_SCHED; PG8_LDA(At, 1, 0); PG8_STAGE(PG8_SA(0, 1), a2 + hstepA, voffA);
;             PG8_WAIT_V(8); PG8_WAIT_L(0); PG8_BAR; PG8_MMA(0, 0, At, B0); PG8_MMA(0, 1, At, B1); PG8_BAR; PG8_SCHED;
;             PG8_LDA(At, 1, 1); PG8_STAGE(PG8_SB(1, 0), b3, voffB); PG8_STAGE(PG8_SB(1, 1), b3 + hstepB, voffB); PG8_STAGE(PG8_SA(1, 0), a3, voffA);
;             PG8_WAIT_V(8); PG8_WAIT_L(0); PG8_BAR; PG8_MMA(1, 0, At, B0); PG8_MMA(1, 1, At, B1); PG8_BAR; PG8_SCHED;
.LBB0_1341:
	ds_read_b128 v[144:147], v151
	ds_read_b128 v[160:163], v151 offset:1024
	ds_read_b128 v[164:167], v151 offset:2048
	ds_read_b128 v[168:171], v151 offset:3072
	ds_read_b128 v[172:175], v153
	ds_read_b128 v[176:179], v153 offset:1024
	ds_read_b128 v[180:183], v153 offset:2048
	ds_read_b128 v[184:187], v153 offset:3072
	s_add_u32 s36, s34, 0xfffc0080
	s_addc_u32 s37, s35, -1
	s_cmp_eq_u32 s62, 12
	s_cselect_b32 s39, s23, s37
	s_cselect_b32 s38, s58, s36
	s_cselect_b32 s37, s21, s61
	s_cselect_b32 s36, s59, s60
	v_lshl_add_u64 v[154:155], s[34:35], 0, v[136:137]
	s_add_i32 m0, s29, 0xc000
	ds_read_b128 v[188:191], v157
	ds_read_b128 v[192:195], v157 offset:1024
	ds_read_b128 v[196:199], v157 offset:2048
	ds_read_b128 v[200:203], v157 offset:3072
	ds_read_b128 v[204:207], v157 offset:4096
	ds_read_b128 v[208:211], v157 offset:5120
	ds_read_b128 v[212:215], v157 offset:6144
	ds_read_b128 v[216:219], v157 offset:7168
	global_load_lds_dwordx4 v[154:155], off
	v_lshl_add_u64 v[154:155], s[34:35], 0, v[138:139]
	s_add_i32 m0, s29, 0xe000
	s_nop 0
	global_load_lds_dwordx4 v[154:155], off
	s_waitcnt vmcnt(8)
	s_cmp_lg_u32 s98, 0
	s_cbranch_scc0 .Llk_29
	s_waitcnt lgkmcnt(0)
.Llk_29:
	s_barrier
	s_setprio 1
	s_waitcnt lgkmcnt(0)
	v_mfma_f32_16x16x32_bf16 v[124:127], v[144:147], v[188:191], v[124:127]
	v_mfma_f32_16x16x32_bf16 v[120:123], v[164:167], v[188:191], v[120:123]
	v_mfma_f32_16x16x32_bf16 v[108:111], v[144:147], v[196:199], v[108:111]
	v_mfma_f32_16x16x32_bf16 v[104:107], v[164:167], v[196:199], v[104:107]
	v_mfma_f32_16x16x32_bf16 v[92:95], v[144:147], v[204:207], v[92:95]
	v_mfma_f32_16x16x32_bf16 v[88:91], v[164:167], v[204:207], v[88:91]
	v_mfma_f32_16x16x32_bf16 v[76:79], v[144:147], v[212:215], v[76:79]
	v_mfma_f32_16x16x32_bf16 v[72:75], v[164:167], v[212:215], v[72:75]
	v_mfma_f32_16x16x32_bf16 v[124:127], v[160:163], v[192:195], v[124:127]
	v_mfma_f32_16x16x32_bf16 v[120:123], v[168:171], v[192:195], v[120:123]
	v_mfma_f32_16x16x32_bf16 v[108:111], v[160:163], v[200:203], v[108:111]
	v_mfma_f32_16x16x32_bf16 v[104:107], v[168:171], v[200:203], v[104:107]
	v_mfma_f32_16x16x32_bf16 v[92:95], v[160:163], v[208:211], v[92:95]
	v_mfma_f32_16x16x32_bf16 v[88:91], v[168:171], v[208:211], v[88:91]
	v_mfma_f32_16x16x32_bf16 v[76:79], v[160:163], v[216:219], v[76:79]
	v_mfma_f32_16x16x32_bf16 v[72:75], v[168:171], v[216:219], v[72:75]
	s_setprio 0
	s_setprio 1
	v_mfma_f32_16x16x32_bf16 v[116:119], v[172:175], v[188:191], v[116:119]
	v_mfma_f32_16x16x32_bf16 v[112:115], v[180:183], v[188:191], v[112:115]
	v_mfma_f32_16x16x32_bf16 v[100:103], v[172:175], v[196:199], v[100:103]
	v_mfma_f32_16x16x32_bf16 v[96:99], v[180:183], v[196:199], v[96:99]
	v_mfma_f32_16x16x32_bf16 v[84:87], v[172:175], v[204:207], v[84:87]
	v_mfma_f32_16x16x32_bf16 v[80:83], v[180:183], v[204:207], v[80:83]
	v_mfma_f32_16x16x32_bf16 v[68:71], v[172:175], v[212:215], v[68:71]
	v_mfma_f32_16x16x32_bf16 v[64:67], v[180:183], v[212:215], v[64:67]
	v_mfma_f32_16x16x32_bf16 v[116:119], v[176:179], v[192:195], v[116:119]
	v_mfma_f32_16x16x32_bf16 v[112:115], v[184:187], v[192:195], v[112:115]
	v_mfma_f32_16x16x32_bf16 v[100:103], v[176:179], v[200:203], v[100:103]
	v_mfma_f32_16x16x32_bf16 v[96:99], v[184:187], v[200:203], v[96:99]
	v_mfma_f32_16x16x32_bf16 v[84:87], v[176:179], v[208:211], v[84:87]
	v_mfma_f32_16x16x32_bf16 v[80:83], v[184:187], v[208:211], v[80:83]
	v_mfma_f32_16x16x32_bf16 v[68:71], v[176:179], v[216:219], v[68:71]
	v_mfma_f32_16x16x32_bf16 v[64:67], v[184:187], v[216:219], v[64:67]
	s_setprio 0
	s_barrier
	s_add_i32 s48, s54, s43
	v_lshl_add_u64 v[154:155], s[36:37], 0, v[132:133]
	s_mov_b32 m0, s48
	ds_read_b128 v[188:191], v157 offset:16384
	ds_read_b128 v[192:195], v157 offset:17408
	ds_read_b128 v[196:199], v157 offset:18432
	ds_read_b128 v[200:203], v157 offset:19456
	ds_read_b128 v[204:207], v157 offset:20480
	ds_read_b128 v[208:211], v157 offset:21504
	ds_read_b128 v[212:215], v157 offset:22528
	ds_read_b128 v[216:219], v157 offset:23552
	global_load_lds_dwordx4 v[154:155], off
	s_add_i32 m0, s48, 0x2000
	s_add_u32 s48, s36, 0x40000
	v_lshl_add_u64 v[220:221], s[36:37], 0, v[128:129]
	s_addc_u32 s49, s37, 0
	s_add_i32 s63, s55, s43
	global_load_lds_dwordx4 v[220:221], off
	v_lshl_add_u64 v[222:223], s[48:49], 0, v[132:133]
	s_mov_b32 m0, s63
	v_lshl_add_u64 v[224:225], s[38:39], 0, v[130:131]
	global_load_lds_dwordx4 v[222:223], off
	v_lshl_add_u64 v[222:223], s[48:49], 0, v[128:129]
	s_add_i32 m0, s63, 0x2000
	s_nop 0
	global_load_lds_dwordx4 v[222:223], off
	v_lshl_add_u64 v[222:223], s[38:39], 0, v[134:135]
	s_mov_b32 m0, s29
	s_nop 0
	global_load_lds_dwordx4 v[222:223], off
	s_mov_b32 m0, s44
	s_nop 0
	global_load_lds_dwordx4 v[224:225], off
	s_waitcnt vmcnt(8)
	s_cmp_lg_u32 s98, 0
	s_cbranch_scc0 .Llk_30
	s_waitcnt lgkmcnt(0)
; #define PG8_STAGE(bufoff, gbase, voff) do { _Pragma("unroll") for (int _i = 0; _i < 2; ++_i) \
;         __builtin_amdgcn_global_load_lds((const unsigned*)((const char*)(gbase) + (voff)[_i]), (PG8_LAS unsigned*)(lds + (bufoff) + ldsw + _i * 8192), 16, 0, 0); } while (0)
; #define PG8_LDA(dst, b, h) do { _Pragma("unroll") for (int m = 0; m < 4; ++m) _Pragma("unroll") for (int k = 0; k < 2; ++k) dst[m][k] = *(const PG8_LAS bf16x8*)(lds + PG8_SA(b, h) + aoff + m * 2048 + k * 1024); } while (0)
; #define PG8_LDB(dst, b, h) do { _Pragma("unroll") for (int n = 0; n < 2; ++n) _Pragma("unroll") for (int k = 0; k < 2; ++k) dst[n][k] = *(const PG8_LAS bf16x8*)(lds + PG8_SB(b, h) + boff + n * 2048 + k * 1024); } while (0)
; #define PG8_MMA(ai, bj, At, Bt) do { __builtin_amdgcn_s_setprio(1); _Pragma("unroll") for (int m = 0; m < 4; ++m) _Pragma("unroll") for (int n = 0; n < 2; ++n) _Pragma("unroll") for (int k = 0; k < 2; ++k) \
;         acc[ai][bj][m][n] = __builtin_amdgcn_mfma_f32_16x16x32_bf16(Bt[n][k], At[m][k], acc[ai][bj][m][n], 0, 0, 0); __builtin_amdgcn_s_setprio(0); } while (0)
; #define PG8_WAIT_V(n) asm volatile("s_waitcnt vmcnt(" #n ")" ::: "memory")
; #define PG8_WAIT_L(n) asm volatile("s_waitcnt lgkmcnt(" #n ")" ::: "memory")
; #define PG8_BAR __builtin_amdgcn_s_barrier()
; #define PG8_SCHED __builtin_amdgcn_sched_barrier(0)
;     ...
;             PG8_LDB(B0, 0, 0); PG8_LDB(B1, 0, 1); PG8_SCHED; PG8_LDA(At, 0, 0); PG8_STAGE(PG8_SA(1, 1), a1 + hstepA, voffA);
;             PG8_WAIT_V(8); PG8_WAIT_L(0); PG8_BAR; PG8_MMA(0, 0, At, B0); PG8_MMA(0, 1, At, B1); PG8_BAR; PG8_SCHED;
;             PG8_LDA(At, 0, 1); PG8_STAGE(PG8_SB(0, 0), b2, voffB); PG8_STAGE(PG8_SB(0, 1), b2 + hstepB, voffB); PG8_STAGE(PG8_SA(0, 0), a2, voffA);
;             PG8_WAIT_V(8); PG8_WAIT_L(0); PG8_BAR; PG8_MMA(1, 0, At, B0); PG8_MMA(1, 1, At, B1); PG8_BAR; PG8_SCHED;
;             PG8_LDB(B0, 1, 0); PG8_LDB(B1, 1, 1); PG8_SCHED; PG8_LDA(At, 1, 0); PG8_STAGE(PG8_SA(0, 1), a2 + hstepA, voffA);
;             PG8_WAIT_V(8); PG8_WAIT_L(0); PG8_BAR; PG8_MMA(0, 0, At, B0); PG8_MMA(0, 1, At, B1); PG8_BAR; PG8_SCHED;
;             PG8_LDA(At, 1, 1); PG8_STAGE(PG8_SB(1, 0), b3, voffB); PG8_STAGE(PG8_SB(1, 1), b3 + hstepB, voffB); PG8_STAGE(PG8_SA(1, 0), a3, voffA);
;             PG8_WAIT_V(8); PG8_WAIT_L(0); PG8_BAR; PG8_MMA(1, 0, At, B0); PG8_MMA(1, 1, At, B1); PG8_BAR; PG8_SCHED;
.Llk_30:
	s_barrier
	s_setprio 1
	s_waitcnt lgkmcnt(0)
	v_mfma_f32_16x16x32_bf16 v[60:63], v[144:147], v[188:191], v[60:63]
	v_mfma_f32_16x16x32_bf16 v[56:59], v[164:167], v[188:191], v[56:59]
	v_mfma_f32_16x16x32_bf16 v[44:47], v[144:147], v[196:199], v[44:47]
	v_mfma_f32_16x16x32_bf16 v[40:43], v[164:167], v[196:199], v[40:43]
	v_mfma_f32_16x16x32_bf16 v[28:31], v[144:147], v[204:207], v[28:31]
	v_mfma_f32_16x16x32_bf16 v[24:27], v[164:167], v[204:207], v[24:27]
	v_mfma_f32_16x16x32_bf16 v[12:15], v[144:147], v[212:215], v[12:15]
	v_mfma_f32_16x16x32_bf16 v[8:11], v[164:167], v[212:215], v[8:11]
	v_mfma_f32_16x16x32_bf16 v[60:63], v[160:163], v[192:195], v[60:63]
	v_mfma_f32_16x16x32_bf16 v[56:59], v[168:171], v[192:195], v[56:59]
	v_mfma_f32_16x16x32_bf16 v[44:47], v[160:163], v[200:203], v[44:47]
	v_mfma_f32_16x16x32_bf16 v[40:43], v[168:171], v[200:203], v[40:43]
	v_mfma_f32_16x16x32_bf16 v[28:31], v[160:163], v[208:211], v[28:31]
	v_mfma_f32_16x16x32_bf16 v[24:27], v[168:171], v[208:211], v[24:27]
	v_mfma_f32_16x16x32_bf16 v[12:15], v[160:163], v[216:219], v[12:15]
	v_mfma_f32_16x16x32_bf16 v[8:11], v[168:171], v[216:219], v[8:11]
	s_setprio 0
	s_setprio 1
	v_mfma_f32_16x16x32_bf16 v[52:55], v[172:175], v[188:191], v[52:55]
	v_mfma_f32_16x16x32_bf16 v[48:51], v[180:183], v[188:191], v[48:51]
	v_mfma_f32_16x16x32_bf16 v[36:39], v[172:175], v[196:199], v[36:39]
	v_mfma_f32_16x16x32_bf16 v[32:35], v[180:183], v[196:199], v[32:35]
	v_mfma_f32_16x16x32_bf16 v[20:23], v[172:175], v[204:207], v[20:23]
	v_mfma_f32_16x16x32_bf16 v[16:19], v[180:183], v[204:207], v[16:19]
	v_mfma_f32_16x16x32_bf16 v[4:7], v[172:175], v[212:215], v[4:7]
	v_mfma_f32_16x16x32_bf16 v[0:3], v[180:183], v[212:215], v[0:3]
	v_mfma_f32_16x16x32_bf16 v[52:55], v[176:179], v[192:195], v[52:55]
	v_mfma_f32_16x16x32_bf16 v[48:51], v[184:187], v[192:195], v[48:51]
	v_mfma_f32_16x16x32_bf16 v[36:39], v[176:179], v[200:203], v[36:39]
	v_mfma_f32_16x16x32_bf16 v[32:35], v[184:187], v[200:203], v[32:35]
	v_mfma_f32_16x16x32_bf16 v[20:23], v[176:179], v[208:211], v[20:23]
	v_mfma_f32_16x16x32_bf16 v[16:19], v[184:187], v[208:211], v[16:19]
	v_mfma_f32_16x16x32_bf16 v[4:7], v[176:179], v[216:219], v[4:7]
	v_mfma_f32_16x16x32_bf16 v[0:3], v[184:187], v[216:219], v[0:3]
	s_setprio 0
	s_barrier
	s_add_i32 s48, 0, 0x18000
	v_add_u32_e32 v148, s48, v149
	s_add_i32 s49, 0, 0x1c000
	ds_read_b128 v[144:147], v148
	ds_read_b128 v[160:163], v148 offset:1024
	ds_read_b128 v[164:167], v148 offset:2048
	ds_read_b128 v[168:171], v148 offset:3072
	v_add_u32_e32 v148, s49, v149
	ds_read_b128 v[172:175], v148
	ds_read_b128 v[176:179], v148 offset:1024
	ds_read_b128 v[180:183], v148 offset:2048
	ds_read_b128 v[184:187], v148 offset:3072
	s_add_u32 s38, s38, 0x40000
	s_addc_u32 s39, s39, 0
	s_mov_b32 m0, s45
	v_lshl_add_u64 v[226:227], s[38:39], 0, v[134:135]
	ds_read_b128 v[188:191], v157 offset:32768
	ds_read_b128 v[192:195], v157 offset:33792
	ds_read_b128 v[196:199], v157 offset:34816
	ds_read_b128 v[200:203], v157 offset:35840
	ds_read_b128 v[204:207], v157 offset:36864
	ds_read_b128 v[208:211], v157 offset:37888
	ds_read_b128 v[212:215], v157 offset:38912
	ds_read_b128 v[216:219], v157 offset:39936
	global_load_lds_dwordx4 v[226:227], off
	v_lshl_add_u64 v[226:227], s[38:39], 0, v[130:131]
	s_mov_b32 m0, s46
	s_nop 0
	global_load_lds_dwordx4 v[226:227], off
	s_waitcnt vmcnt(8)
	s_cmp_lg_u32 s98, 0
	s_cbranch_scc0 .Llk_31
	s_waitcnt lgkmcnt(0)
; #define PG8_STAGE(bufoff, gbase, voff) do { _Pragma("unroll") for (int _i = 0; _i < 2; ++_i) \
;         __builtin_amdgcn_global_load_lds((const unsigned*)((const char*)(gbase) + (voff)[_i]), (PG8_LAS unsigned*)(lds + (bufoff) + ldsw + _i * 8192), 16, 0, 0); } while (0)
; #define PG8_LDA(dst, b, h) do { _Pragma("unroll") for (int m = 0; m < 4; ++m) _Pragma("unroll") for (int k = 0; k < 2; ++k) dst[m][k] = *(const PG8_LAS bf16x8*)(lds + PG8_SA(b, h) + aoff + m * 2048 + k * 1024); } while (0)
; #define PG8_LDB(dst, b, h) do { _Pragma("unroll") for (int n = 0; n < 2; ++n) _Pragma("unroll") for (int k = 0; k < 2; ++k) dst[n][k] = *(const PG8_LAS bf16x8*)(lds + PG8_SB(b, h) + boff + n * 2048 + k * 1024); } while (0)
; #define PG8_WAIT_V(n) asm volatile("s_waitcnt vmcnt(" #n ")" ::: "memory")
; #define PG8_WAIT_L(n) asm volatile("s_waitcnt lgkmcnt(" #n ")" ::: "memory")
; #define PG8_BAR __builtin_amdgcn_s_barrier()
;     ...
;         for (int t = 0; t < nt; t += 2) {
;             const bool last = (t == nt - 2);
;             const char* a1 = cA + (size_t)(t + 1) * kstep;
;             const char* a2 = last ? nA : cA + (size_t)(t + 2) * kstep; const char* b2 = last ? nB : cB + (size_t)(t + 2) * kstep;
;             const char* a3 = a2 + kstep; const char* b3 = b2 + kstep;
;             if (last && has_next) S.a_ready(nxt);
;     ...
;             PG8_LDB(B0, 0, 0); PG8_LDB(B1, 0, 1); PG8_SCHED; PG8_LDA(At, 0, 0); PG8_STAGE(PG8_SA(1, 1), a1 + hstepA, voffA);
;             PG8_WAIT_V(8); PG8_WAIT_L(0); PG8_BAR; PG8_MMA(0, 0, At, B0); PG8_MMA(0, 1, At, B1); PG8_BAR; PG8_SCHED;
;             PG8_LDA(At, 0, 1); PG8_STAGE(PG8_SB(0, 0), b2, voffB); PG8_STAGE(PG8_SB(0, 1), b2 + hstepB, voffB); PG8_STAGE(PG8_SA(0, 0), a2, voffA);
;             PG8_WAIT_V(8); PG8_WAIT_L(0); PG8_BAR; PG8_MMA(1, 0, At, B0); PG8_MMA(1, 1, At, B1); PG8_BAR; PG8_SCHED;
;             PG8_LDB(B0, 1, 0); PG8_LDB(B1, 1, 1); PG8_SCHED; PG8_LDA(At, 1, 0); PG8_STAGE(PG8_SA(0, 1), a2 + hstepA, voffA);
;             PG8_WAIT_V(8); PG8_WAIT_L(0); PG8_BAR; PG8_MMA(0, 0, At, B0); PG8_MMA(0, 1, At, B1); PG8_BAR; PG8_SCHED;
;             PG8_LDA(At, 1, 1); PG8_STAGE(PG8_SB(1, 0), b3, voffB); PG8_STAGE(PG8_SB(1, 1), b3 + hstepB, voffB); PG8_STAGE(PG8_SA(1, 0), a3, voffA);
;             PG8_WAIT_V(8); PG8_WAIT_L(0); PG8_BAR; PG8_MMA(1, 0, At, B0); PG8_MMA(1, 1, At, B1); PG8_BAR; PG8_SCHED;
.Llk_31:
	s_barrier
	s_setprio 1
	s_waitcnt lgkmcnt(0)
	v_mfma_f32_16x16x32_bf16 v[124:127], v[144:147], v[188:191], v[124:127]
	v_mfma_f32_16x16x32_bf16 v[120:123], v[164:167], v[188:191], v[120:123]
	v_mfma_f32_16x16x32_bf16 v[108:111], v[144:147], v[196:199], v[108:111]
	v_mfma_f32_16x16x32_bf16 v[104:107], v[164:167], v[196:199], v[104:107]
	v_mfma_f32_16x16x32_bf16 v[92:95], v[144:147], v[204:207], v[92:95]
	v_mfma_f32_16x16x32_bf16 v[88:91], v[164:167], v[204:207], v[88:91]
	v_mfma_f32_16x16x32_bf16 v[76:79], v[144:147], v[212:215], v[76:79]
	v_mfma_f32_16x16x32_bf16 v[72:75], v[164:167], v[212:215], v[72:75]
	v_mfma_f32_16x16x32_bf16 v[124:127], v[160:163], v[192:195], v[124:127]
	v_mfma_f32_16x16x32_bf16 v[120:123], v[168:171], v[192:195], v[120:123]
	v_mfma_f32_16x16x32_bf16 v[108:111], v[160:163], v[200:203], v[108:111]
	v_mfma_f32_16x16x32_bf16 v[104:107], v[168:171], v[200:203], v[104:107]
	v_mfma_f32_16x16x32_bf16 v[92:95], v[160:163], v[208:211], v[92:95]
	v_mfma_f32_16x16x32_bf16 v[88:91], v[168:171], v[208:211], v[88:91]
	v_mfma_f32_16x16x32_bf16 v[76:79], v[160:163], v[216:219], v[76:79]
	v_mfma_f32_16x16x32_bf16 v[72:75], v[168:171], v[216:219], v[72:75]
	s_setprio 0
	s_setprio 1
	v_mfma_f32_16x16x32_bf16 v[116:119], v[172:175], v[188:191], v[116:119]
	v_mfma_f32_16x16x32_bf16 v[112:115], v[180:183], v[188:191], v[112:115]
	v_mfma_f32_16x16x32_bf16 v[100:103], v[172:175], v[196:199], v[100:103]
	v_mfma_f32_16x16x32_bf16 v[96:99], v[180:183], v[196:199], v[96:99]
	v_mfma_f32_16x16x32_bf16 v[84:87], v[172:175], v[204:207], v[84:87]
	v_mfma_f32_16x16x32_bf16 v[80:83], v[180:183], v[204:207], v[80:83]
	v_mfma_f32_16x16x32_bf16 v[68:71], v[172:175], v[212:215], v[68:71]
	v_mfma_f32_16x16x32_bf16 v[64:67], v[180:183], v[212:215], v[64:67]
	v_mfma_f32_16x16x32_bf16 v[116:119], v[176:179], v[192:195], v[116:119]
	v_mfma_f32_16x16x32_bf16 v[112:115], v[184:187], v[192:195], v[112:115]
	v_mfma_f32_16x16x32_bf16 v[100:103], v[176:179], v[200:203], v[100:103]
	v_mfma_f32_16x16x32_bf16 v[96:99], v[184:187], v[200:203], v[96:99]
	v_mfma_f32_16x16x32_bf16 v[84:87], v[176:179], v[208:211], v[84:87]
	v_mfma_f32_16x16x32_bf16 v[80:83], v[184:187], v[208:211], v[80:83]
	v_mfma_f32_16x16x32_bf16 v[68:71], v[176:179], v[216:219], v[68:71]
	v_mfma_f32_16x16x32_bf16 v[64:67], v[184:187], v[216:219], v[64:67]
	s_setprio 0
	s_barrier
	s_add_i32 s38, s48, s43
	v_lshl_add_u64 v[154:155], v[154:155], 0, s[10:11]
	s_mov_b32 m0, s38
	ds_read_b128 v[188:191], v157 offset:49152
	ds_read_b128 v[192:195], v157 offset:50176
	ds_read_b128 v[196:199], v157 offset:51200
	ds_read_b128 v[200:203], v157 offset:52224
	ds_read_b128 v[204:207], v157 offset:53248
	ds_read_b128 v[208:211], v157 offset:54272
	ds_read_b128 v[212:215], v157 offset:55296
	ds_read_b128 v[216:219], v157 offset:56320
	global_load_lds_dwordx4 v[154:155], off
	s_add_i32 m0, s38, 0x2000
	s_add_u32 s36, s36, 0x40080
	v_lshl_add_u64 v[154:155], v[220:221], 0, s[10:11]
	s_addc_u32 s37, s37, 0
	s_add_i32 s38, s49, s43
	global_load_lds_dwordx4 v[154:155], off
	v_lshl_add_u64 v[154:155], s[36:37], 0, v[132:133]
	s_mov_b32 m0, s38
	s_nop 0
	global_load_lds_dwordx4 v[154:155], off
	v_lshl_add_u64 v[154:155], s[36:37], 0, v[128:129]
	s_add_i32 m0, s38, 0x2000
	s_nop 0
	global_load_lds_dwordx4 v[154:155], off
	v_lshl_add_u64 v[154:155], v[222:223], 0, s[10:11]
	s_mov_b32 m0, s52
	s_nop 0
	global_load_lds_dwordx4 v[154:155], off
	v_lshl_add_u64 v[154:155], v[224:225], 0, s[10:11]
	s_mov_b32 m0, s53
	s_nop 0
	global_load_lds_dwordx4 v[154:155], off
	s_waitcnt vmcnt(8)
	s_cmp_lg_u32 s98, 0
	s_cbranch_scc0 .Llk_32
	s_waitcnt lgkmcnt(0)
.Llk_32:
	s_barrier
	s_setprio 1
	s_waitcnt lgkmcnt(0)
	v_mfma_f32_16x16x32_bf16 v[60:63], v[144:147], v[188:191], v[60:63]
	v_mfma_f32_16x16x32_bf16 v[56:59], v[164:167], v[188:191], v[56:59]
	v_mfma_f32_16x16x32_bf16 v[44:47], v[144:147], v[196:199], v[44:47]
	v_mfma_f32_16x16x32_bf16 v[40:43], v[164:167], v[196:199], v[40:43]
	v_mfma_f32_16x16x32_bf16 v[28:31], v[144:147], v[204:207], v[28:31]
	v_mfma_f32_16x16x32_bf16 v[24:27], v[164:167], v[204:207], v[24:27]
	v_mfma_f32_16x16x32_bf16 v[12:15], v[144:147], v[212:215], v[12:15]
	v_mfma_f32_16x16x32_bf16 v[8:11], v[164:167], v[212:215], v[8:11]
	v_mfma_f32_16x16x32_bf16 v[60:63], v[160:163], v[192:195], v[60:63]
	v_mfma_f32_16x16x32_bf16 v[56:59], v[168:171], v[192:195], v[56:59]
	v_mfma_f32_16x16x32_bf16 v[44:47], v[160:163], v[200:203], v[44:47]
	v_mfma_f32_16x16x32_bf16 v[40:43], v[168:171], v[200:203], v[40:43]
	v_mfma_f32_16x16x32_bf16 v[28:31], v[160:163], v[208:211], v[28:31]
	v_mfma_f32_16x16x32_bf16 v[24:27], v[168:171], v[208:211], v[24:27]
	v_mfma_f32_16x16x32_bf16 v[12:15], v[160:163], v[216:219], v[12:15]
	v_mfma_f32_16x16x32_bf16 v[8:11], v[168:171], v[216:219], v[8:11]
	s_setprio 0
	s_setprio 1
	v_mfma_f32_16x16x32_bf16 v[52:55], v[172:175], v[188:191], v[52:55]
	v_mfma_f32_16x16x32_bf16 v[48:51], v[180:183], v[188:191], v[48:51]
	v_mfma_f32_16x16x32_bf16 v[36:39], v[172:175], v[196:199], v[36:39]
	v_mfma_f32_16x16x32_bf16 v[32:35], v[180:183], v[196:199], v[32:35]
	v_mfma_f32_16x16x32_bf16 v[20:23], v[172:175], v[204:207], v[20:23]
	v_mfma_f32_16x16x32_bf16 v[16:19], v[180:183], v[204:207], v[16:19]
	v_mfma_f32_16x16x32_bf16 v[4:7], v[172:175], v[212:215], v[4:7]
	v_mfma_f32_16x16x32_bf16 v[0:3], v[180:183], v[212:215], v[0:3]
	v_mfma_f32_16x16x32_bf16 v[52:55], v[176:179], v[192:195], v[52:55]
	v_mfma_f32_16x16x32_bf16 v[48:51], v[184:187], v[192:195], v[48:51]
	v_mfma_f32_16x16x32_bf16 v[36:39], v[176:179], v[200:203], v[36:39]
	v_mfma_f32_16x16x32_bf16 v[32:35], v[184:187], v[200:203], v[32:35]
	v_mfma_f32_16x16x32_bf16 v[20:23], v[176:179], v[208:211], v[20:23]
	v_mfma_f32_16x16x32_bf16 v[16:19], v[184:187], v[208:211], v[16:19]
	v_mfma_f32_16x16x32_bf16 v[4:7], v[176:179], v[216:219], v[4:7]
	v_mfma_f32_16x16x32_bf16 v[0:3], v[184:187], v[216:219], v[0:3]
	s_setprio 0
	s_barrier
	s_add_i32 s62, s62, 2
	s_add_u32 s34, s34, 0x100
	s_addc_u32 s35, s35, 0
	s_add_u32 s60, s60, 0x100
	s_addc_u32 s61, s61, 0
	s_cmp_gt_u32 s62, 13
	s_cbranch_scc0 .LBB0_1341
	s_and_b64 vcc, exec, s[16:17]
	s_cbranch_vccz .LBB0_1344
	s_barrier

; #define PG8_STAGE(bufoff, gbase, voff) do { _Pragma("unroll") for (int _i = 0; _i < 2; ++_i) \
;         __builtin_amdgcn_global_load_lds((const unsigned*)((const char*)(gbase) + (voff)[_i]), (PG8_LAS unsigned*)(lds + (bufoff) + ldsw + _i * 8192), 16, 0, 0); } while (0)
; #define PG8_LDA(dst, b, h) do { _Pragma("unroll") for (int m = 0; m < 4; ++m) _Pragma("unroll") for (int k = 0; k < 2; ++k) dst[m][k] = *(const PG8_LAS bf16x8*)(lds + PG8_SA(b, h) + aoff + m * 2048 + k * 1024); } while (0)
; #define PG8_LDB(dst, b, h) do { _Pragma("unroll") for (int n = 0; n < 2; ++n) _Pragma("unroll") for (int k = 0; k < 2; ++k) dst[n][k] = *(const PG8_LAS bf16x8*)(lds + PG8_SB(b, h) + boff + n * 2048 + k * 1024); } while (0)
; #define PG8_WAIT_V(n) asm volatile("s_waitcnt vmcnt(" #n ")" ::: "memory")
; #define PG8_WAIT_L(n) asm volatile("s_waitcnt lgkmcnt(" #n ")" ::: "memory")
; #define PG8_BAR __builtin_amdgcn_s_barrier()
;     ...
;         for (int t = 0; t < nt; t += 2) {
;             const bool last = (t == nt - 2);
;             const char* a1 = cA + (size_t)(t + 1) * kstep;
;             const char* a2 = last ? nA : cA + (size_t)(t + 2) * kstep; const char* b2 = last ? nB : cB + (size_t)(t + 2) * kstep;
;             const char* a3 = a2 + kstep; const char* b3 = b2 + kstep;
;             if (last && has_next) S.a_ready(nxt);
;             if constexpr (SP2) {
;             PG8_LDB(B0, 0, 0); PG8_LDB(B1, 0, 1); PG8_SCHED; PG8_LDA(At, 0, 0); PG8_STAGE(PG8_SA(1, 1), a1 + hstepA, voffA);
;             PG8_WAIT_V(8); PG8_WAIT_L(0); PG8_BAR; PG8_MMA(0, 0, At, B0); PG8_MMA(0, 1, At, B1); PG8_BAR; PG8_SCHED;
;             PG8_LDA(At, 0, 1); PG8_STAGE(PG8_SB(0, 0), b2, voffB); PG8_STAGE(PG8_SB(0, 1), b2 + hstepB, voffB); PG8_STAGE(PG8_SA(0, 0), a2, voffA);
;             PG8_WAIT_V(8); PG8_WAIT_L(0); PG8_BAR; PG8_MMA(1, 0, At, B0); PG8_MMA(1, 1, At, B1); PG8_BAR; PG8_SCHED;
;             PG8_LDB(B0, 1, 0); PG8_LDB(B1, 1, 1); PG8_SCHED; PG8_LDA(At, 1, 0); PG8_STAGE(PG8_SA(0, 1), a2 + hstepA, voffA);
;             PG8_WAIT_V(8); PG8_WAIT_L(0); PG8_BAR; PG8_MMA(0, 0, At, B0); PG8_MMA(0, 1, At, B1); PG8_BAR; PG8_SCHED;
;             PG8_LDA(At, 1, 1); PG8_STAGE(PG8_SB(1, 0), b3, voffB); PG8_STAGE(PG8_SB(1, 1), b3 + hstepB, voffB); PG8_STAGE(PG8_SA(1, 0), a3, voffA);
;             PG8_WAIT_V(8); PG8_WAIT_L(0); PG8_BAR; PG8_MMA(1, 0, At, B0); PG8_MMA(1, 1, At, B1); PG8_BAR; PG8_SCHED;
.LBB0_1414:
	ds_read_b128 v[128:131], v163
	ds_read_b128 v[132:135], v163 offset:1024
	ds_read_b128 v[152:155], v163 offset:2048
	ds_read_b128 v[156:159], v163 offset:3072
	ds_read_b128 v[166:169], v164
	ds_read_b128 v[170:173], v164 offset:1024
	ds_read_b128 v[174:177], v164 offset:2048
	ds_read_b128 v[178:181], v164 offset:3072
	s_add_u32 s28, s26, 0xfff00080
	s_addc_u32 s29, s27, -1
	s_cmp_eq_u32 s52, 60
	s_cselect_b32 s35, s21, s29
	s_cselect_b32 s34, s48, s28
	s_cselect_b32 s29, s19, s51
	s_cselect_b32 s28, s49, s50
	v_lshl_add_u64 v[160:161], s[26:27], 0, v[144:145]
	s_add_i32 m0, s8, 0xc000
	ds_read_b128 v[182:185], v165
	ds_read_b128 v[186:189], v165 offset:1024
	ds_read_b128 v[190:193], v165 offset:2048
	ds_read_b128 v[194:197], v165 offset:3072
	ds_read_b128 v[198:201], v165 offset:4096
	ds_read_b128 v[202:205], v165 offset:5120
	ds_read_b128 v[206:209], v165 offset:6144
	ds_read_b128 v[210:213], v165 offset:7168
	global_load_lds_dwordx4 v[160:161], off
	v_lshl_add_u64 v[160:161], s[26:27], 0, v[146:147]
	s_add_i32 m0, s8, 0xe000
	s_nop 0
	global_load_lds_dwordx4 v[160:161], off
	s_waitcnt vmcnt(8)
	s_cmp_lg_u32 s98, 0
	s_cbranch_scc0 .Llk_33
	s_waitcnt lgkmcnt(0)
.Llk_33:
	s_barrier
	s_setprio 1
	s_waitcnt lgkmcnt(0)
	v_mfma_f32_16x16x32_bf16 v[124:127], v[128:131], v[182:185], v[124:127]
	v_mfma_f32_16x16x32_bf16 v[120:123], v[152:155], v[182:185], v[120:123]
	v_mfma_f32_16x16x32_bf16 v[108:111], v[128:131], v[190:193], v[108:111]
	v_mfma_f32_16x16x32_bf16 v[104:107], v[152:155], v[190:193], v[104:107]
	v_mfma_f32_16x16x32_bf16 v[92:95], v[128:131], v[198:201], v[92:95]
	v_mfma_f32_16x16x32_bf16 v[88:91], v[152:155], v[198:201], v[88:91]
	v_mfma_f32_16x16x32_bf16 v[76:79], v[128:131], v[206:209], v[76:79]
	v_mfma_f32_16x16x32_bf16 v[72:75], v[152:155], v[206:209], v[72:75]
	v_mfma_f32_16x16x32_bf16 v[124:127], v[132:135], v[186:189], v[124:127]
	v_mfma_f32_16x16x32_bf16 v[120:123], v[156:159], v[186:189], v[120:123]
	v_mfma_f32_16x16x32_bf16 v[108:111], v[132:135], v[194:197], v[108:111]
	v_mfma_f32_16x16x32_bf16 v[104:107], v[156:159], v[194:197], v[104:107]
	v_mfma_f32_16x16x32_bf16 v[92:95], v[132:135], v[202:205], v[92:95]
	v_mfma_f32_16x16x32_bf16 v[88:91], v[156:159], v[202:205], v[88:91]
	v_mfma_f32_16x16x32_bf16 v[76:79], v[132:135], v[210:213], v[76:79]
	v_mfma_f32_16x16x32_bf16 v[72:75], v[156:159], v[210:213], v[72:75]
	s_setprio 0
	s_setprio 1
	v_mfma_f32_16x16x32_bf16 v[116:119], v[166:169], v[182:185], v[116:119]
	v_mfma_f32_16x16x32_bf16 v[112:115], v[174:177], v[182:185], v[112:115]
	v_mfma_f32_16x16x32_bf16 v[100:103], v[166:169], v[190:193], v[100:103]
	v_mfma_f32_16x16x32_bf16 v[96:99], v[174:177], v[190:193], v[96:99]
	v_mfma_f32_16x16x32_bf16 v[84:87], v[166:169], v[198:201], v[84:87]
	v_mfma_f32_16x16x32_bf16 v[80:83], v[174:177], v[198:201], v[80:83]
	v_mfma_f32_16x16x32_bf16 v[68:71], v[166:169], v[206:209], v[68:71]
	v_mfma_f32_16x16x32_bf16 v[64:67], v[174:177], v[206:209], v[64:67]
	v_mfma_f32_16x16x32_bf16 v[116:119], v[170:173], v[186:189], v[116:119]
	v_mfma_f32_16x16x32_bf16 v[112:115], v[178:181], v[186:189], v[112:115]
	v_mfma_f32_16x16x32_bf16 v[100:103], v[170:173], v[194:197], v[100:103]
	v_mfma_f32_16x16x32_bf16 v[96:99], v[178:181], v[194:197], v[96:99]
	v_mfma_f32_16x16x32_bf16 v[84:87], v[170:173], v[202:205], v[84:87]
	v_mfma_f32_16x16x32_bf16 v[80:83], v[178:181], v[202:205], v[80:83]
	v_mfma_f32_16x16x32_bf16 v[68:71], v[170:173], v[210:213], v[68:71]
	v_mfma_f32_16x16x32_bf16 v[64:67], v[178:181], v[210:213], v[64:67]
	s_setprio 0
	s_barrier
	s_add_i32 s53, s46, s39
	v_lshl_add_u64 v[160:161], s[28:29], 0, v[140:141]
	s_mov_b32 m0, s53
	ds_read_b128 v[182:185], v165 offset:16384
	ds_read_b128 v[186:189], v165 offset:17408
	ds_read_b128 v[190:193], v165 offset:18432
	ds_read_b128 v[194:197], v165 offset:19456
	ds_read_b128 v[198:201], v165 offset:20480
	ds_read_b128 v[202:205], v165 offset:21504
	ds_read_b128 v[206:209], v165 offset:22528
	ds_read_b128 v[210:213], v165 offset:23552
	global_load_lds_dwordx4 v[160:161], off
	s_add_i32 m0, s53, 0x2000
	s_add_u32 s54, s28, 0x100000
	v_lshl_add_u64 v[214:215], s[28:29], 0, v[136:137]
	s_addc_u32 s55, s29, 0
	s_add_i32 s53, s47, s39
	global_load_lds_dwordx4 v[214:215], off
	v_lshl_add_u64 v[216:217], s[54:55], 0, v[140:141]
	s_mov_b32 m0, s53
	v_lshl_add_u64 v[218:219], s[34:35], 0, v[138:139]
	global_load_lds_dwordx4 v[216:217], off
	v_lshl_add_u64 v[216:217], s[54:55], 0, v[136:137]
	s_add_i32 m0, s53, 0x2000
	s_nop 0
	global_load_lds_dwordx4 v[216:217], off
	v_lshl_add_u64 v[216:217], s[34:35], 0, v[142:143]
	s_mov_b32 m0, s8
	s_nop 0
	global_load_lds_dwordx4 v[216:217], off
	s_mov_b32 m0, s13
	s_nop 0
	global_load_lds_dwordx4 v[218:219], off
	s_waitcnt vmcnt(8)
	s_cmp_lg_u32 s98, 0
	s_cbranch_scc0 .Llk_34
	s_waitcnt lgkmcnt(0)
; #define PG8_STAGE(bufoff, gbase, voff) do { _Pragma("unroll") for (int _i = 0; _i < 2; ++_i) \
;         __builtin_amdgcn_global_load_lds((const unsigned*)((const char*)(gbase) + (voff)[_i]), (PG8_LAS unsigned*)(lds + (bufoff) + ldsw + _i * 8192), 16, 0, 0); } while (0)
; #define PG8_LDA(dst, b, h) do { _Pragma("unroll") for (int m = 0; m < 4; ++m) _Pragma("unroll") for (int k = 0; k < 2; ++k) dst[m][k] = *(const PG8_LAS bf16x8*)(lds + PG8_SA(b, h) + aoff + m * 2048 + k * 1024); } while (0)
; #define PG8_LDB(dst, b, h) do { _Pragma("unroll") for (int n = 0; n < 2; ++n) _Pragma("unroll") for (int k = 0; k < 2; ++k) dst[n][k] = *(const PG8_LAS bf16x8*)(lds + PG8_SB(b, h) + boff + n * 2048 + k * 1024); } while (0)
; #define PG8_MMA(ai, bj, At, Bt) do { __builtin_amdgcn_s_setprio(1); _Pragma("unroll") for (int m = 0; m < 4; ++m) _Pragma("unroll") for (int n = 0; n < 2; ++n) _Pragma("unroll") for (int k = 0; k < 2; ++k) \
;         acc[ai][bj][m][n] = __builtin_amdgcn_mfma_f32_16x16x32_bf16(Bt[n][k], At[m][k], acc[ai][bj][m][n], 0, 0, 0); __builtin_amdgcn_s_setprio(0); } while (0)
; #define PG8_WAIT_V(n) asm volatile("s_waitcnt vmcnt(" #n ")" ::: "memory")
; #define PG8_WAIT_L(n) asm volatile("s_waitcnt lgkmcnt(" #n ")" ::: "memory")
; #define PG8_BAR __builtin_amdgcn_s_barrier()
; #define PG8_SCHED __builtin_amdgcn_sched_barrier(0)
;     ...
;             PG8_LDB(B0, 0, 0); PG8_LDB(B1, 0, 1); PG8_SCHED; PG8_LDA(At, 0, 0); PG8_STAGE(PG8_SA(1, 1), a1 + hstepA, voffA);
;             PG8_WAIT_V(8); PG8_WAIT_L(0); PG8_BAR; PG8_MMA(0, 0, At, B0); PG8_MMA(0, 1, At, B1); PG8_BAR; PG8_SCHED;
;             PG8_LDA(At, 0, 1); PG8_STAGE(PG8_SB(0, 0), b2, voffB); PG8_STAGE(PG8_SB(0, 1), b2 + hstepB, voffB); PG8_STAGE(PG8_SA(0, 0), a2, voffA);
;             PG8_WAIT_V(8); PG8_WAIT_L(0); PG8_BAR; PG8_MMA(1, 0, At, B0); PG8_MMA(1, 1, At, B1); PG8_BAR; PG8_SCHED;
;             PG8_LDB(B0, 1, 0); PG8_LDB(B1, 1, 1); PG8_SCHED; PG8_LDA(At, 1, 0); PG8_STAGE(PG8_SA(0, 1), a2 + hstepA, voffA);
;             PG8_WAIT_V(8); PG8_WAIT_L(0); PG8_BAR; PG8_MMA(0, 0, At, B0); PG8_MMA(0, 1, At, B1); PG8_BAR; PG8_SCHED;
;             PG8_LDA(At, 1, 1); PG8_STAGE(PG8_SB(1, 0), b3, voffB); PG8_STAGE(PG8_SB(1, 1), b3 + hstepB, voffB); PG8_STAGE(PG8_SA(1, 0), a3, voffA);
;             PG8_WAIT_V(8); PG8_WAIT_L(0); PG8_BAR; PG8_MMA(1, 0, At, B0); PG8_MMA(1, 1, At, B1); PG8_BAR; PG8_SCHED;
.Llk_34:
	s_barrier
	s_setprio 1
	s_waitcnt lgkmcnt(0)
	v_mfma_f32_16x16x32_bf16 v[60:63], v[128:131], v[182:185], v[60:63]
	v_mfma_f32_16x16x32_bf16 v[56:59], v[152:155], v[182:185], v[56:59]
	v_mfma_f32_16x16x32_bf16 v[48:51], v[128:131], v[190:193], v[48:51]
	v_mfma_f32_16x16x32_bf16 v[40:43], v[152:155], v[190:193], v[40:43]
	v_mfma_f32_16x16x32_bf16 v[32:35], v[128:131], v[198:201], v[32:35]
	v_mfma_f32_16x16x32_bf16 v[24:27], v[152:155], v[198:201], v[24:27]
	v_mfma_f32_16x16x32_bf16 v[16:19], v[128:131], v[206:209], v[16:19]
	v_mfma_f32_16x16x32_bf16 v[8:11], v[152:155], v[206:209], v[8:11]
	v_mfma_f32_16x16x32_bf16 v[60:63], v[132:135], v[186:189], v[60:63]
	v_mfma_f32_16x16x32_bf16 v[56:59], v[156:159], v[186:189], v[56:59]
	v_mfma_f32_16x16x32_bf16 v[48:51], v[132:135], v[194:197], v[48:51]
	v_mfma_f32_16x16x32_bf16 v[40:43], v[156:159], v[194:197], v[40:43]
	v_mfma_f32_16x16x32_bf16 v[32:35], v[132:135], v[202:205], v[32:35]
	v_mfma_f32_16x16x32_bf16 v[24:27], v[156:159], v[202:205], v[24:27]
	v_mfma_f32_16x16x32_bf16 v[16:19], v[132:135], v[210:213], v[16:19]
	v_mfma_f32_16x16x32_bf16 v[8:11], v[156:159], v[210:213], v[8:11]
	s_setprio 0
	s_setprio 1
	v_mfma_f32_16x16x32_bf16 v[52:55], v[166:169], v[182:185], v[52:55]
	v_mfma_f32_16x16x32_bf16 v[44:47], v[174:177], v[182:185], v[44:47]
	v_mfma_f32_16x16x32_bf16 v[36:39], v[166:169], v[190:193], v[36:39]
	v_mfma_f32_16x16x32_bf16 v[28:31], v[174:177], v[190:193], v[28:31]
	v_mfma_f32_16x16x32_bf16 v[20:23], v[166:169], v[198:201], v[20:23]
	v_mfma_f32_16x16x32_bf16 v[12:15], v[174:177], v[198:201], v[12:15]
	v_mfma_f32_16x16x32_bf16 v[4:7], v[166:169], v[206:209], v[4:7]
	v_mfma_f32_16x16x32_bf16 v[0:3], v[174:177], v[206:209], v[0:3]
	v_mfma_f32_16x16x32_bf16 v[52:55], v[170:173], v[186:189], v[52:55]
	v_mfma_f32_16x16x32_bf16 v[44:47], v[178:181], v[186:189], v[44:47]
	v_mfma_f32_16x16x32_bf16 v[36:39], v[170:173], v[194:197], v[36:39]
	v_mfma_f32_16x16x32_bf16 v[28:31], v[178:181], v[194:197], v[28:31]
	v_mfma_f32_16x16x32_bf16 v[20:23], v[170:173], v[202:205], v[20:23]
	v_mfma_f32_16x16x32_bf16 v[12:15], v[178:181], v[202:205], v[12:15]
	v_mfma_f32_16x16x32_bf16 v[4:7], v[170:173], v[210:213], v[4:7]
	v_mfma_f32_16x16x32_bf16 v[0:3], v[178:181], v[210:213], v[0:3]
	s_setprio 0
	s_barrier
	s_add_i32 s53, 0, 0x18000
	s_add_i32 s54, 0, 0x1c000
	v_add_u32_e32 v156, s53, v162
	v_add_u32_e32 v178, s54, v162
	ds_read_b128 v[128:131], v156
	ds_read_b128 v[132:135], v156 offset:1024
	ds_read_b128 v[152:155], v156 offset:2048
	ds_read_b128 v[156:159], v156 offset:3072
	ds_read_b128 v[166:169], v178
	ds_read_b128 v[170:173], v178 offset:1024
	ds_read_b128 v[174:177], v178 offset:2048
	ds_read_b128 v[178:181], v178 offset:3072
	s_add_u32 s34, s34, 0x100000
	s_addc_u32 s35, s35, 0
	s_mov_b32 m0, s40
	v_lshl_add_u64 v[220:221], s[34:35], 0, v[142:143]
	ds_read_b128 v[182:185], v165 offset:32768
	ds_read_b128 v[186:189], v165 offset:33792
	ds_read_b128 v[190:193], v165 offset:34816
	ds_read_b128 v[194:197], v165 offset:35840
	ds_read_b128 v[198:201], v165 offset:36864
	ds_read_b128 v[202:205], v165 offset:37888
	ds_read_b128 v[206:209], v165 offset:38912
	ds_read_b128 v[210:213], v165 offset:39936
	global_load_lds_dwordx4 v[220:221], off
	v_lshl_add_u64 v[220:221], s[34:35], 0, v[138:139]
	s_mov_b32 m0, s41
	s_nop 0
	global_load_lds_dwordx4 v[220:221], off
	s_waitcnt vmcnt(8)
	s_cmp_lg_u32 s98, 0
	s_cbranch_scc0 .Llk_35
	s_waitcnt lgkmcnt(0)
; #define PG8_STAGE(bufoff, gbase, voff) do { _Pragma("unroll") for (int _i = 0; _i < 2; ++_i) \
;         __builtin_amdgcn_global_load_lds((const unsigned*)((const char*)(gbase) + (voff)[_i]), (PG8_LAS unsigned*)(lds + (bufoff) + ldsw + _i * 8192), 16, 0, 0); } while (0)
; #define PG8_LDA(dst, b, h) do { _Pragma("unroll") for (int m = 0; m < 4; ++m) _Pragma("unroll") for (int k = 0; k < 2; ++k) dst[m][k] = *(const PG8_LAS bf16x8*)(lds + PG8_SA(b, h) + aoff + m * 2048 + k * 1024); } while (0)
; #define PG8_LDB(dst, b, h) do { _Pragma("unroll") for (int n = 0; n < 2; ++n) _Pragma("unroll") for (int k = 0; k < 2; ++k) dst[n][k] = *(const PG8_LAS bf16x8*)(lds + PG8_SB(b, h) + boff + n * 2048 + k * 1024); } while (0)
; #define PG8_WAIT_V(n) asm volatile("s_waitcnt vmcnt(" #n ")" ::: "memory")
; #define PG8_WAIT_L(n) asm volatile("s_waitcnt lgkmcnt(" #n ")" ::: "memory")
; #define PG8_BAR __builtin_amdgcn_s_barrier()
;     ...
;         for (int t = 0; t < nt; t += 2) {
;             const bool last = (t == nt - 2);
;             const char* a1 = cA + (size_t)(t + 1) * kstep;
;             const char* a2 = last ? nA : cA + (size_t)(t + 2) * kstep; const char* b2 = last ? nB : cB + (size_t)(t + 2) * kstep;
;             const char* a3 = a2 + kstep; const char* b3 = b2 + kstep;
;             if (last && has_next) S.a_ready(nxt);
;     ...
;             PG8_LDB(B0, 0, 0); PG8_LDB(B1, 0, 1); PG8_SCHED; PG8_LDA(At, 0, 0); PG8_STAGE(PG8_SA(1, 1), a1 + hstepA, voffA);
;             PG8_WAIT_V(8); PG8_WAIT_L(0); PG8_BAR; PG8_MMA(0, 0, At, B0); PG8_MMA(0, 1, At, B1); PG8_BAR; PG8_SCHED;
;             PG8_LDA(At, 0, 1); PG8_STAGE(PG8_SB(0, 0), b2, voffB); PG8_STAGE(PG8_SB(0, 1), b2 + hstepB, voffB); PG8_STAGE(PG8_SA(0, 0), a2, voffA);
;             PG8_WAIT_V(8); PG8_WAIT_L(0); PG8_BAR; PG8_MMA(1, 0, At, B0); PG8_MMA(1, 1, At, B1); PG8_BAR; PG8_SCHED;
;             PG8_LDB(B0, 1, 0); PG8_LDB(B1, 1, 1); PG8_SCHED; PG8_LDA(At, 1, 0); PG8_STAGE(PG8_SA(0, 1), a2 + hstepA, voffA);
;             PG8_WAIT_V(8); PG8_WAIT_L(0); PG8_BAR; PG8_MMA(0, 0, At, B0); PG8_MMA(0, 1, At, B1); PG8_BAR; PG8_SCHED;
;             PG8_LDA(At, 1, 1); PG8_STAGE(PG8_SB(1, 0), b3, voffB); PG8_STAGE(PG8_SB(1, 1), b3 + hstepB, voffB); PG8_STAGE(PG8_SA(1, 0), a3, voffA);
;             PG8_WAIT_V(8); PG8_WAIT_L(0); PG8_BAR; PG8_MMA(1, 0, At, B0); PG8_MMA(1, 1, At, B1); PG8_BAR; PG8_SCHED;
.Llk_35:
	s_barrier
	s_setprio 1
	s_waitcnt lgkmcnt(0)
	v_mfma_f32_16x16x32_bf16 v[124:127], v[128:131], v[182:185], v[124:127]
	v_mfma_f32_16x16x32_bf16 v[120:123], v[152:155], v[182:185], v[120:123]
	v_mfma_f32_16x16x32_bf16 v[108:111], v[128:131], v[190:193], v[108:111]
	v_mfma_f32_16x16x32_bf16 v[104:107], v[152:155], v[190:193], v[104:107]
	v_mfma_f32_16x16x32_bf16 v[92:95], v[128:131], v[198:201], v[92:95]
	v_mfma_f32_16x16x32_bf16 v[88:91], v[152:155], v[198:201], v[88:91]
	v_mfma_f32_16x16x32_bf16 v[76:79], v[128:131], v[206:209], v[76:79]
	v_mfma_f32_16x16x32_bf16 v[72:75], v[152:155], v[206:209], v[72:75]
	v_mfma_f32_16x16x32_bf16 v[124:127], v[132:135], v[186:189], v[124:127]
	v_mfma_f32_16x16x32_bf16 v[120:123], v[156:159], v[186:189], v[120:123]
	v_mfma_f32_16x16x32_bf16 v[108:111], v[132:135], v[194:197], v[108:111]
	v_mfma_f32_16x16x32_bf16 v[104:107], v[156:159], v[194:197], v[104:107]
	v_mfma_f32_16x16x32_bf16 v[92:95], v[132:135], v[202:205], v[92:95]
	v_mfma_f32_16x16x32_bf16 v[88:91], v[156:159], v[202:205], v[88:91]
	v_mfma_f32_16x16x32_bf16 v[76:79], v[132:135], v[210:213], v[76:79]
	v_mfma_f32_16x16x32_bf16 v[72:75], v[156:159], v[210:213], v[72:75]
	s_setprio 0
	s_setprio 1
	v_mfma_f32_16x16x32_bf16 v[116:119], v[166:169], v[182:185], v[116:119]
	v_mfma_f32_16x16x32_bf16 v[112:115], v[174:177], v[182:185], v[112:115]
	v_mfma_f32_16x16x32_bf16 v[100:103], v[166:169], v[190:193], v[100:103]
	v_mfma_f32_16x16x32_bf16 v[96:99], v[174:177], v[190:193], v[96:99]
	v_mfma_f32_16x16x32_bf16 v[84:87], v[166:169], v[198:201], v[84:87]
	v_mfma_f32_16x16x32_bf16 v[80:83], v[174:177], v[198:201], v[80:83]
	v_mfma_f32_16x16x32_bf16 v[68:71], v[166:169], v[206:209], v[68:71]
	v_mfma_f32_16x16x32_bf16 v[64:67], v[174:177], v[206:209], v[64:67]
	v_mfma_f32_16x16x32_bf16 v[116:119], v[170:173], v[186:189], v[116:119]
	v_mfma_f32_16x16x32_bf16 v[112:115], v[178:181], v[186:189], v[112:115]
	v_mfma_f32_16x16x32_bf16 v[100:103], v[170:173], v[194:197], v[100:103]
	v_mfma_f32_16x16x32_bf16 v[96:99], v[178:181], v[194:197], v[96:99]
	v_mfma_f32_16x16x32_bf16 v[84:87], v[170:173], v[202:205], v[84:87]
	v_mfma_f32_16x16x32_bf16 v[80:83], v[178:181], v[202:205], v[80:83]
	v_mfma_f32_16x16x32_bf16 v[68:71], v[170:173], v[210:213], v[68:71]
	v_mfma_f32_16x16x32_bf16 v[64:67], v[178:181], v[210:213], v[64:67]
	s_setprio 0
	s_barrier
	s_add_i32 s34, s53, s39
	v_lshl_add_u64 v[160:161], v[160:161], 0, s[14:15]
	s_mov_b32 m0, s34
	ds_read_b128 v[182:185], v165 offset:49152
	ds_read_b128 v[186:189], v165 offset:50176
	ds_read_b128 v[190:193], v165 offset:51200
	ds_read_b128 v[194:197], v165 offset:52224
	ds_read_b128 v[198:201], v165 offset:53248
	ds_read_b128 v[202:205], v165 offset:54272
	ds_read_b128 v[206:209], v165 offset:55296
	ds_read_b128 v[210:213], v165 offset:56320
	global_load_lds_dwordx4 v[160:161], off
	s_add_i32 m0, s34, 0x2000
	s_add_u32 s28, s28, 0x100080
	v_lshl_add_u64 v[160:161], v[214:215], 0, s[14:15]
	s_addc_u32 s29, s29, 0
	s_add_i32 s34, s54, s39
	global_load_lds_dwordx4 v[160:161], off
	v_lshl_add_u64 v[160:161], s[28:29], 0, v[140:141]
	s_mov_b32 m0, s34
	s_nop 0
	global_load_lds_dwordx4 v[160:161], off
	v_lshl_add_u64 v[160:161], s[28:29], 0, v[136:137]
	s_add_i32 m0, s34, 0x2000
	s_nop 0
	global_load_lds_dwordx4 v[160:161], off
	v_lshl_add_u64 v[160:161], v[216:217], 0, s[14:15]
	s_mov_b32 m0, s44
	s_nop 0
	global_load_lds_dwordx4 v[160:161], off
	v_lshl_add_u64 v[160:161], v[218:219], 0, s[14:15]
	s_mov_b32 m0, s45
	s_nop 0
	global_load_lds_dwordx4 v[160:161], off
	s_waitcnt vmcnt(8)
	s_cmp_lg_u32 s98, 0
	s_cbranch_scc0 .Llk_36
	s_waitcnt lgkmcnt(0)
.Llk_36:
	s_barrier
	s_setprio 1
	s_waitcnt lgkmcnt(0)
	v_mfma_f32_16x16x32_bf16 v[60:63], v[128:131], v[182:185], v[60:63]
	v_mfma_f32_16x16x32_bf16 v[56:59], v[152:155], v[182:185], v[56:59]
	v_mfma_f32_16x16x32_bf16 v[48:51], v[128:131], v[190:193], v[48:51]
	v_mfma_f32_16x16x32_bf16 v[40:43], v[152:155], v[190:193], v[40:43]
	v_mfma_f32_16x16x32_bf16 v[32:35], v[128:131], v[198:201], v[32:35]
	v_mfma_f32_16x16x32_bf16 v[24:27], v[152:155], v[198:201], v[24:27]
	v_mfma_f32_16x16x32_bf16 v[16:19], v[128:131], v[206:209], v[16:19]
	v_mfma_f32_16x16x32_bf16 v[8:11], v[152:155], v[206:209], v[8:11]
	v_mfma_f32_16x16x32_bf16 v[60:63], v[132:135], v[186:189], v[60:63]
	v_mfma_f32_16x16x32_bf16 v[56:59], v[156:159], v[186:189], v[56:59]
	v_mfma_f32_16x16x32_bf16 v[48:51], v[132:135], v[194:197], v[48:51]
	v_mfma_f32_16x16x32_bf16 v[40:43], v[156:159], v[194:197], v[40:43]
	v_mfma_f32_16x16x32_bf16 v[32:35], v[132:135], v[202:205], v[32:35]
	v_mfma_f32_16x16x32_bf16 v[24:27], v[156:159], v[202:205], v[24:27]
	v_mfma_f32_16x16x32_bf16 v[16:19], v[132:135], v[210:213], v[16:19]
	v_mfma_f32_16x16x32_bf16 v[8:11], v[156:159], v[210:213], v[8:11]
	s_setprio 0
	s_setprio 1
	v_mfma_f32_16x16x32_bf16 v[52:55], v[166:169], v[182:185], v[52:55]
	v_mfma_f32_16x16x32_bf16 v[44:47], v[174:177], v[182:185], v[44:47]
	v_mfma_f32_16x16x32_bf16 v[36:39], v[166:169], v[190:193], v[36:39]
	v_mfma_f32_16x16x32_bf16 v[28:31], v[174:177], v[190:193], v[28:31]
	v_mfma_f32_16x16x32_bf16 v[20:23], v[166:169], v[198:201], v[20:23]
	v_mfma_f32_16x16x32_bf16 v[12:15], v[174:177], v[198:201], v[12:15]
	v_mfma_f32_16x16x32_bf16 v[4:7], v[166:169], v[206:209], v[4:7]
	v_mfma_f32_16x16x32_bf16 v[0:3], v[174:177], v[206:209], v[0:3]
	v_mfma_f32_16x16x32_bf16 v[52:55], v[170:173], v[186:189], v[52:55]
	v_mfma_f32_16x16x32_bf16 v[44:47], v[178:181], v[186:189], v[44:47]
	v_mfma_f32_16x16x32_bf16 v[36:39], v[170:173], v[194:197], v[36:39]
	v_mfma_f32_16x16x32_bf16 v[28:31], v[178:181], v[194:197], v[28:31]
	v_mfma_f32_16x16x32_bf16 v[20:23], v[170:173], v[202:205], v[20:23]
	v_mfma_f32_16x16x32_bf16 v[12:15], v[178:181], v[202:205], v[12:15]
	v_mfma_f32_16x16x32_bf16 v[4:7], v[170:173], v[210:213], v[4:7]
	v_mfma_f32_16x16x32_bf16 v[0:3], v[178:181], v[210:213], v[0:3]
	s_setprio 0
	s_barrier
	s_add_i32 s52, s52, 2
	s_add_u32 s26, s26, 0x100
	s_addc_u32 s27, s27, 0
	s_add_u32 s50, s50, 0x100
	s_addc_u32 s51, s51, 0
	s_cmp_gt_u32 s52, 61
	s_cbranch_scc0 .LBB0_1414
	s_and_b64 vcc, exec, s[16:17]
	s_cbranch_vccz .LBB0_1417
	s_barrier
